# merge: L2 prefetch of the workgroup's next tile (first group) during the current tile's last group
# speedup vs baseline: 1.0066x; 1.0023x over previous
.LBB0_1004:
	v_and_b32_e32 v2, 7, v192
	v_lshrrev_b32_e32 v3, 3, v192
	v_bfe_u32 v4, v192, 4, 3
	v_xor_b32_e32 v2, v2, v4
	v_lshlrev_b32_e32 v2, 4, v2
	v_mul_u32_u24_e32 v4, 0x3e00, v3
	v_add_u32_e32 v188, v4, v2
	v_add_u32_e32 v189, 0xf8000, v188
	v_add_u32_e32 v190, 0x1f0000, v188
	v_add_u32_e32 v191, 0x2e8000, v188
	v_and_b32_e32 v4, 35, v3
	v_bfe_u32 v5, v3, 4, 1
	v_lshl_or_b32 v4, v5, 2, v4
	v_bfe_u32 v5, v3, 2, 2
	v_lshl_or_b32 v4, v5, 3, v4
	v_lshl_or_b32 v205, v4, 10, v2
	v_add_u32_e32 v206, 0x10000, v205
	v_bfe_u32 v2, v192, 1, 3
	v_bfe_u32 v3, v192, 4, 2
	v_xor_b32_e32 v2, v2, v3
	v_lshlrev_b32_e32 v2, 4, v2
	v_and_b32_e32 v3, 15, v192
	v_lshrrev_b32_e32 v4, 7, v192
	v_lshl_or_b32 v4, v4, 6, v3
	v_lshl_or_b32 v207, v4, 7, v2
	v_xor_b32_e32 v119, 64, v207
	v_add_u32_e32 v0, 0x10000, v207
	v_add_u32_e32 v255, 0x10000, v119
	v_bfe_u32 v4, v192, 6, 1
	v_lshl_or_b32 v4, v4, 6, v3
	v_lshl_or_b32 v4, v4, 7, v2
	v_add_u32_e32 v90, 0x18000, v4
	v_xor_b32_e32 v91, 64, v90
	v_lshrrev_b32_e32 v5, 6, v192
	s_nop 0
	v_readfirstlane_b32 s67, v5
	s_lshl_b32 s67, s67, 10
	s_add_u32 s80, s46, 0xc00
	s_addc_u32 s81, s47, 0
	s_mov_b32 s96, s48
	s_mov_b32 s97, s49
	v_lshrrev_b32_e32 v2, 4, v192
	v_mul_u32_u24_e32 v2, 0x3e00, v2
	v_and_b32_e32 v3, 15, v192
	v_lshl_or_b32 v93, v3, 6, v2
	s_lshr_b32 s32, s13, 17
	s_mul_i32 s32, s32, 0x7c000
	s_add_u32 s86, s46, s32
	s_addc_u32 s87, s47, 0
	s_add_u32 s98, s86, 0x1000
	s_addc_u32 s99, s87, 0
	global_load_dword v92, v93, s[98:99]
	s_add_i32 m0, s67, 0x0
	s_nop 0
	global_load_lds_dwordx4 v188, s[80:81]
	s_add_i32 m0, s67, 0x2000
	s_nop 0
	global_load_lds_dwordx4 v189, s[80:81]
	s_add_i32 m0, s67, 0x4000
	s_nop 0
	global_load_lds_dwordx4 v190, s[80:81]
	s_add_i32 m0, s67, 0x6000
	s_nop 0
	global_load_lds_dwordx4 v191, s[80:81]
	s_add_i32 m0, s67, 0x18000
	s_nop 0
	global_load_lds_dwordx4 v205, s[96:97]
	s_add_i32 m0, s67, 0x1a000
	s_nop 0
	global_load_lds_dwordx4 v206, s[96:97]
	s_add_u32 s80, s80, 0x80
	s_addc_u32 s81, s81, 0
	s_add_u32 s96, s96, 0x80
	s_addc_u32 s97, s97, 0
	s_add_i32 m0, s67, 0x8000
	s_nop 0
	global_load_lds_dwordx4 v188, s[80:81]
	s_add_i32 m0, s67, 0xa000
	s_nop 0
	global_load_lds_dwordx4 v189, s[80:81]
	s_add_i32 m0, s67, 0xc000
	s_nop 0
	global_load_lds_dwordx4 v190, s[80:81]
	s_add_i32 m0, s67, 0xe000
	s_nop 0
	global_load_lds_dwordx4 v191, s[80:81]
	s_add_i32 m0, s67, 0x1c000
	s_nop 0
	global_load_lds_dwordx4 v205, s[96:97]
	s_add_i32 m0, s67, 0x1e000
	s_nop 0
	global_load_lds_dwordx4 v206, s[96:97]
	s_add_u32 s80, s80, 0x80
	s_addc_u32 s81, s81, 0
	s_add_u32 s96, s96, 0x80
	s_addc_u32 s97, s97, 0
	s_add_i32 m0, s67, 0x10000
	s_nop 0
	global_load_lds_dwordx4 v188, s[80:81]
	s_add_i32 m0, s67, 0x12000
	s_nop 0
	global_load_lds_dwordx4 v189, s[80:81]
	s_add_i32 m0, s67, 0x14000
	s_nop 0
	global_load_lds_dwordx4 v190, s[80:81]
	s_add_i32 m0, s67, 0x16000
	s_nop 0
	global_load_lds_dwordx4 v191, s[80:81]
	s_add_i32 m0, s67, 0x20400
	s_nop 0
	global_load_lds_dwordx4 v205, s[96:97]
	s_add_i32 m0, s67, 0x22400
	s_nop 0
	global_load_lds_dwordx4 v206, s[96:97]
	s_add_u32 s80, s80, 0x80
	s_addc_u32 s81, s81, 0
	s_add_u32 s96, s96, 0x80
	s_addc_u32 s97, s97, 0
	s_waitcnt vmcnt(12)
	s_barrier
	ds_read_b128 v[82:85], v90 offset:0
	ds_read_b128 v[86:89], v90 offset:2048
	ds_read_b128 v[208:211], v90 offset:4096
	ds_read_b128 v[212:215], v90 offset:6144
	ds_read_b128 v[66:69], v207 offset:0
	ds_read_b128 v[70:73], v207 offset:2048
	ds_read_b128 v[74:77], v207 offset:4096
	ds_read_b128 v[78:81], v207 offset:6144
	ds_read_b128 v[216:219], v91 offset:0
	ds_read_b128 v[220:223], v91 offset:2048
	ds_read_b128 v[224:227], v91 offset:4096
	ds_read_b128 v[228:231], v91 offset:6144
	s_waitcnt lgkmcnt(7)
	v_mfma_f32_16x16x32_bf16 v[6:9], v[82:85], v[66:69], 0
	v_mfma_f32_16x16x32_bf16 v[30:33], v[86:89], v[66:69], 0
	v_mfma_f32_16x16x32_bf16 v[38:41], v[208:211], v[66:69], 0
	v_mfma_f32_16x16x32_bf16 v[42:45], v[212:215], v[66:69], 0
	ds_read_b128 v[66:69], v119 offset:0
	s_waitcnt lgkmcnt(7)
	v_mfma_f32_16x16x32_bf16 v[46:49], v[82:85], v[70:73], 0
	v_mfma_f32_16x16x32_bf16 v[26:29], v[86:89], v[70:73], 0
	v_mfma_f32_16x16x32_bf16 v[14:17], v[208:211], v[70:73], 0
	v_mfma_f32_16x16x32_bf16 v[10:13], v[212:215], v[70:73], 0
	ds_read_b128 v[70:73], v119 offset:2048
	s_waitcnt lgkmcnt(7)
	v_mfma_f32_16x16x32_bf16 v[34:37], v[82:85], v[74:77], 0
	v_mfma_f32_16x16x32_bf16 v[22:25], v[86:89], v[74:77], 0
	v_mfma_f32_16x16x32_bf16 v[18:21], v[208:211], v[74:77], 0
	v_mfma_f32_16x16x32_bf16 v[62:65], v[212:215], v[74:77], 0
	ds_read_b128 v[74:77], v119 offset:4096
	s_waitcnt lgkmcnt(7)
	v_mfma_f32_16x16x32_bf16 v[58:61], v[82:85], v[78:81], 0
	v_mfma_f32_16x16x32_bf16 v[54:57], v[86:89], v[78:81], 0
	v_mfma_f32_16x16x32_bf16 v[50:53], v[208:211], v[78:81], 0
	v_mfma_f32_16x16x32_bf16 v[2:5], v[212:215], v[78:81], 0
	ds_read_b128 v[78:81], v119 offset:6144
	s_waitcnt lgkmcnt(3)
	v_mfma_f32_16x16x32_bf16 v[6:9], v[216:219], v[66:69], v[6:9]
	v_mfma_f32_16x16x32_bf16 v[30:33], v[220:223], v[66:69], v[30:33]
	v_mfma_f32_16x16x32_bf16 v[38:41], v[224:227], v[66:69], v[38:41]
	v_mfma_f32_16x16x32_bf16 v[42:45], v[228:231], v[66:69], v[42:45]
	s_waitcnt lgkmcnt(2)
	v_mfma_f32_16x16x32_bf16 v[46:49], v[216:219], v[70:73], v[46:49]
	v_mfma_f32_16x16x32_bf16 v[26:29], v[220:223], v[70:73], v[26:29]
	v_mfma_f32_16x16x32_bf16 v[14:17], v[224:227], v[70:73], v[14:17]
	v_mfma_f32_16x16x32_bf16 v[10:13], v[228:231], v[70:73], v[10:13]
	s_waitcnt vmcnt(6)
	s_waitcnt lgkmcnt(0)
	s_barrier
	s_add_i32 m0, s67, 0x0
	s_nop 0
	global_load_lds_dwordx4 v188, s[80:81]
	s_add_i32 m0, s67, 0x2000
	s_nop 0
	global_load_lds_dwordx4 v189, s[80:81]
	s_add_i32 m0, s67, 0x4000
	s_nop 0
	global_load_lds_dwordx4 v190, s[80:81]
	s_add_i32 m0, s67, 0x6000
	s_nop 0
	global_load_lds_dwordx4 v191, s[80:81]
	s_add_i32 m0, s67, 0x18000
	s_nop 0
	global_load_lds_dwordx4 v205, s[96:97]
	s_add_i32 m0, s67, 0x1a000
	s_nop 0
	global_load_lds_dwordx4 v206, s[96:97]
	s_add_u32 s80, s80, 0x80
	s_addc_u32 s81, s81, 0
	s_add_u32 s96, s96, 0x80
	s_addc_u32 s97, s97, 0
	ds_read_b128 v[82:85], v90 offset:16384
	ds_read_b128 v[86:89], v90 offset:18432
	ds_read_b128 v[208:211], v90 offset:20480
	ds_read_b128 v[212:215], v90 offset:22528
	ds_read_b128 v[66:69], v207 offset:32768
	ds_read_b128 v[70:73], v207 offset:34816
	v_mfma_f32_16x16x32_bf16 v[34:37], v[216:219], v[74:77], v[34:37]
	v_mfma_f32_16x16x32_bf16 v[22:25], v[220:223], v[74:77], v[22:25]
	v_mfma_f32_16x16x32_bf16 v[18:21], v[224:227], v[74:77], v[18:21]
	v_mfma_f32_16x16x32_bf16 v[62:65], v[228:231], v[74:77], v[62:65]
	ds_read_b128 v[74:77], v207 offset:36864
	v_mfma_f32_16x16x32_bf16 v[58:61], v[216:219], v[78:81], v[58:61]
	v_mfma_f32_16x16x32_bf16 v[54:57], v[220:223], v[78:81], v[54:57]
	v_mfma_f32_16x16x32_bf16 v[50:53], v[224:227], v[78:81], v[50:53]
	v_mfma_f32_16x16x32_bf16 v[2:5], v[228:231], v[78:81], v[2:5]
	ds_read_b128 v[78:81], v207 offset:38912
	ds_read_b128 v[216:219], v91 offset:16384
	ds_read_b128 v[220:223], v91 offset:18432
	ds_read_b128 v[224:227], v91 offset:20480
	ds_read_b128 v[228:231], v91 offset:22528
	s_waitcnt lgkmcnt(7)
	v_mfma_f32_16x16x32_bf16 v[6:9], v[82:85], v[66:69], v[6:9]
	v_mfma_f32_16x16x32_bf16 v[30:33], v[86:89], v[66:69], v[30:33]
	v_mfma_f32_16x16x32_bf16 v[38:41], v[208:211], v[66:69], v[38:41]
	v_mfma_f32_16x16x32_bf16 v[42:45], v[212:215], v[66:69], v[42:45]
	ds_read_b128 v[66:69], v119 offset:32768
	s_waitcnt lgkmcnt(7)
	v_mfma_f32_16x16x32_bf16 v[46:49], v[82:85], v[70:73], v[46:49]
	v_mfma_f32_16x16x32_bf16 v[26:29], v[86:89], v[70:73], v[26:29]
	v_mfma_f32_16x16x32_bf16 v[14:17], v[208:211], v[70:73], v[14:17]
	v_mfma_f32_16x16x32_bf16 v[10:13], v[212:215], v[70:73], v[10:13]
	ds_read_b128 v[70:73], v119 offset:34816
	s_waitcnt lgkmcnt(7)
	v_mfma_f32_16x16x32_bf16 v[34:37], v[82:85], v[74:77], v[34:37]
	v_mfma_f32_16x16x32_bf16 v[22:25], v[86:89], v[74:77], v[22:25]
	v_mfma_f32_16x16x32_bf16 v[18:21], v[208:211], v[74:77], v[18:21]
	v_mfma_f32_16x16x32_bf16 v[62:65], v[212:215], v[74:77], v[62:65]
	ds_read_b128 v[74:77], v119 offset:36864
	s_waitcnt lgkmcnt(7)
	v_mfma_f32_16x16x32_bf16 v[58:61], v[82:85], v[78:81], v[58:61]
	v_mfma_f32_16x16x32_bf16 v[54:57], v[86:89], v[78:81], v[54:57]
	v_mfma_f32_16x16x32_bf16 v[50:53], v[208:211], v[78:81], v[50:53]
	v_mfma_f32_16x16x32_bf16 v[2:5], v[212:215], v[78:81], v[2:5]
	ds_read_b128 v[78:81], v119 offset:38912
	s_waitcnt lgkmcnt(3)
	v_mfma_f32_16x16x32_bf16 v[6:9], v[216:219], v[66:69], v[6:9]
	v_mfma_f32_16x16x32_bf16 v[30:33], v[220:223], v[66:69], v[30:33]
	v_mfma_f32_16x16x32_bf16 v[38:41], v[224:227], v[66:69], v[38:41]
	v_mfma_f32_16x16x32_bf16 v[42:45], v[228:231], v[66:69], v[42:45]
	s_waitcnt lgkmcnt(2)
	v_mfma_f32_16x16x32_bf16 v[46:49], v[216:219], v[70:73], v[46:49]
	v_mfma_f32_16x16x32_bf16 v[26:29], v[220:223], v[70:73], v[26:29]
	v_mfma_f32_16x16x32_bf16 v[14:17], v[224:227], v[70:73], v[14:17]
	v_mfma_f32_16x16x32_bf16 v[10:13], v[228:231], v[70:73], v[10:13]
	s_waitcnt vmcnt(6)
	s_waitcnt lgkmcnt(0)
	s_barrier
	s_add_i32 m0, s67, 0x8000
	s_nop 0
	global_load_lds_dwordx4 v188, s[80:81]
	s_add_i32 m0, s67, 0xa000
	s_nop 0
	global_load_lds_dwordx4 v189, s[80:81]
	s_add_i32 m0, s67, 0xc000
	s_nop 0
	global_load_lds_dwordx4 v190, s[80:81]
	s_add_i32 m0, s67, 0xe000
	s_nop 0
	global_load_lds_dwordx4 v191, s[80:81]
	s_add_i32 m0, s67, 0x1c000
	s_nop 0
	global_load_lds_dwordx4 v205, s[96:97]
	s_add_i32 m0, s67, 0x1e000
	s_nop 0
	global_load_lds_dwordx4 v206, s[96:97]
	s_add_u32 s80, s80, 0x80
	s_addc_u32 s81, s81, 0
	s_add_u32 s96, s96, 0x80
	s_addc_u32 s97, s97, 0
	ds_read_b128 v[82:85], v90 offset:33792
	ds_read_b128 v[86:89], v90 offset:35840
	ds_read_b128 v[208:211], v90 offset:37888
	ds_read_b128 v[212:215], v90 offset:39936
	ds_read_b128 v[66:69], v0 offset:0
	ds_read_b128 v[70:73], v0 offset:2048
	v_mfma_f32_16x16x32_bf16 v[34:37], v[216:219], v[74:77], v[34:37]
	v_mfma_f32_16x16x32_bf16 v[22:25], v[220:223], v[74:77], v[22:25]
	v_mfma_f32_16x16x32_bf16 v[18:21], v[224:227], v[74:77], v[18:21]
	v_mfma_f32_16x16x32_bf16 v[62:65], v[228:231], v[74:77], v[62:65]
	ds_read_b128 v[74:77], v0 offset:4096
	v_mfma_f32_16x16x32_bf16 v[58:61], v[216:219], v[78:81], v[58:61]
	v_mfma_f32_16x16x32_bf16 v[54:57], v[220:223], v[78:81], v[54:57]
	v_mfma_f32_16x16x32_bf16 v[50:53], v[224:227], v[78:81], v[50:53]
	v_mfma_f32_16x16x32_bf16 v[2:5], v[228:231], v[78:81], v[2:5]
	ds_read_b128 v[78:81], v0 offset:6144
	ds_read_b128 v[216:219], v91 offset:33792
	ds_read_b128 v[220:223], v91 offset:35840
	ds_read_b128 v[224:227], v91 offset:37888
	ds_read_b128 v[228:231], v91 offset:39936
	s_waitcnt lgkmcnt(7)
	v_mfma_f32_16x16x32_bf16 v[6:9], v[82:85], v[66:69], v[6:9]
	v_mfma_f32_16x16x32_bf16 v[30:33], v[86:89], v[66:69], v[30:33]
	v_mfma_f32_16x16x32_bf16 v[38:41], v[208:211], v[66:69], v[38:41]
	v_mfma_f32_16x16x32_bf16 v[42:45], v[212:215], v[66:69], v[42:45]
	ds_read_b128 v[66:69], v255 offset:0
	s_waitcnt lgkmcnt(7)
	v_mfma_f32_16x16x32_bf16 v[46:49], v[82:85], v[70:73], v[46:49]
	v_mfma_f32_16x16x32_bf16 v[26:29], v[86:89], v[70:73], v[26:29]
	v_mfma_f32_16x16x32_bf16 v[14:17], v[208:211], v[70:73], v[14:17]
	v_mfma_f32_16x16x32_bf16 v[10:13], v[212:215], v[70:73], v[10:13]
	ds_read_b128 v[70:73], v255 offset:2048
	s_waitcnt lgkmcnt(7)
	v_mfma_f32_16x16x32_bf16 v[34:37], v[82:85], v[74:77], v[34:37]
	v_mfma_f32_16x16x32_bf16 v[22:25], v[86:89], v[74:77], v[22:25]
	v_mfma_f32_16x16x32_bf16 v[18:21], v[208:211], v[74:77], v[18:21]
	v_mfma_f32_16x16x32_bf16 v[62:65], v[212:215], v[74:77], v[62:65]
	ds_read_b128 v[74:77], v255 offset:4096
	s_waitcnt lgkmcnt(7)
	v_mfma_f32_16x16x32_bf16 v[58:61], v[82:85], v[78:81], v[58:61]
	v_mfma_f32_16x16x32_bf16 v[54:57], v[86:89], v[78:81], v[54:57]
	v_mfma_f32_16x16x32_bf16 v[50:53], v[208:211], v[78:81], v[50:53]
	v_mfma_f32_16x16x32_bf16 v[2:5], v[212:215], v[78:81], v[2:5]
	ds_read_b128 v[78:81], v255 offset:6144
	s_waitcnt lgkmcnt(3)
	v_mfma_f32_16x16x32_bf16 v[6:9], v[216:219], v[66:69], v[6:9]
	v_mfma_f32_16x16x32_bf16 v[30:33], v[220:223], v[66:69], v[30:33]
	v_mfma_f32_16x16x32_bf16 v[38:41], v[224:227], v[66:69], v[38:41]
	v_mfma_f32_16x16x32_bf16 v[42:45], v[228:231], v[66:69], v[42:45]
	s_waitcnt lgkmcnt(2)
	v_mfma_f32_16x16x32_bf16 v[46:49], v[216:219], v[70:73], v[46:49]
	v_mfma_f32_16x16x32_bf16 v[26:29], v[220:223], v[70:73], v[26:29]
	v_mfma_f32_16x16x32_bf16 v[14:17], v[224:227], v[70:73], v[14:17]
	v_mfma_f32_16x16x32_bf16 v[10:13], v[228:231], v[70:73], v[10:13]
	s_waitcnt vmcnt(6)
	s_waitcnt lgkmcnt(0)
	s_barrier
	s_add_i32 m0, s67, 0x10000
	s_nop 0
	global_load_lds_dwordx4 v188, s[80:81]
	s_add_i32 m0, s67, 0x12000
	s_nop 0
	global_load_lds_dwordx4 v189, s[80:81]
	s_add_i32 m0, s67, 0x14000
	s_nop 0
	global_load_lds_dwordx4 v190, s[80:81]
	s_add_i32 m0, s67, 0x16000
	s_nop 0
	global_load_lds_dwordx4 v191, s[80:81]
	s_add_i32 m0, s67, 0x20400
	s_nop 0
	global_load_lds_dwordx4 v205, s[96:97]
	s_add_i32 m0, s67, 0x22400
	s_nop 0
	global_load_lds_dwordx4 v206, s[96:97]
	s_add_u32 s80, s80, 0x80
	s_addc_u32 s81, s81, 0
	s_add_u32 s96, s96, 0x80
	s_addc_u32 s97, s97, 0
	ds_read_b128 v[82:85], v90 offset:0
	ds_read_b128 v[86:89], v90 offset:2048
	ds_read_b128 v[208:211], v90 offset:4096
	ds_read_b128 v[212:215], v90 offset:6144
	ds_read_b128 v[66:69], v207 offset:0
	ds_read_b128 v[70:73], v207 offset:2048
	v_mfma_f32_16x16x32_bf16 v[34:37], v[216:219], v[74:77], v[34:37]
	v_mfma_f32_16x16x32_bf16 v[22:25], v[220:223], v[74:77], v[22:25]
	v_mfma_f32_16x16x32_bf16 v[18:21], v[224:227], v[74:77], v[18:21]
	v_mfma_f32_16x16x32_bf16 v[62:65], v[228:231], v[74:77], v[62:65]
	ds_read_b128 v[74:77], v207 offset:4096
	v_mfma_f32_16x16x32_bf16 v[58:61], v[216:219], v[78:81], v[58:61]
	v_mfma_f32_16x16x32_bf16 v[54:57], v[220:223], v[78:81], v[54:57]
	v_mfma_f32_16x16x32_bf16 v[50:53], v[224:227], v[78:81], v[50:53]
	v_mfma_f32_16x16x32_bf16 v[2:5], v[228:231], v[78:81], v[2:5]
	ds_read_b128 v[78:81], v207 offset:6144
	ds_read_b128 v[216:219], v91 offset:0
	ds_read_b128 v[220:223], v91 offset:2048
	ds_read_b128 v[224:227], v91 offset:4096
	ds_read_b128 v[228:231], v91 offset:6144
	s_waitcnt lgkmcnt(7)
	v_mfma_f32_16x16x32_bf16 v[6:9], v[82:85], v[66:69], v[6:9]
	v_mfma_f32_16x16x32_bf16 v[30:33], v[86:89], v[66:69], v[30:33]
	v_mfma_f32_16x16x32_bf16 v[38:41], v[208:211], v[66:69], v[38:41]
	v_mfma_f32_16x16x32_bf16 v[42:45], v[212:215], v[66:69], v[42:45]
	ds_read_b128 v[66:69], v119 offset:0
	s_waitcnt lgkmcnt(7)
	v_mfma_f32_16x16x32_bf16 v[46:49], v[82:85], v[70:73], v[46:49]
	v_mfma_f32_16x16x32_bf16 v[26:29], v[86:89], v[70:73], v[26:29]
	v_mfma_f32_16x16x32_bf16 v[14:17], v[208:211], v[70:73], v[14:17]
	v_mfma_f32_16x16x32_bf16 v[10:13], v[212:215], v[70:73], v[10:13]
	ds_read_b128 v[70:73], v119 offset:2048
	s_waitcnt lgkmcnt(7)
	v_mfma_f32_16x16x32_bf16 v[34:37], v[82:85], v[74:77], v[34:37]
	v_mfma_f32_16x16x32_bf16 v[22:25], v[86:89], v[74:77], v[22:25]
	v_mfma_f32_16x16x32_bf16 v[18:21], v[208:211], v[74:77], v[18:21]
	v_mfma_f32_16x16x32_bf16 v[62:65], v[212:215], v[74:77], v[62:65]
	ds_read_b128 v[74:77], v119 offset:4096
	s_waitcnt lgkmcnt(7)
	v_mfma_f32_16x16x32_bf16 v[58:61], v[82:85], v[78:81], v[58:61]
	v_mfma_f32_16x16x32_bf16 v[54:57], v[86:89], v[78:81], v[54:57]
	v_mfma_f32_16x16x32_bf16 v[50:53], v[208:211], v[78:81], v[50:53]
	v_mfma_f32_16x16x32_bf16 v[2:5], v[212:215], v[78:81], v[2:5]
	ds_read_b128 v[78:81], v119 offset:6144
	s_waitcnt lgkmcnt(3)
	v_mfma_f32_16x16x32_bf16 v[6:9], v[216:219], v[66:69], v[6:9]
	v_mfma_f32_16x16x32_bf16 v[30:33], v[220:223], v[66:69], v[30:33]
	v_mfma_f32_16x16x32_bf16 v[38:41], v[224:227], v[66:69], v[38:41]
	v_mfma_f32_16x16x32_bf16 v[42:45], v[228:231], v[66:69], v[42:45]
	s_waitcnt lgkmcnt(2)
	v_mfma_f32_16x16x32_bf16 v[46:49], v[216:219], v[70:73], v[46:49]
	v_mfma_f32_16x16x32_bf16 v[26:29], v[220:223], v[70:73], v[26:29]
	v_mfma_f32_16x16x32_bf16 v[14:17], v[224:227], v[70:73], v[14:17]
	v_mfma_f32_16x16x32_bf16 v[10:13], v[228:231], v[70:73], v[10:13]
	s_waitcnt vmcnt(6)
	s_waitcnt lgkmcnt(0)
	s_barrier
	s_add_i32 m0, s67, 0x0
	s_nop 0
	global_load_lds_dwordx4 v188, s[80:81]
	s_add_i32 m0, s67, 0x2000
	s_nop 0
	global_load_lds_dwordx4 v189, s[80:81]
	s_add_i32 m0, s67, 0x4000
	s_nop 0
	global_load_lds_dwordx4 v190, s[80:81]
	s_add_i32 m0, s67, 0x6000
	s_nop 0
	global_load_lds_dwordx4 v191, s[80:81]
	s_add_i32 m0, s67, 0x18000
	s_nop 0
	global_load_lds_dwordx4 v205, s[96:97]
	s_add_i32 m0, s67, 0x1a000
	s_nop 0
	global_load_lds_dwordx4 v206, s[96:97]
	s_add_u32 s80, s80, 0x80
	s_addc_u32 s81, s81, 0
	s_add_u32 s96, s96, 0x80
	s_addc_u32 s97, s97, 0
	s_movk_i32 s10, 0x0
	s_mov_b32 s11, 0
	v_lshl_add_u64 v[248:249], v[128:129], 0, s[10:11]
	global_load_dwordx2 v[232:233], v[248:249], off
	global_load_dwordx2 v[234:235], v[248:249], off offset:32
	v_lshl_add_u64 v[248:249], v[132:133], 0, s[10:11]
	global_load_dwordx2 v[236:237], v[248:249], off
	global_load_dwordx2 v[238:239], v[248:249], off offset:32
	v_lshl_add_u64 v[248:249], v[152:153], 0, s[10:11]
	global_load_dwordx2 v[240:241], v[248:249], off
	global_load_dwordx2 v[242:243], v[248:249], off offset:32
	v_lshl_add_u64 v[248:249], v[154:155], 0, s[10:11]
	global_load_dwordx2 v[244:245], v[248:249], off
	global_load_dwordx2 v[246:247], v[248:249], off offset:32
	ds_read_b128 v[82:85], v90 offset:16384
	ds_read_b128 v[86:89], v90 offset:18432
	ds_read_b128 v[208:211], v90 offset:20480
	ds_read_b128 v[212:215], v90 offset:22528
	ds_read_b128 v[66:69], v207 offset:32768
	ds_read_b128 v[70:73], v207 offset:34816
	v_mfma_f32_16x16x32_bf16 v[34:37], v[216:219], v[74:77], v[34:37]
	v_mfma_f32_16x16x32_bf16 v[22:25], v[220:223], v[74:77], v[22:25]
	v_mfma_f32_16x16x32_bf16 v[18:21], v[224:227], v[74:77], v[18:21]
	v_mfma_f32_16x16x32_bf16 v[62:65], v[228:231], v[74:77], v[62:65]
	ds_read_b128 v[74:77], v207 offset:36864
	v_mfma_f32_16x16x32_bf16 v[58:61], v[216:219], v[78:81], v[58:61]
	v_mfma_f32_16x16x32_bf16 v[54:57], v[220:223], v[78:81], v[54:57]
	v_mfma_f32_16x16x32_bf16 v[50:53], v[224:227], v[78:81], v[50:53]
	v_mfma_f32_16x16x32_bf16 v[2:5], v[228:231], v[78:81], v[2:5]
	ds_read_b128 v[78:81], v207 offset:38912
	ds_read_b128 v[216:219], v91 offset:16384
	ds_read_b128 v[220:223], v91 offset:18432
	ds_read_b128 v[224:227], v91 offset:20480
	ds_read_b128 v[228:231], v91 offset:22528
	s_waitcnt lgkmcnt(7)
	v_mfma_f32_16x16x32_bf16 v[6:9], v[82:85], v[66:69], v[6:9]
	v_mfma_f32_16x16x32_bf16 v[30:33], v[86:89], v[66:69], v[30:33]
	v_mfma_f32_16x16x32_bf16 v[38:41], v[208:211], v[66:69], v[38:41]
	v_mfma_f32_16x16x32_bf16 v[42:45], v[212:215], v[66:69], v[42:45]
	ds_read_b128 v[66:69], v119 offset:32768
	s_waitcnt lgkmcnt(7)
	v_mfma_f32_16x16x32_bf16 v[46:49], v[82:85], v[70:73], v[46:49]
	v_mfma_f32_16x16x32_bf16 v[26:29], v[86:89], v[70:73], v[26:29]
	v_mfma_f32_16x16x32_bf16 v[14:17], v[208:211], v[70:73], v[14:17]
	v_mfma_f32_16x16x32_bf16 v[10:13], v[212:215], v[70:73], v[10:13]
	ds_read_b128 v[70:73], v119 offset:34816
	s_waitcnt lgkmcnt(7)
	v_mfma_f32_16x16x32_bf16 v[34:37], v[82:85], v[74:77], v[34:37]
	v_mfma_f32_16x16x32_bf16 v[22:25], v[86:89], v[74:77], v[22:25]
	v_mfma_f32_16x16x32_bf16 v[18:21], v[208:211], v[74:77], v[18:21]
	v_mfma_f32_16x16x32_bf16 v[62:65], v[212:215], v[74:77], v[62:65]
	ds_read_b128 v[74:77], v119 offset:36864
	s_waitcnt lgkmcnt(7)
	v_mfma_f32_16x16x32_bf16 v[58:61], v[82:85], v[78:81], v[58:61]
	v_mfma_f32_16x16x32_bf16 v[54:57], v[86:89], v[78:81], v[54:57]
	v_mfma_f32_16x16x32_bf16 v[50:53], v[208:211], v[78:81], v[50:53]
	v_mfma_f32_16x16x32_bf16 v[2:5], v[212:215], v[78:81], v[2:5]
	ds_read_b128 v[78:81], v119 offset:38912
	s_waitcnt lgkmcnt(3)
	v_mfma_f32_16x16x32_bf16 v[6:9], v[216:219], v[66:69], v[6:9]
	v_mfma_f32_16x16x32_bf16 v[30:33], v[220:223], v[66:69], v[30:33]
	v_mfma_f32_16x16x32_bf16 v[38:41], v[224:227], v[66:69], v[38:41]
	v_mfma_f32_16x16x32_bf16 v[42:45], v[228:231], v[66:69], v[42:45]
	s_waitcnt lgkmcnt(2)
	v_mfma_f32_16x16x32_bf16 v[46:49], v[216:219], v[70:73], v[46:49]
	v_mfma_f32_16x16x32_bf16 v[26:29], v[220:223], v[70:73], v[26:29]
	v_mfma_f32_16x16x32_bf16 v[14:17], v[224:227], v[70:73], v[14:17]
	v_mfma_f32_16x16x32_bf16 v[10:13], v[228:231], v[70:73], v[10:13]
	s_waitcnt vmcnt(14)
	s_waitcnt lgkmcnt(0)
	s_barrier
	s_add_i32 m0, s67, 0x8000
	s_nop 0
	global_load_lds_dwordx4 v188, s[80:81]
	s_add_i32 m0, s67, 0xa000
	s_nop 0
	global_load_lds_dwordx4 v189, s[80:81]
	s_add_i32 m0, s67, 0xc000
	s_nop 0
	global_load_lds_dwordx4 v190, s[80:81]
	s_add_i32 m0, s67, 0xe000
	s_nop 0
	global_load_lds_dwordx4 v191, s[80:81]
	s_add_i32 m0, s67, 0x1c000
	s_nop 0
	global_load_lds_dwordx4 v205, s[96:97]
	s_add_i32 m0, s67, 0x1e000
	s_nop 0
	global_load_lds_dwordx4 v206, s[96:97]
	s_add_u32 s80, s80, 0x80
	s_addc_u32 s81, s81, 0
	s_add_u32 s96, s96, 0xffc80
	s_addc_u32 s97, s97, 0
	ds_read_b128 v[82:85], v90 offset:33792
	ds_read_b128 v[86:89], v90 offset:35840
	ds_read_b128 v[208:211], v90 offset:37888
	ds_read_b128 v[212:215], v90 offset:39936
	ds_read_b128 v[66:69], v0 offset:0
	ds_read_b128 v[70:73], v0 offset:2048
	v_mfma_f32_16x16x32_bf16 v[34:37], v[216:219], v[74:77], v[34:37]
	v_mfma_f32_16x16x32_bf16 v[22:25], v[220:223], v[74:77], v[22:25]
	v_mfma_f32_16x16x32_bf16 v[18:21], v[224:227], v[74:77], v[18:21]
	v_mfma_f32_16x16x32_bf16 v[62:65], v[228:231], v[74:77], v[62:65]
	ds_read_b128 v[74:77], v0 offset:4096
	v_mfma_f32_16x16x32_bf16 v[58:61], v[216:219], v[78:81], v[58:61]
	v_mfma_f32_16x16x32_bf16 v[54:57], v[220:223], v[78:81], v[54:57]
	v_mfma_f32_16x16x32_bf16 v[50:53], v[224:227], v[78:81], v[50:53]
	v_mfma_f32_16x16x32_bf16 v[2:5], v[228:231], v[78:81], v[2:5]
	ds_read_b128 v[78:81], v0 offset:6144
	ds_read_b128 v[216:219], v91 offset:33792
	ds_read_b128 v[220:223], v91 offset:35840
	ds_read_b128 v[224:227], v91 offset:37888
	ds_read_b128 v[228:231], v91 offset:39936
	s_waitcnt lgkmcnt(7)
	v_mfma_f32_16x16x32_bf16 v[6:9], v[82:85], v[66:69], v[6:9]
	v_mfma_f32_16x16x32_bf16 v[30:33], v[86:89], v[66:69], v[30:33]
	v_mfma_f32_16x16x32_bf16 v[38:41], v[208:211], v[66:69], v[38:41]
	v_mfma_f32_16x16x32_bf16 v[42:45], v[212:215], v[66:69], v[42:45]
	ds_read_b128 v[66:69], v255 offset:0
	s_waitcnt lgkmcnt(7)
	v_mfma_f32_16x16x32_bf16 v[46:49], v[82:85], v[70:73], v[46:49]
	v_mfma_f32_16x16x32_bf16 v[26:29], v[86:89], v[70:73], v[26:29]
	v_mfma_f32_16x16x32_bf16 v[14:17], v[208:211], v[70:73], v[14:17]
	v_mfma_f32_16x16x32_bf16 v[10:13], v[212:215], v[70:73], v[10:13]
	ds_read_b128 v[70:73], v255 offset:2048
	s_waitcnt lgkmcnt(7)
	v_mfma_f32_16x16x32_bf16 v[34:37], v[82:85], v[74:77], v[34:37]
	v_mfma_f32_16x16x32_bf16 v[22:25], v[86:89], v[74:77], v[22:25]
	v_mfma_f32_16x16x32_bf16 v[18:21], v[208:211], v[74:77], v[18:21]
	v_mfma_f32_16x16x32_bf16 v[62:65], v[212:215], v[74:77], v[62:65]
	ds_read_b128 v[74:77], v255 offset:4096
	s_waitcnt lgkmcnt(7)
	v_mfma_f32_16x16x32_bf16 v[58:61], v[82:85], v[78:81], v[58:61]
	v_mfma_f32_16x16x32_bf16 v[54:57], v[86:89], v[78:81], v[54:57]
	v_mfma_f32_16x16x32_bf16 v[50:53], v[208:211], v[78:81], v[50:53]
	v_mfma_f32_16x16x32_bf16 v[2:5], v[212:215], v[78:81], v[2:5]
	ds_read_b128 v[78:81], v255 offset:6144
	s_waitcnt lgkmcnt(3)
	v_mfma_f32_16x16x32_bf16 v[6:9], v[216:219], v[66:69], v[6:9]
	v_mfma_f32_16x16x32_bf16 v[30:33], v[220:223], v[66:69], v[30:33]
	v_mfma_f32_16x16x32_bf16 v[38:41], v[224:227], v[66:69], v[38:41]
	v_mfma_f32_16x16x32_bf16 v[42:45], v[228:231], v[66:69], v[42:45]
	s_waitcnt lgkmcnt(2)
	v_mfma_f32_16x16x32_bf16 v[46:49], v[216:219], v[70:73], v[46:49]
	v_mfma_f32_16x16x32_bf16 v[26:29], v[220:223], v[70:73], v[26:29]
	v_mfma_f32_16x16x32_bf16 v[14:17], v[224:227], v[70:73], v[14:17]
	v_mfma_f32_16x16x32_bf16 v[10:13], v[228:231], v[70:73], v[10:13]
	s_waitcnt vmcnt(14)
	s_waitcnt lgkmcnt(0)
	s_barrier
	s_add_i32 m0, s67, 0x10000
	s_nop 0
	global_load_lds_dwordx4 v188, s[80:81]
	s_add_i32 m0, s67, 0x12000
	s_nop 0
	global_load_lds_dwordx4 v189, s[80:81]
	s_add_i32 m0, s67, 0x14000
	s_nop 0
	global_load_lds_dwordx4 v190, s[80:81]
	s_add_i32 m0, s67, 0x16000
	s_nop 0
	global_load_lds_dwordx4 v191, s[80:81]
	s_add_i32 m0, s67, 0x20400
	s_nop 0
	global_load_lds_dwordx4 v205, s[96:97]
	s_add_i32 m0, s67, 0x22400
	s_nop 0
	global_load_lds_dwordx4 v206, s[96:97]
	s_add_u32 s80, s80, 0x80
	s_addc_u32 s81, s81, 0
	s_add_u32 s96, s96, 0x80
	s_addc_u32 s97, s97, 0
	ds_read_b128 v[82:85], v90 offset:0
	ds_read_b128 v[86:89], v90 offset:2048
	ds_read_b128 v[208:211], v90 offset:4096
	ds_read_b128 v[212:215], v90 offset:6144
	ds_read_b128 v[66:69], v207 offset:0
	ds_read_b128 v[70:73], v207 offset:2048
	v_mfma_f32_16x16x32_bf16 v[34:37], v[216:219], v[74:77], v[34:37]
	v_mfma_f32_16x16x32_bf16 v[22:25], v[220:223], v[74:77], v[22:25]
	v_mfma_f32_16x16x32_bf16 v[18:21], v[224:227], v[74:77], v[18:21]
	v_mfma_f32_16x16x32_bf16 v[62:65], v[228:231], v[74:77], v[62:65]
	ds_read_b128 v[74:77], v207 offset:4096
	v_mfma_f32_16x16x32_bf16 v[58:61], v[216:219], v[78:81], v[58:61]
	v_mfma_f32_16x16x32_bf16 v[54:57], v[220:223], v[78:81], v[54:57]
	v_mfma_f32_16x16x32_bf16 v[50:53], v[224:227], v[78:81], v[50:53]
	v_mfma_f32_16x16x32_bf16 v[2:5], v[228:231], v[78:81], v[2:5]
	ds_read_b128 v[78:81], v207 offset:6144
	ds_read_b128 v[216:219], v91 offset:0
	ds_read_b128 v[220:223], v91 offset:2048
	ds_read_b128 v[224:227], v91 offset:4096
	ds_read_b128 v[228:231], v91 offset:6144
	s_waitcnt lgkmcnt(7)
	v_mfma_f32_16x16x32_bf16 v[6:9], v[82:85], v[66:69], v[6:9]
	v_mfma_f32_16x16x32_bf16 v[30:33], v[86:89], v[66:69], v[30:33]
	v_mfma_f32_16x16x32_bf16 v[38:41], v[208:211], v[66:69], v[38:41]
	v_mfma_f32_16x16x32_bf16 v[42:45], v[212:215], v[66:69], v[42:45]
	ds_read_b128 v[66:69], v119 offset:0
	s_waitcnt lgkmcnt(7)
	v_mfma_f32_16x16x32_bf16 v[46:49], v[82:85], v[70:73], v[46:49]
	v_mfma_f32_16x16x32_bf16 v[26:29], v[86:89], v[70:73], v[26:29]
	v_mfma_f32_16x16x32_bf16 v[14:17], v[208:211], v[70:73], v[14:17]
	v_mfma_f32_16x16x32_bf16 v[10:13], v[212:215], v[70:73], v[10:13]
	ds_read_b128 v[70:73], v119 offset:2048
	s_waitcnt lgkmcnt(7)
	v_mfma_f32_16x16x32_bf16 v[34:37], v[82:85], v[74:77], v[34:37]
	v_mfma_f32_16x16x32_bf16 v[22:25], v[86:89], v[74:77], v[22:25]
	v_mfma_f32_16x16x32_bf16 v[18:21], v[208:211], v[74:77], v[18:21]
	v_mfma_f32_16x16x32_bf16 v[62:65], v[212:215], v[74:77], v[62:65]
	ds_read_b128 v[74:77], v119 offset:4096
	s_waitcnt lgkmcnt(7)
	v_mfma_f32_16x16x32_bf16 v[58:61], v[82:85], v[78:81], v[58:61]
	v_mfma_f32_16x16x32_bf16 v[54:57], v[86:89], v[78:81], v[54:57]
	v_mfma_f32_16x16x32_bf16 v[50:53], v[208:211], v[78:81], v[50:53]
	v_mfma_f32_16x16x32_bf16 v[2:5], v[212:215], v[78:81], v[2:5]
	ds_read_b128 v[78:81], v119 offset:6144
	s_waitcnt lgkmcnt(3)
	v_mfma_f32_16x16x32_bf16 v[6:9], v[216:219], v[66:69], v[6:9]
	v_mfma_f32_16x16x32_bf16 v[30:33], v[220:223], v[66:69], v[30:33]
	v_mfma_f32_16x16x32_bf16 v[38:41], v[224:227], v[66:69], v[38:41]
	v_mfma_f32_16x16x32_bf16 v[42:45], v[228:231], v[66:69], v[42:45]
	s_waitcnt lgkmcnt(2)
	v_mfma_f32_16x16x32_bf16 v[46:49], v[216:219], v[70:73], v[46:49]
	v_mfma_f32_16x16x32_bf16 v[26:29], v[220:223], v[70:73], v[26:29]
	v_mfma_f32_16x16x32_bf16 v[14:17], v[224:227], v[70:73], v[14:17]
	v_mfma_f32_16x16x32_bf16 v[10:13], v[228:231], v[70:73], v[10:13]
	s_waitcnt vmcnt(6)
	s_waitcnt lgkmcnt(0)
	s_barrier
	s_add_i32 m0, s67, 0x0
	s_nop 0
	global_load_lds_dwordx4 v188, s[80:81]
	s_add_i32 m0, s67, 0x2000
	s_nop 0
	global_load_lds_dwordx4 v189, s[80:81]
	s_add_i32 m0, s67, 0x4000
	s_nop 0
	global_load_lds_dwordx4 v190, s[80:81]
	s_add_i32 m0, s67, 0x6000
	s_nop 0
	global_load_lds_dwordx4 v191, s[80:81]
	s_add_i32 m0, s67, 0x18000
	s_nop 0
	global_load_lds_dwordx4 v205, s[96:97]
	s_add_i32 m0, s67, 0x1a000
	s_nop 0
	global_load_lds_dwordx4 v206, s[96:97]
	s_add_u32 s80, s80, 0x80
	s_addc_u32 s81, s81, 0
	s_add_u32 s96, s96, 0x80
	s_addc_u32 s97, s97, 0
	ds_read_b128 v[82:85], v90 offset:16384
	ds_read_b128 v[86:89], v90 offset:18432
	ds_read_b128 v[208:211], v90 offset:20480
	ds_read_b128 v[212:215], v90 offset:22528
	ds_read_b128 v[66:69], v207 offset:32768
	ds_read_b128 v[70:73], v207 offset:34816
	v_mfma_f32_16x16x32_bf16 v[34:37], v[216:219], v[74:77], v[34:37]
	v_mfma_f32_16x16x32_bf16 v[22:25], v[220:223], v[74:77], v[22:25]
	v_mfma_f32_16x16x32_bf16 v[18:21], v[224:227], v[74:77], v[18:21]
	v_mfma_f32_16x16x32_bf16 v[62:65], v[228:231], v[74:77], v[62:65]
	ds_read_b128 v[74:77], v207 offset:36864
	v_mfma_f32_16x16x32_bf16 v[58:61], v[216:219], v[78:81], v[58:61]
	v_mfma_f32_16x16x32_bf16 v[54:57], v[220:223], v[78:81], v[54:57]
	v_mfma_f32_16x16x32_bf16 v[50:53], v[224:227], v[78:81], v[50:53]
	v_mfma_f32_16x16x32_bf16 v[2:5], v[228:231], v[78:81], v[2:5]
	ds_read_b128 v[78:81], v207 offset:38912
	ds_read_b128 v[216:219], v91 offset:16384
	ds_read_b128 v[220:223], v91 offset:18432
	ds_read_b128 v[224:227], v91 offset:20480
	ds_read_b128 v[228:231], v91 offset:22528
	s_waitcnt lgkmcnt(7)
	v_mfma_f32_16x16x32_bf16 v[6:9], v[82:85], v[66:69], v[6:9]
	v_mfma_f32_16x16x32_bf16 v[30:33], v[86:89], v[66:69], v[30:33]
	v_mfma_f32_16x16x32_bf16 v[38:41], v[208:211], v[66:69], v[38:41]
	v_mfma_f32_16x16x32_bf16 v[42:45], v[212:215], v[66:69], v[42:45]
	ds_read_b128 v[66:69], v119 offset:32768
	s_waitcnt lgkmcnt(7)
	v_mfma_f32_16x16x32_bf16 v[46:49], v[82:85], v[70:73], v[46:49]
	v_mfma_f32_16x16x32_bf16 v[26:29], v[86:89], v[70:73], v[26:29]
	v_mfma_f32_16x16x32_bf16 v[14:17], v[208:211], v[70:73], v[14:17]
	v_mfma_f32_16x16x32_bf16 v[10:13], v[212:215], v[70:73], v[10:13]
	ds_read_b128 v[70:73], v119 offset:34816
	s_waitcnt lgkmcnt(7)
	v_mfma_f32_16x16x32_bf16 v[34:37], v[82:85], v[74:77], v[34:37]
	v_mfma_f32_16x16x32_bf16 v[22:25], v[86:89], v[74:77], v[22:25]
	v_mfma_f32_16x16x32_bf16 v[18:21], v[208:211], v[74:77], v[18:21]
	v_mfma_f32_16x16x32_bf16 v[62:65], v[212:215], v[74:77], v[62:65]
	ds_read_b128 v[74:77], v119 offset:36864
	s_waitcnt lgkmcnt(7)
	v_mfma_f32_16x16x32_bf16 v[58:61], v[82:85], v[78:81], v[58:61]
	v_mfma_f32_16x16x32_bf16 v[54:57], v[86:89], v[78:81], v[54:57]
	v_mfma_f32_16x16x32_bf16 v[50:53], v[208:211], v[78:81], v[50:53]
	v_mfma_f32_16x16x32_bf16 v[2:5], v[212:215], v[78:81], v[2:5]
	ds_read_b128 v[78:81], v119 offset:38912
	s_waitcnt lgkmcnt(3)
	v_mfma_f32_16x16x32_bf16 v[6:9], v[216:219], v[66:69], v[6:9]
	s_waitcnt vmcnt(18)
	v_mfma_f32_16x16x32_bf16 v[30:33], v[220:223], v[66:69], v[30:33]
	v_mfma_f32_16x16x32_bf16 v[38:41], v[224:227], v[66:69], v[38:41]
	v_mfma_f32_16x16x32_bf16 v[42:45], v[228:231], v[66:69], v[42:45]
	v_cvt_f32_ubyte0_e32 v248, v232
	v_cvt_f32_ubyte1_e32 v249, v232
	v_cvt_f32_ubyte2_e32 v250, v232
	v_cvt_f32_ubyte3_e32 v251, v232
	v_mul_f32_e32 v248, s34, v248
	v_mul_f32_e32 v249, s34, v249
	v_mul_f32_e32 v250, s34, v250
	v_mul_f32_e32 v251, s34, v251
	v_fma_f32 v184, v6, v248, v184
	v_fma_f32 v185, v7, v249, v185
	v_fma_f32 v186, v8, v250, v186
	v_fma_f32 v187, v9, v251, v187
	s_waitcnt lgkmcnt(2)
	v_mfma_f32_16x16x32_bf16 v[46:49], v[216:219], v[70:73], v[46:49]
	v_cvt_f32_ubyte0_e32 v248, v233
	v_cvt_f32_ubyte1_e32 v249, v233
	v_cvt_f32_ubyte2_e32 v250, v233
	v_cvt_f32_ubyte3_e32 v251, v233
	v_mul_f32_e32 v248, s34, v248
	v_mul_f32_e32 v249, s34, v249
	v_mul_f32_e32 v250, s34, v250
	v_mul_f32_e32 v251, s34, v251
	v_fma_f32 v180, v30, v248, v180
	v_fma_f32 v181, v31, v249, v181
	v_fma_f32 v182, v32, v250, v182
	v_fma_f32 v183, v33, v251, v183
	v_mfma_f32_16x16x32_bf16 v[26:29], v[220:223], v[70:73], v[26:29]
	v_cvt_f32_ubyte0_e32 v248, v234
	v_cvt_f32_ubyte1_e32 v249, v234
	v_cvt_f32_ubyte2_e32 v250, v234
	v_cvt_f32_ubyte3_e32 v251, v234
	v_mul_f32_e32 v248, s34, v248
	v_mul_f32_e32 v249, s34, v249
	v_mul_f32_e32 v250, s34, v250
	v_mul_f32_e32 v251, s34, v251
	v_fma_f32 v176, v38, v248, v176
	v_fma_f32 v177, v39, v249, v177
	v_fma_f32 v178, v40, v250, v178
	v_fma_f32 v179, v41, v251, v179
	v_mfma_f32_16x16x32_bf16 v[14:17], v[224:227], v[70:73], v[14:17]
	v_cvt_f32_ubyte0_e32 v248, v235
	v_cvt_f32_ubyte1_e32 v249, v235
	v_cvt_f32_ubyte2_e32 v250, v235
	v_cvt_f32_ubyte3_e32 v251, v235
	v_mul_f32_e32 v248, s34, v248
	v_mul_f32_e32 v249, s34, v249
	v_mul_f32_e32 v250, s34, v250
	v_mul_f32_e32 v251, s34, v251
	v_fma_f32 v172, v42, v248, v172
	v_fma_f32 v173, v43, v249, v173
	v_fma_f32 v174, v44, v250, v174
	v_fma_f32 v175, v45, v251, v175
	v_mfma_f32_16x16x32_bf16 v[10:13], v[228:231], v[70:73], v[10:13]
	v_cvt_f32_ubyte0_e32 v248, v236
	v_cvt_f32_ubyte1_e32 v249, v236
	v_cvt_f32_ubyte2_e32 v250, v236
	v_cvt_f32_ubyte3_e32 v251, v236
	v_mul_f32_e32 v248, s34, v248
	v_mul_f32_e32 v249, s34, v249
	v_mul_f32_e32 v250, s34, v250
	v_mul_f32_e32 v251, s34, v251
	v_fma_f32 v168, v46, v248, v168
	v_fma_f32 v169, v47, v249, v169
	v_fma_f32 v170, v48, v250, v170
	v_fma_f32 v171, v49, v251, v171
	s_waitcnt vmcnt(6)
	s_waitcnt lgkmcnt(0)
	s_barrier
	s_add_i32 m0, s67, 0x8000
	s_nop 0
	global_load_lds_dwordx4 v188, s[80:81]
	s_add_i32 m0, s67, 0xa000
	s_nop 0
	global_load_lds_dwordx4 v189, s[80:81]
	s_add_i32 m0, s67, 0xc000
	s_nop 0
	global_load_lds_dwordx4 v190, s[80:81]
	s_add_i32 m0, s67, 0xe000
	s_nop 0
	global_load_lds_dwordx4 v191, s[80:81]
	s_add_i32 m0, s67, 0x1c000
	s_nop 0
	global_load_lds_dwordx4 v205, s[96:97]
	s_add_i32 m0, s67, 0x1e000
	s_nop 0
	global_load_lds_dwordx4 v206, s[96:97]
	s_add_u32 s80, s80, 0x80
	s_addc_u32 s81, s81, 0
	s_add_u32 s96, s96, 0x80
	s_addc_u32 s97, s97, 0
	ds_read_b128 v[82:85], v90 offset:33792
	ds_read_b128 v[86:89], v90 offset:35840
	ds_read_b128 v[208:211], v90 offset:37888
	ds_read_b128 v[212:215], v90 offset:39936
	ds_read_b128 v[66:69], v0 offset:0
	ds_read_b128 v[70:73], v0 offset:2048
	v_mfma_f32_16x16x32_bf16 v[34:37], v[216:219], v[74:77], v[34:37]
	v_cvt_f32_ubyte0_e32 v248, v237
	v_cvt_f32_ubyte1_e32 v249, v237
	v_cvt_f32_ubyte2_e32 v250, v237
	v_cvt_f32_ubyte3_e32 v251, v237
	v_mul_f32_e32 v248, s34, v248
	v_mul_f32_e32 v249, s34, v249
	v_mul_f32_e32 v250, s34, v250
	v_mul_f32_e32 v251, s34, v251
	v_fma_f32 v164, v26, v248, v164
	v_fma_f32 v165, v27, v249, v165
	v_fma_f32 v166, v28, v250, v166
	v_fma_f32 v167, v29, v251, v167
	v_mfma_f32_16x16x32_bf16 v[22:25], v[220:223], v[74:77], v[22:25]
	v_cvt_f32_ubyte0_e32 v248, v238
	v_cvt_f32_ubyte1_e32 v249, v238
	v_cvt_f32_ubyte2_e32 v250, v238
	v_cvt_f32_ubyte3_e32 v251, v238
	v_mul_f32_e32 v248, s34, v248
	v_mul_f32_e32 v249, s34, v249
	v_mul_f32_e32 v250, s34, v250
	v_mul_f32_e32 v251, s34, v251
	v_fma_f32 v160, v14, v248, v160
	v_fma_f32 v161, v15, v249, v161
	v_fma_f32 v162, v16, v250, v162
	v_fma_f32 v163, v17, v251, v163
	v_mfma_f32_16x16x32_bf16 v[18:21], v[224:227], v[74:77], v[18:21]
	v_cvt_f32_ubyte0_e32 v248, v239
	v_cvt_f32_ubyte1_e32 v249, v239
	v_cvt_f32_ubyte2_e32 v250, v239
	v_cvt_f32_ubyte3_e32 v251, v239
	v_mul_f32_e32 v248, s34, v248
	v_mul_f32_e32 v249, s34, v249
	v_mul_f32_e32 v250, s34, v250
	v_mul_f32_e32 v251, s34, v251
	v_fma_f32 v156, v10, v248, v156
	v_fma_f32 v157, v11, v249, v157
	v_fma_f32 v158, v12, v250, v158
	v_fma_f32 v159, v13, v251, v159
	v_mfma_f32_16x16x32_bf16 v[62:65], v[228:231], v[74:77], v[62:65]
	v_cvt_f32_ubyte0_e32 v248, v240
	v_cvt_f32_ubyte1_e32 v249, v240
	v_cvt_f32_ubyte2_e32 v250, v240
	v_cvt_f32_ubyte3_e32 v251, v240
	v_mul_f32_e32 v248, s34, v248
	v_mul_f32_e32 v249, s34, v249
	v_mul_f32_e32 v250, s34, v250
	v_mul_f32_e32 v251, s34, v251
	v_fma_f32 v136, v34, v248, v136
	v_fma_f32 v137, v35, v249, v137
	v_fma_f32 v150, v36, v250, v150
	v_fma_f32 v151, v37, v251, v151
	ds_read_b128 v[74:77], v0 offset:4096
	v_mfma_f32_16x16x32_bf16 v[58:61], v[216:219], v[78:81], v[58:61]
	v_cvt_f32_ubyte0_e32 v248, v241
	v_cvt_f32_ubyte1_e32 v249, v241
	v_cvt_f32_ubyte2_e32 v250, v241
	v_cvt_f32_ubyte3_e32 v251, v241
	v_mul_f32_e32 v248, s34, v248
	v_mul_f32_e32 v249, s34, v249
	v_mul_f32_e32 v250, s34, v250
	v_mul_f32_e32 v251, s34, v251
	v_fma_f32 v130, v22, v248, v130
	v_fma_f32 v131, v23, v249, v131
	v_fma_f32 v134, v24, v250, v134
	v_fma_f32 v135, v25, v251, v135
	v_mfma_f32_16x16x32_bf16 v[54:57], v[220:223], v[78:81], v[54:57]
	v_cvt_f32_ubyte0_e32 v248, v242
	v_cvt_f32_ubyte1_e32 v249, v242
	v_cvt_f32_ubyte2_e32 v250, v242
	v_cvt_f32_ubyte3_e32 v251, v242
	v_mul_f32_e32 v248, s34, v248
	v_mul_f32_e32 v249, s34, v249
	v_mul_f32_e32 v250, s34, v250
	v_mul_f32_e32 v251, s34, v251
	v_fma_f32 v124, v18, v248, v124
	v_fma_f32 v125, v19, v249, v125
	v_fma_f32 v126, v20, v250, v126
	v_fma_f32 v127, v21, v251, v127
	v_mfma_f32_16x16x32_bf16 v[50:53], v[224:227], v[78:81], v[50:53]
	v_cvt_f32_ubyte0_e32 v248, v243
	v_cvt_f32_ubyte1_e32 v249, v243
	v_cvt_f32_ubyte2_e32 v250, v243
	v_cvt_f32_ubyte3_e32 v251, v243
	v_mul_f32_e32 v248, s34, v248
	v_mul_f32_e32 v249, s34, v249
	v_mul_f32_e32 v250, s34, v250
	v_mul_f32_e32 v251, s34, v251
	v_fma_f32 v120, v62, v248, v120
	v_fma_f32 v121, v63, v249, v121
	v_fma_f32 v122, v64, v250, v122
	v_fma_f32 v123, v65, v251, v123
	v_mfma_f32_16x16x32_bf16 v[2:5], v[228:231], v[78:81], v[2:5]
	v_cvt_f32_ubyte0_e32 v248, v244
	v_cvt_f32_ubyte1_e32 v249, v244
	v_cvt_f32_ubyte2_e32 v250, v244
	v_cvt_f32_ubyte3_e32 v251, v244
	v_mul_f32_e32 v248, s34, v248
	v_mul_f32_e32 v249, s34, v249
	v_mul_f32_e32 v250, s34, v250
	v_mul_f32_e32 v251, s34, v251
	v_fma_f32 v114, v58, v248, v114
	v_fma_f32 v115, v59, v249, v115
	v_fma_f32 v116, v60, v250, v116
	v_fma_f32 v117, v61, v251, v117
	ds_read_b128 v[78:81], v0 offset:6144
	s_nop 7
	s_nop 3
	v_cvt_f32_ubyte0_e32 v248, v245
	v_cvt_f32_ubyte1_e32 v249, v245
	v_cvt_f32_ubyte2_e32 v250, v245
	v_cvt_f32_ubyte3_e32 v251, v245
	v_mul_f32_e32 v248, s34, v248
	v_mul_f32_e32 v249, s34, v249
	v_mul_f32_e32 v250, s34, v250
	v_mul_f32_e32 v251, s34, v251
	v_fma_f32 v106, v54, v248, v106
	v_fma_f32 v107, v55, v249, v107
	v_fma_f32 v108, v56, v250, v108
	v_fma_f32 v109, v57, v251, v109
	v_cvt_f32_ubyte0_e32 v248, v246
	v_cvt_f32_ubyte1_e32 v249, v246
	v_cvt_f32_ubyte2_e32 v250, v246
	v_cvt_f32_ubyte3_e32 v251, v246
	v_mul_f32_e32 v248, s34, v248
	v_mul_f32_e32 v249, s34, v249
	v_mul_f32_e32 v250, s34, v250
	v_mul_f32_e32 v251, s34, v251
	v_fma_f32 v100, v50, v248, v100
	v_fma_f32 v101, v51, v249, v101
	v_fma_f32 v102, v52, v250, v102
	v_fma_f32 v103, v53, v251, v103
	v_cvt_f32_ubyte0_e32 v248, v247
	v_cvt_f32_ubyte1_e32 v249, v247
	v_cvt_f32_ubyte2_e32 v250, v247
	v_cvt_f32_ubyte3_e32 v251, v247
	v_mul_f32_e32 v248, s34, v248
	v_mul_f32_e32 v249, s34, v249
	v_mul_f32_e32 v250, s34, v250
	v_mul_f32_e32 v251, s34, v251
	v_fma_f32 v96, v2, v248, v96
	v_fma_f32 v97, v3, v249, v97
	v_fma_f32 v98, v4, v250, v98
	v_fma_f32 v99, v5, v251, v99
	s_add_u32 s98, s86, 0x1600
	s_addc_u32 s99, s87, 0
	global_load_dword v92, v93, s[98:99]
	ds_read_b128 v[216:219], v91 offset:33792
	ds_read_b128 v[220:223], v91 offset:35840
	ds_read_b128 v[224:227], v91 offset:37888
	ds_read_b128 v[228:231], v91 offset:39936
	s_waitcnt lgkmcnt(7)
	v_mfma_f32_16x16x32_bf16 v[6:9], v[82:85], v[66:69], 0
	v_mfma_f32_16x16x32_bf16 v[30:33], v[86:89], v[66:69], 0
	v_mfma_f32_16x16x32_bf16 v[38:41], v[208:211], v[66:69], 0
	v_mfma_f32_16x16x32_bf16 v[42:45], v[212:215], v[66:69], 0
	ds_read_b128 v[66:69], v255 offset:0
	s_waitcnt lgkmcnt(7)
	v_mfma_f32_16x16x32_bf16 v[46:49], v[82:85], v[70:73], 0
	v_mfma_f32_16x16x32_bf16 v[26:29], v[86:89], v[70:73], 0
	v_mfma_f32_16x16x32_bf16 v[14:17], v[208:211], v[70:73], 0
	v_mfma_f32_16x16x32_bf16 v[10:13], v[212:215], v[70:73], 0
	ds_read_b128 v[70:73], v255 offset:2048
	s_waitcnt lgkmcnt(7)
	v_mfma_f32_16x16x32_bf16 v[34:37], v[82:85], v[74:77], 0
	v_mfma_f32_16x16x32_bf16 v[22:25], v[86:89], v[74:77], 0
	v_mfma_f32_16x16x32_bf16 v[18:21], v[208:211], v[74:77], 0
	v_mfma_f32_16x16x32_bf16 v[62:65], v[212:215], v[74:77], 0
	ds_read_b128 v[74:77], v255 offset:4096
	s_waitcnt lgkmcnt(7)
	v_mfma_f32_16x16x32_bf16 v[58:61], v[82:85], v[78:81], 0
	v_mfma_f32_16x16x32_bf16 v[54:57], v[86:89], v[78:81], 0
	v_mfma_f32_16x16x32_bf16 v[50:53], v[208:211], v[78:81], 0
	v_mfma_f32_16x16x32_bf16 v[2:5], v[212:215], v[78:81], 0
	ds_read_b128 v[78:81], v255 offset:6144
	s_waitcnt lgkmcnt(3)
	v_mfma_f32_16x16x32_bf16 v[6:9], v[216:219], v[66:69], v[6:9]
	v_mfma_f32_16x16x32_bf16 v[30:33], v[220:223], v[66:69], v[30:33]
	v_mfma_f32_16x16x32_bf16 v[38:41], v[224:227], v[66:69], v[38:41]
	v_mfma_f32_16x16x32_bf16 v[42:45], v[228:231], v[66:69], v[42:45]
	s_waitcnt lgkmcnt(2)
	v_mfma_f32_16x16x32_bf16 v[46:49], v[216:219], v[70:73], v[46:49]
	v_mfma_f32_16x16x32_bf16 v[26:29], v[220:223], v[70:73], v[26:29]
	v_mfma_f32_16x16x32_bf16 v[14:17], v[224:227], v[70:73], v[14:17]
	v_mfma_f32_16x16x32_bf16 v[10:13], v[228:231], v[70:73], v[10:13]
	s_waitcnt vmcnt(7)
	s_waitcnt lgkmcnt(0)
	s_barrier
	s_add_i32 m0, s67, 0x10000
	s_nop 0
	global_load_lds_dwordx4 v188, s[80:81]
	s_add_i32 m0, s67, 0x12000
	s_nop 0
	global_load_lds_dwordx4 v189, s[80:81]
	s_add_i32 m0, s67, 0x14000
	s_nop 0
	global_load_lds_dwordx4 v190, s[80:81]
	s_add_i32 m0, s67, 0x16000
	s_nop 0
	global_load_lds_dwordx4 v191, s[80:81]
	s_add_i32 m0, s67, 0x20400
	s_nop 0
	global_load_lds_dwordx4 v205, s[96:97]
	s_add_i32 m0, s67, 0x22400
	s_nop 0
	global_load_lds_dwordx4 v206, s[96:97]
	s_add_u32 s80, s80, 0x80
	s_addc_u32 s81, s81, 0
	s_add_u32 s96, s96, 0x80
	s_addc_u32 s97, s97, 0
	ds_read_b128 v[82:85], v90 offset:0
	ds_read_b128 v[86:89], v90 offset:2048
	ds_read_b128 v[208:211], v90 offset:4096
	ds_read_b128 v[212:215], v90 offset:6144
	ds_read_b128 v[66:69], v207 offset:0
	ds_read_b128 v[70:73], v207 offset:2048
	v_mfma_f32_16x16x32_bf16 v[34:37], v[216:219], v[74:77], v[34:37]
	v_mfma_f32_16x16x32_bf16 v[22:25], v[220:223], v[74:77], v[22:25]
	v_mfma_f32_16x16x32_bf16 v[18:21], v[224:227], v[74:77], v[18:21]
	v_mfma_f32_16x16x32_bf16 v[62:65], v[228:231], v[74:77], v[62:65]
	ds_read_b128 v[74:77], v207 offset:4096
	v_mfma_f32_16x16x32_bf16 v[58:61], v[216:219], v[78:81], v[58:61]
	v_mfma_f32_16x16x32_bf16 v[54:57], v[220:223], v[78:81], v[54:57]
	v_mfma_f32_16x16x32_bf16 v[50:53], v[224:227], v[78:81], v[50:53]
	v_mfma_f32_16x16x32_bf16 v[2:5], v[228:231], v[78:81], v[2:5]
	ds_read_b128 v[78:81], v207 offset:6144
	ds_read_b128 v[216:219], v91 offset:0
	ds_read_b128 v[220:223], v91 offset:2048
	ds_read_b128 v[224:227], v91 offset:4096
	ds_read_b128 v[228:231], v91 offset:6144
	s_waitcnt lgkmcnt(7)
	v_mfma_f32_16x16x32_bf16 v[6:9], v[82:85], v[66:69], v[6:9]
	v_mfma_f32_16x16x32_bf16 v[30:33], v[86:89], v[66:69], v[30:33]
	v_mfma_f32_16x16x32_bf16 v[38:41], v[208:211], v[66:69], v[38:41]
	v_mfma_f32_16x16x32_bf16 v[42:45], v[212:215], v[66:69], v[42:45]
	ds_read_b128 v[66:69], v119 offset:0
	s_waitcnt lgkmcnt(7)
	v_mfma_f32_16x16x32_bf16 v[46:49], v[82:85], v[70:73], v[46:49]
	v_mfma_f32_16x16x32_bf16 v[26:29], v[86:89], v[70:73], v[26:29]
	v_mfma_f32_16x16x32_bf16 v[14:17], v[208:211], v[70:73], v[14:17]
	v_mfma_f32_16x16x32_bf16 v[10:13], v[212:215], v[70:73], v[10:13]
	ds_read_b128 v[70:73], v119 offset:2048
	s_waitcnt lgkmcnt(7)
	v_mfma_f32_16x16x32_bf16 v[34:37], v[82:85], v[74:77], v[34:37]
	v_mfma_f32_16x16x32_bf16 v[22:25], v[86:89], v[74:77], v[22:25]
	v_mfma_f32_16x16x32_bf16 v[18:21], v[208:211], v[74:77], v[18:21]
	v_mfma_f32_16x16x32_bf16 v[62:65], v[212:215], v[74:77], v[62:65]
	ds_read_b128 v[74:77], v119 offset:4096
	s_waitcnt lgkmcnt(7)
	v_mfma_f32_16x16x32_bf16 v[58:61], v[82:85], v[78:81], v[58:61]
	v_mfma_f32_16x16x32_bf16 v[54:57], v[86:89], v[78:81], v[54:57]
	v_mfma_f32_16x16x32_bf16 v[50:53], v[208:211], v[78:81], v[50:53]
	v_mfma_f32_16x16x32_bf16 v[2:5], v[212:215], v[78:81], v[2:5]
	ds_read_b128 v[78:81], v119 offset:6144
	s_waitcnt lgkmcnt(3)
	v_mfma_f32_16x16x32_bf16 v[6:9], v[216:219], v[66:69], v[6:9]
	v_mfma_f32_16x16x32_bf16 v[30:33], v[220:223], v[66:69], v[30:33]
	v_mfma_f32_16x16x32_bf16 v[38:41], v[224:227], v[66:69], v[38:41]
	v_mfma_f32_16x16x32_bf16 v[42:45], v[228:231], v[66:69], v[42:45]
	s_waitcnt lgkmcnt(2)
	v_mfma_f32_16x16x32_bf16 v[46:49], v[216:219], v[70:73], v[46:49]
	v_mfma_f32_16x16x32_bf16 v[26:29], v[220:223], v[70:73], v[26:29]
	v_mfma_f32_16x16x32_bf16 v[14:17], v[224:227], v[70:73], v[14:17]
	v_mfma_f32_16x16x32_bf16 v[10:13], v[228:231], v[70:73], v[10:13]
	s_waitcnt vmcnt(7)
	s_waitcnt lgkmcnt(0)
	s_barrier
	s_add_i32 m0, s67, 0x0
	s_nop 0
	global_load_lds_dwordx4 v188, s[80:81]
	s_add_i32 m0, s67, 0x2000
	s_nop 0
	global_load_lds_dwordx4 v189, s[80:81]
	s_add_i32 m0, s67, 0x4000
	s_nop 0
	global_load_lds_dwordx4 v190, s[80:81]
	s_add_i32 m0, s67, 0x6000
	s_nop 0
	global_load_lds_dwordx4 v191, s[80:81]
	s_add_i32 m0, s67, 0x18000
	s_nop 0
	global_load_lds_dwordx4 v205, s[96:97]
	s_add_i32 m0, s67, 0x1a000
	s_nop 0
	global_load_lds_dwordx4 v206, s[96:97]
	s_add_u32 s80, s80, 0x80
	s_addc_u32 s81, s81, 0
	s_add_u32 s96, s96, 0x80
	s_addc_u32 s97, s97, 0
	ds_read_b128 v[82:85], v90 offset:16384
	ds_read_b128 v[86:89], v90 offset:18432
	ds_read_b128 v[208:211], v90 offset:20480
	ds_read_b128 v[212:215], v90 offset:22528
	ds_read_b128 v[66:69], v207 offset:32768
	ds_read_b128 v[70:73], v207 offset:34816
	v_mfma_f32_16x16x32_bf16 v[34:37], v[216:219], v[74:77], v[34:37]
	v_mfma_f32_16x16x32_bf16 v[22:25], v[220:223], v[74:77], v[22:25]
	v_mfma_f32_16x16x32_bf16 v[18:21], v[224:227], v[74:77], v[18:21]
	v_mfma_f32_16x16x32_bf16 v[62:65], v[228:231], v[74:77], v[62:65]
	ds_read_b128 v[74:77], v207 offset:36864
	v_mfma_f32_16x16x32_bf16 v[58:61], v[216:219], v[78:81], v[58:61]
	v_mfma_f32_16x16x32_bf16 v[54:57], v[220:223], v[78:81], v[54:57]
	v_mfma_f32_16x16x32_bf16 v[50:53], v[224:227], v[78:81], v[50:53]
	v_mfma_f32_16x16x32_bf16 v[2:5], v[228:231], v[78:81], v[2:5]
	ds_read_b128 v[78:81], v207 offset:38912
	ds_read_b128 v[216:219], v91 offset:16384
	ds_read_b128 v[220:223], v91 offset:18432
	ds_read_b128 v[224:227], v91 offset:20480
	ds_read_b128 v[228:231], v91 offset:22528
	s_waitcnt lgkmcnt(7)
	v_mfma_f32_16x16x32_bf16 v[6:9], v[82:85], v[66:69], v[6:9]
	v_mfma_f32_16x16x32_bf16 v[30:33], v[86:89], v[66:69], v[30:33]
	v_mfma_f32_16x16x32_bf16 v[38:41], v[208:211], v[66:69], v[38:41]
	v_mfma_f32_16x16x32_bf16 v[42:45], v[212:215], v[66:69], v[42:45]
	ds_read_b128 v[66:69], v119 offset:32768
	s_waitcnt lgkmcnt(7)
	v_mfma_f32_16x16x32_bf16 v[46:49], v[82:85], v[70:73], v[46:49]
	v_mfma_f32_16x16x32_bf16 v[26:29], v[86:89], v[70:73], v[26:29]
	v_mfma_f32_16x16x32_bf16 v[14:17], v[208:211], v[70:73], v[14:17]
	v_mfma_f32_16x16x32_bf16 v[10:13], v[212:215], v[70:73], v[10:13]
	ds_read_b128 v[70:73], v119 offset:34816
	s_waitcnt lgkmcnt(7)
	v_mfma_f32_16x16x32_bf16 v[34:37], v[82:85], v[74:77], v[34:37]
	v_mfma_f32_16x16x32_bf16 v[22:25], v[86:89], v[74:77], v[22:25]
	v_mfma_f32_16x16x32_bf16 v[18:21], v[208:211], v[74:77], v[18:21]
	v_mfma_f32_16x16x32_bf16 v[62:65], v[212:215], v[74:77], v[62:65]
	ds_read_b128 v[74:77], v119 offset:36864
	s_waitcnt lgkmcnt(7)
	v_mfma_f32_16x16x32_bf16 v[58:61], v[82:85], v[78:81], v[58:61]
	v_mfma_f32_16x16x32_bf16 v[54:57], v[86:89], v[78:81], v[54:57]
	v_mfma_f32_16x16x32_bf16 v[50:53], v[208:211], v[78:81], v[50:53]
	v_mfma_f32_16x16x32_bf16 v[2:5], v[212:215], v[78:81], v[2:5]
	ds_read_b128 v[78:81], v119 offset:38912
	s_waitcnt lgkmcnt(3)
	v_mfma_f32_16x16x32_bf16 v[6:9], v[216:219], v[66:69], v[6:9]
	v_mfma_f32_16x16x32_bf16 v[30:33], v[220:223], v[66:69], v[30:33]
	v_mfma_f32_16x16x32_bf16 v[38:41], v[224:227], v[66:69], v[38:41]
	v_mfma_f32_16x16x32_bf16 v[42:45], v[228:231], v[66:69], v[42:45]
	s_waitcnt lgkmcnt(2)
	v_mfma_f32_16x16x32_bf16 v[46:49], v[216:219], v[70:73], v[46:49]
	v_mfma_f32_16x16x32_bf16 v[26:29], v[220:223], v[70:73], v[26:29]
	v_mfma_f32_16x16x32_bf16 v[14:17], v[224:227], v[70:73], v[14:17]
	v_mfma_f32_16x16x32_bf16 v[10:13], v[228:231], v[70:73], v[10:13]
	s_waitcnt vmcnt(6)
	s_waitcnt lgkmcnt(0)
	s_barrier
	s_add_i32 m0, s67, 0x8000
	s_nop 0
	global_load_lds_dwordx4 v188, s[80:81]
	s_add_i32 m0, s67, 0xa000
	s_nop 0
	global_load_lds_dwordx4 v189, s[80:81]
	s_add_i32 m0, s67, 0xc000
	s_nop 0
	global_load_lds_dwordx4 v190, s[80:81]
	s_add_i32 m0, s67, 0xe000
	s_nop 0
	global_load_lds_dwordx4 v191, s[80:81]
	s_add_i32 m0, s67, 0x1c000
	s_nop 0
	global_load_lds_dwordx4 v205, s[96:97]
	s_add_i32 m0, s67, 0x1e000
	s_nop 0
	global_load_lds_dwordx4 v206, s[96:97]
	s_add_u32 s80, s80, 0x80
	s_addc_u32 s81, s81, 0
	s_add_u32 s96, s96, 0x80
	s_addc_u32 s97, s97, 0
	ds_read_b128 v[82:85], v90 offset:33792
	ds_read_b128 v[86:89], v90 offset:35840
	ds_read_b128 v[208:211], v90 offset:37888
	ds_read_b128 v[212:215], v90 offset:39936
	ds_read_b128 v[66:69], v0 offset:0
	ds_read_b128 v[70:73], v0 offset:2048
	v_mfma_f32_16x16x32_bf16 v[34:37], v[216:219], v[74:77], v[34:37]
	v_mfma_f32_16x16x32_bf16 v[22:25], v[220:223], v[74:77], v[22:25]
	v_mfma_f32_16x16x32_bf16 v[18:21], v[224:227], v[74:77], v[18:21]
	v_mfma_f32_16x16x32_bf16 v[62:65], v[228:231], v[74:77], v[62:65]
	ds_read_b128 v[74:77], v0 offset:4096
	v_mfma_f32_16x16x32_bf16 v[58:61], v[216:219], v[78:81], v[58:61]
	v_mfma_f32_16x16x32_bf16 v[54:57], v[220:223], v[78:81], v[54:57]
	v_mfma_f32_16x16x32_bf16 v[50:53], v[224:227], v[78:81], v[50:53]
	v_mfma_f32_16x16x32_bf16 v[2:5], v[228:231], v[78:81], v[2:5]
	ds_read_b128 v[78:81], v0 offset:6144
	ds_read_b128 v[216:219], v91 offset:33792
	ds_read_b128 v[220:223], v91 offset:35840
	ds_read_b128 v[224:227], v91 offset:37888
	ds_read_b128 v[228:231], v91 offset:39936
	s_waitcnt lgkmcnt(7)
	v_mfma_f32_16x16x32_bf16 v[6:9], v[82:85], v[66:69], v[6:9]
	v_mfma_f32_16x16x32_bf16 v[30:33], v[86:89], v[66:69], v[30:33]
	v_mfma_f32_16x16x32_bf16 v[38:41], v[208:211], v[66:69], v[38:41]
	v_mfma_f32_16x16x32_bf16 v[42:45], v[212:215], v[66:69], v[42:45]
	ds_read_b128 v[66:69], v255 offset:0
	s_waitcnt lgkmcnt(7)
	v_mfma_f32_16x16x32_bf16 v[46:49], v[82:85], v[70:73], v[46:49]
	v_mfma_f32_16x16x32_bf16 v[26:29], v[86:89], v[70:73], v[26:29]
	v_mfma_f32_16x16x32_bf16 v[14:17], v[208:211], v[70:73], v[14:17]
	v_mfma_f32_16x16x32_bf16 v[10:13], v[212:215], v[70:73], v[10:13]
	ds_read_b128 v[70:73], v255 offset:2048
	s_waitcnt lgkmcnt(7)
	v_mfma_f32_16x16x32_bf16 v[34:37], v[82:85], v[74:77], v[34:37]
	v_mfma_f32_16x16x32_bf16 v[22:25], v[86:89], v[74:77], v[22:25]
	v_mfma_f32_16x16x32_bf16 v[18:21], v[208:211], v[74:77], v[18:21]
	v_mfma_f32_16x16x32_bf16 v[62:65], v[212:215], v[74:77], v[62:65]
	ds_read_b128 v[74:77], v255 offset:4096
	s_waitcnt lgkmcnt(7)
	v_mfma_f32_16x16x32_bf16 v[58:61], v[82:85], v[78:81], v[58:61]
	v_mfma_f32_16x16x32_bf16 v[54:57], v[86:89], v[78:81], v[54:57]
	v_mfma_f32_16x16x32_bf16 v[50:53], v[208:211], v[78:81], v[50:53]
	v_mfma_f32_16x16x32_bf16 v[2:5], v[212:215], v[78:81], v[2:5]
	ds_read_b128 v[78:81], v255 offset:6144
	s_waitcnt lgkmcnt(3)
	v_mfma_f32_16x16x32_bf16 v[6:9], v[216:219], v[66:69], v[6:9]
	v_mfma_f32_16x16x32_bf16 v[30:33], v[220:223], v[66:69], v[30:33]
	v_mfma_f32_16x16x32_bf16 v[38:41], v[224:227], v[66:69], v[38:41]
	v_mfma_f32_16x16x32_bf16 v[42:45], v[228:231], v[66:69], v[42:45]
	s_waitcnt lgkmcnt(2)
	v_mfma_f32_16x16x32_bf16 v[46:49], v[216:219], v[70:73], v[46:49]
	v_mfma_f32_16x16x32_bf16 v[26:29], v[220:223], v[70:73], v[26:29]
	v_mfma_f32_16x16x32_bf16 v[14:17], v[224:227], v[70:73], v[14:17]
	v_mfma_f32_16x16x32_bf16 v[10:13], v[228:231], v[70:73], v[10:13]
	s_waitcnt vmcnt(6)
	s_waitcnt lgkmcnt(0)
	s_barrier
	s_add_i32 m0, s67, 0x10000
	s_nop 0
	global_load_lds_dwordx4 v188, s[80:81]
	s_add_i32 m0, s67, 0x12000
	s_nop 0
	global_load_lds_dwordx4 v189, s[80:81]
	s_add_i32 m0, s67, 0x14000
	s_nop 0
	global_load_lds_dwordx4 v190, s[80:81]
	s_add_i32 m0, s67, 0x16000
	s_nop 0
	global_load_lds_dwordx4 v191, s[80:81]
	s_add_i32 m0, s67, 0x20400
	s_nop 0
	global_load_lds_dwordx4 v205, s[96:97]
	s_add_i32 m0, s67, 0x22400
	s_nop 0
	global_load_lds_dwordx4 v206, s[96:97]
	s_add_u32 s80, s80, 0x80
	s_addc_u32 s81, s81, 0
	s_add_u32 s96, s96, 0x80
	s_addc_u32 s97, s97, 0
	s_movk_i32 s10, 0x400
	s_mov_b32 s11, 0
	v_lshl_add_u64 v[248:249], v[128:129], 0, s[10:11]
	global_load_dwordx2 v[232:233], v[248:249], off
	global_load_dwordx2 v[234:235], v[248:249], off offset:32
	v_lshl_add_u64 v[248:249], v[132:133], 0, s[10:11]
	global_load_dwordx2 v[236:237], v[248:249], off
	global_load_dwordx2 v[238:239], v[248:249], off offset:32
	v_lshl_add_u64 v[248:249], v[152:153], 0, s[10:11]
	global_load_dwordx2 v[240:241], v[248:249], off
	global_load_dwordx2 v[242:243], v[248:249], off offset:32
	v_lshl_add_u64 v[248:249], v[154:155], 0, s[10:11]
	global_load_dwordx2 v[244:245], v[248:249], off
	global_load_dwordx2 v[246:247], v[248:249], off offset:32
	ds_read_b128 v[82:85], v90 offset:0
	ds_read_b128 v[86:89], v90 offset:2048
	ds_read_b128 v[208:211], v90 offset:4096
	ds_read_b128 v[212:215], v90 offset:6144
	ds_read_b128 v[66:69], v207 offset:0
	ds_read_b128 v[70:73], v207 offset:2048
	v_mfma_f32_16x16x32_bf16 v[34:37], v[216:219], v[74:77], v[34:37]
	v_mfma_f32_16x16x32_bf16 v[22:25], v[220:223], v[74:77], v[22:25]
	v_mfma_f32_16x16x32_bf16 v[18:21], v[224:227], v[74:77], v[18:21]
	v_mfma_f32_16x16x32_bf16 v[62:65], v[228:231], v[74:77], v[62:65]
	ds_read_b128 v[74:77], v207 offset:4096
	v_mfma_f32_16x16x32_bf16 v[58:61], v[216:219], v[78:81], v[58:61]
	v_mfma_f32_16x16x32_bf16 v[54:57], v[220:223], v[78:81], v[54:57]
	v_mfma_f32_16x16x32_bf16 v[50:53], v[224:227], v[78:81], v[50:53]
	v_mfma_f32_16x16x32_bf16 v[2:5], v[228:231], v[78:81], v[2:5]
	ds_read_b128 v[78:81], v207 offset:6144
	ds_read_b128 v[216:219], v91 offset:0
	ds_read_b128 v[220:223], v91 offset:2048
	ds_read_b128 v[224:227], v91 offset:4096
	ds_read_b128 v[228:231], v91 offset:6144
	s_waitcnt lgkmcnt(7)
	v_mfma_f32_16x16x32_bf16 v[6:9], v[82:85], v[66:69], v[6:9]
	v_mfma_f32_16x16x32_bf16 v[30:33], v[86:89], v[66:69], v[30:33]
	v_mfma_f32_16x16x32_bf16 v[38:41], v[208:211], v[66:69], v[38:41]
	v_mfma_f32_16x16x32_bf16 v[42:45], v[212:215], v[66:69], v[42:45]
	ds_read_b128 v[66:69], v119 offset:0
	s_waitcnt lgkmcnt(7)
	v_mfma_f32_16x16x32_bf16 v[46:49], v[82:85], v[70:73], v[46:49]
	v_mfma_f32_16x16x32_bf16 v[26:29], v[86:89], v[70:73], v[26:29]
	v_mfma_f32_16x16x32_bf16 v[14:17], v[208:211], v[70:73], v[14:17]
	v_mfma_f32_16x16x32_bf16 v[10:13], v[212:215], v[70:73], v[10:13]
	ds_read_b128 v[70:73], v119 offset:2048
	s_waitcnt lgkmcnt(7)
	v_mfma_f32_16x16x32_bf16 v[34:37], v[82:85], v[74:77], v[34:37]
	v_mfma_f32_16x16x32_bf16 v[22:25], v[86:89], v[74:77], v[22:25]
	v_mfma_f32_16x16x32_bf16 v[18:21], v[208:211], v[74:77], v[18:21]
	v_mfma_f32_16x16x32_bf16 v[62:65], v[212:215], v[74:77], v[62:65]
	ds_read_b128 v[74:77], v119 offset:4096
	s_waitcnt lgkmcnt(7)
	v_mfma_f32_16x16x32_bf16 v[58:61], v[82:85], v[78:81], v[58:61]
	v_mfma_f32_16x16x32_bf16 v[54:57], v[86:89], v[78:81], v[54:57]
	v_mfma_f32_16x16x32_bf16 v[50:53], v[208:211], v[78:81], v[50:53]
	v_mfma_f32_16x16x32_bf16 v[2:5], v[212:215], v[78:81], v[2:5]
	ds_read_b128 v[78:81], v119 offset:6144
	s_waitcnt lgkmcnt(3)
	v_mfma_f32_16x16x32_bf16 v[6:9], v[216:219], v[66:69], v[6:9]
	v_mfma_f32_16x16x32_bf16 v[30:33], v[220:223], v[66:69], v[30:33]
	v_mfma_f32_16x16x32_bf16 v[38:41], v[224:227], v[66:69], v[38:41]
	v_mfma_f32_16x16x32_bf16 v[42:45], v[228:231], v[66:69], v[42:45]
	s_waitcnt lgkmcnt(2)
	v_mfma_f32_16x16x32_bf16 v[46:49], v[216:219], v[70:73], v[46:49]
	v_mfma_f32_16x16x32_bf16 v[26:29], v[220:223], v[70:73], v[26:29]
	v_mfma_f32_16x16x32_bf16 v[14:17], v[224:227], v[70:73], v[14:17]
	v_mfma_f32_16x16x32_bf16 v[10:13], v[228:231], v[70:73], v[10:13]
	s_waitcnt vmcnt(14)
	s_waitcnt lgkmcnt(0)
	s_barrier
	s_add_i32 m0, s67, 0x0
	s_nop 0
	global_load_lds_dwordx4 v188, s[80:81]
	s_add_i32 m0, s67, 0x2000
	s_nop 0
	global_load_lds_dwordx4 v189, s[80:81]
	s_add_i32 m0, s67, 0x4000
	s_nop 0
	global_load_lds_dwordx4 v190, s[80:81]
	s_add_i32 m0, s67, 0x6000
	s_nop 0
	global_load_lds_dwordx4 v191, s[80:81]
	s_add_i32 m0, s67, 0x18000
	s_nop 0
	global_load_lds_dwordx4 v205, s[96:97]
	s_add_i32 m0, s67, 0x1a000
	s_nop 0
	global_load_lds_dwordx4 v206, s[96:97]
	s_add_u32 s80, s80, 0x280
	s_addc_u32 s81, s81, 0
	s_add_u32 s96, s96, 0xffc80
	s_addc_u32 s97, s97, 0
	ds_read_b128 v[82:85], v90 offset:16384
	ds_read_b128 v[86:89], v90 offset:18432
	ds_read_b128 v[208:211], v90 offset:20480
	ds_read_b128 v[212:215], v90 offset:22528
	ds_read_b128 v[66:69], v207 offset:32768
	ds_read_b128 v[70:73], v207 offset:34816
	v_mfma_f32_16x16x32_bf16 v[34:37], v[216:219], v[74:77], v[34:37]
	v_mfma_f32_16x16x32_bf16 v[22:25], v[220:223], v[74:77], v[22:25]
	v_mfma_f32_16x16x32_bf16 v[18:21], v[224:227], v[74:77], v[18:21]
	v_mfma_f32_16x16x32_bf16 v[62:65], v[228:231], v[74:77], v[62:65]
	ds_read_b128 v[74:77], v207 offset:36864
	v_mfma_f32_16x16x32_bf16 v[58:61], v[216:219], v[78:81], v[58:61]
	v_mfma_f32_16x16x32_bf16 v[54:57], v[220:223], v[78:81], v[54:57]
	v_mfma_f32_16x16x32_bf16 v[50:53], v[224:227], v[78:81], v[50:53]
	v_mfma_f32_16x16x32_bf16 v[2:5], v[228:231], v[78:81], v[2:5]
	ds_read_b128 v[78:81], v207 offset:38912
	ds_read_b128 v[216:219], v91 offset:16384
	ds_read_b128 v[220:223], v91 offset:18432
	ds_read_b128 v[224:227], v91 offset:20480
	ds_read_b128 v[228:231], v91 offset:22528
	s_waitcnt lgkmcnt(7)
	v_mfma_f32_16x16x32_bf16 v[6:9], v[82:85], v[66:69], v[6:9]
	v_mfma_f32_16x16x32_bf16 v[30:33], v[86:89], v[66:69], v[30:33]
	v_mfma_f32_16x16x32_bf16 v[38:41], v[208:211], v[66:69], v[38:41]
	v_mfma_f32_16x16x32_bf16 v[42:45], v[212:215], v[66:69], v[42:45]
	ds_read_b128 v[66:69], v119 offset:32768
	s_waitcnt lgkmcnt(7)
	v_mfma_f32_16x16x32_bf16 v[46:49], v[82:85], v[70:73], v[46:49]
	v_mfma_f32_16x16x32_bf16 v[26:29], v[86:89], v[70:73], v[26:29]
	v_mfma_f32_16x16x32_bf16 v[14:17], v[208:211], v[70:73], v[14:17]
	v_mfma_f32_16x16x32_bf16 v[10:13], v[212:215], v[70:73], v[10:13]
	ds_read_b128 v[70:73], v119 offset:34816
	s_waitcnt lgkmcnt(7)
	v_mfma_f32_16x16x32_bf16 v[34:37], v[82:85], v[74:77], v[34:37]
	v_mfma_f32_16x16x32_bf16 v[22:25], v[86:89], v[74:77], v[22:25]
	v_mfma_f32_16x16x32_bf16 v[18:21], v[208:211], v[74:77], v[18:21]
	v_mfma_f32_16x16x32_bf16 v[62:65], v[212:215], v[74:77], v[62:65]
	ds_read_b128 v[74:77], v119 offset:36864
	s_waitcnt lgkmcnt(7)
	v_mfma_f32_16x16x32_bf16 v[58:61], v[82:85], v[78:81], v[58:61]
	v_mfma_f32_16x16x32_bf16 v[54:57], v[86:89], v[78:81], v[54:57]
	v_mfma_f32_16x16x32_bf16 v[50:53], v[208:211], v[78:81], v[50:53]
	v_mfma_f32_16x16x32_bf16 v[2:5], v[212:215], v[78:81], v[2:5]
	ds_read_b128 v[78:81], v119 offset:38912
	s_waitcnt lgkmcnt(3)
	v_mfma_f32_16x16x32_bf16 v[6:9], v[216:219], v[66:69], v[6:9]
	v_mfma_f32_16x16x32_bf16 v[30:33], v[220:223], v[66:69], v[30:33]
	v_mfma_f32_16x16x32_bf16 v[38:41], v[224:227], v[66:69], v[38:41]
	v_mfma_f32_16x16x32_bf16 v[42:45], v[228:231], v[66:69], v[42:45]
	s_waitcnt lgkmcnt(2)
	v_mfma_f32_16x16x32_bf16 v[46:49], v[216:219], v[70:73], v[46:49]
	v_mfma_f32_16x16x32_bf16 v[26:29], v[220:223], v[70:73], v[26:29]
	v_mfma_f32_16x16x32_bf16 v[14:17], v[224:227], v[70:73], v[14:17]
	v_mfma_f32_16x16x32_bf16 v[10:13], v[228:231], v[70:73], v[10:13]
	s_waitcnt vmcnt(14)
	s_waitcnt lgkmcnt(0)
	s_barrier
	s_add_i32 m0, s67, 0x8000
	s_nop 0
	global_load_lds_dwordx4 v188, s[80:81]
	s_add_i32 m0, s67, 0xa000
	s_nop 0
	global_load_lds_dwordx4 v189, s[80:81]
	s_add_i32 m0, s67, 0xc000
	s_nop 0
	global_load_lds_dwordx4 v190, s[80:81]
	s_add_i32 m0, s67, 0xe000
	s_nop 0
	global_load_lds_dwordx4 v191, s[80:81]
	s_add_i32 m0, s67, 0x1c000
	s_nop 0
	global_load_lds_dwordx4 v205, s[96:97]
	s_add_i32 m0, s67, 0x1e000
	s_nop 0
	global_load_lds_dwordx4 v206, s[96:97]
	s_add_u32 s80, s80, 0x80
	s_addc_u32 s81, s81, 0
	s_add_u32 s96, s96, 0x80
	s_addc_u32 s97, s97, 0
	ds_read_b128 v[82:85], v90 offset:33792
	ds_read_b128 v[86:89], v90 offset:35840
	ds_read_b128 v[208:211], v90 offset:37888
	ds_read_b128 v[212:215], v90 offset:39936
	ds_read_b128 v[66:69], v0 offset:0
	ds_read_b128 v[70:73], v0 offset:2048
	v_mfma_f32_16x16x32_bf16 v[34:37], v[216:219], v[74:77], v[34:37]
	v_mfma_f32_16x16x32_bf16 v[22:25], v[220:223], v[74:77], v[22:25]
	v_mfma_f32_16x16x32_bf16 v[18:21], v[224:227], v[74:77], v[18:21]
	v_mfma_f32_16x16x32_bf16 v[62:65], v[228:231], v[74:77], v[62:65]
	ds_read_b128 v[74:77], v0 offset:4096
	v_mfma_f32_16x16x32_bf16 v[58:61], v[216:219], v[78:81], v[58:61]
	v_mfma_f32_16x16x32_bf16 v[54:57], v[220:223], v[78:81], v[54:57]
	v_mfma_f32_16x16x32_bf16 v[50:53], v[224:227], v[78:81], v[50:53]
	v_mfma_f32_16x16x32_bf16 v[2:5], v[228:231], v[78:81], v[2:5]
	ds_read_b128 v[78:81], v0 offset:6144
	ds_read_b128 v[216:219], v91 offset:33792
	ds_read_b128 v[220:223], v91 offset:35840
	ds_read_b128 v[224:227], v91 offset:37888
	ds_read_b128 v[228:231], v91 offset:39936
	s_waitcnt lgkmcnt(7)
	v_mfma_f32_16x16x32_bf16 v[6:9], v[82:85], v[66:69], v[6:9]
	v_mfma_f32_16x16x32_bf16 v[30:33], v[86:89], v[66:69], v[30:33]
	v_mfma_f32_16x16x32_bf16 v[38:41], v[208:211], v[66:69], v[38:41]
	v_mfma_f32_16x16x32_bf16 v[42:45], v[212:215], v[66:69], v[42:45]
	ds_read_b128 v[66:69], v255 offset:0
	s_waitcnt lgkmcnt(7)
	v_mfma_f32_16x16x32_bf16 v[46:49], v[82:85], v[70:73], v[46:49]
	v_mfma_f32_16x16x32_bf16 v[26:29], v[86:89], v[70:73], v[26:29]
	v_mfma_f32_16x16x32_bf16 v[14:17], v[208:211], v[70:73], v[14:17]
	v_mfma_f32_16x16x32_bf16 v[10:13], v[212:215], v[70:73], v[10:13]
	ds_read_b128 v[70:73], v255 offset:2048
	s_waitcnt lgkmcnt(7)
	v_mfma_f32_16x16x32_bf16 v[34:37], v[82:85], v[74:77], v[34:37]
	v_mfma_f32_16x16x32_bf16 v[22:25], v[86:89], v[74:77], v[22:25]
	v_mfma_f32_16x16x32_bf16 v[18:21], v[208:211], v[74:77], v[18:21]
	v_mfma_f32_16x16x32_bf16 v[62:65], v[212:215], v[74:77], v[62:65]
	ds_read_b128 v[74:77], v255 offset:4096
	s_waitcnt lgkmcnt(7)
	v_mfma_f32_16x16x32_bf16 v[58:61], v[82:85], v[78:81], v[58:61]
	v_mfma_f32_16x16x32_bf16 v[54:57], v[86:89], v[78:81], v[54:57]
	v_mfma_f32_16x16x32_bf16 v[50:53], v[208:211], v[78:81], v[50:53]
	v_mfma_f32_16x16x32_bf16 v[2:5], v[212:215], v[78:81], v[2:5]
	ds_read_b128 v[78:81], v255 offset:6144
	s_waitcnt lgkmcnt(3)
	v_mfma_f32_16x16x32_bf16 v[6:9], v[216:219], v[66:69], v[6:9]
	v_mfma_f32_16x16x32_bf16 v[30:33], v[220:223], v[66:69], v[30:33]
	v_mfma_f32_16x16x32_bf16 v[38:41], v[224:227], v[66:69], v[38:41]
	v_mfma_f32_16x16x32_bf16 v[42:45], v[228:231], v[66:69], v[42:45]
	s_waitcnt lgkmcnt(2)
	v_mfma_f32_16x16x32_bf16 v[46:49], v[216:219], v[70:73], v[46:49]
	v_mfma_f32_16x16x32_bf16 v[26:29], v[220:223], v[70:73], v[26:29]
	v_mfma_f32_16x16x32_bf16 v[14:17], v[224:227], v[70:73], v[14:17]
	v_mfma_f32_16x16x32_bf16 v[10:13], v[228:231], v[70:73], v[10:13]
	s_waitcnt vmcnt(6)
	s_waitcnt lgkmcnt(0)
	s_barrier
	s_add_i32 m0, s67, 0x10000
	s_nop 0
	global_load_lds_dwordx4 v188, s[80:81]
	s_add_i32 m0, s67, 0x12000
	s_nop 0
	global_load_lds_dwordx4 v189, s[80:81]
	s_add_i32 m0, s67, 0x14000
	s_nop 0
	global_load_lds_dwordx4 v190, s[80:81]
	s_add_i32 m0, s67, 0x16000
	s_nop 0
	global_load_lds_dwordx4 v191, s[80:81]
	s_add_i32 m0, s67, 0x20400
	s_nop 0
	global_load_lds_dwordx4 v205, s[96:97]
	s_add_i32 m0, s67, 0x22400
	s_nop 0
	global_load_lds_dwordx4 v206, s[96:97]
	s_add_u32 s80, s80, 0x80
	s_addc_u32 s81, s81, 0
	s_add_u32 s96, s96, 0x80
	s_addc_u32 s97, s97, 0
	ds_read_b128 v[82:85], v90 offset:0
	ds_read_b128 v[86:89], v90 offset:2048
	ds_read_b128 v[208:211], v90 offset:4096
	ds_read_b128 v[212:215], v90 offset:6144
	ds_read_b128 v[66:69], v207 offset:0
	ds_read_b128 v[70:73], v207 offset:2048
	v_mfma_f32_16x16x32_bf16 v[34:37], v[216:219], v[74:77], v[34:37]
	v_mfma_f32_16x16x32_bf16 v[22:25], v[220:223], v[74:77], v[22:25]
	v_mfma_f32_16x16x32_bf16 v[18:21], v[224:227], v[74:77], v[18:21]
	v_mfma_f32_16x16x32_bf16 v[62:65], v[228:231], v[74:77], v[62:65]
	ds_read_b128 v[74:77], v207 offset:4096
	v_mfma_f32_16x16x32_bf16 v[58:61], v[216:219], v[78:81], v[58:61]
	v_mfma_f32_16x16x32_bf16 v[54:57], v[220:223], v[78:81], v[54:57]
	v_mfma_f32_16x16x32_bf16 v[50:53], v[224:227], v[78:81], v[50:53]
	v_mfma_f32_16x16x32_bf16 v[2:5], v[228:231], v[78:81], v[2:5]
	ds_read_b128 v[78:81], v207 offset:6144
	ds_read_b128 v[216:219], v91 offset:0
	ds_read_b128 v[220:223], v91 offset:2048
	ds_read_b128 v[224:227], v91 offset:4096
	ds_read_b128 v[228:231], v91 offset:6144
	s_waitcnt lgkmcnt(7)
	v_mfma_f32_16x16x32_bf16 v[6:9], v[82:85], v[66:69], v[6:9]
	v_mfma_f32_16x16x32_bf16 v[30:33], v[86:89], v[66:69], v[30:33]
	v_mfma_f32_16x16x32_bf16 v[38:41], v[208:211], v[66:69], v[38:41]
	v_mfma_f32_16x16x32_bf16 v[42:45], v[212:215], v[66:69], v[42:45]
	ds_read_b128 v[66:69], v119 offset:0
	s_waitcnt lgkmcnt(7)
	v_mfma_f32_16x16x32_bf16 v[46:49], v[82:85], v[70:73], v[46:49]
	v_mfma_f32_16x16x32_bf16 v[26:29], v[86:89], v[70:73], v[26:29]
	v_mfma_f32_16x16x32_bf16 v[14:17], v[208:211], v[70:73], v[14:17]
	v_mfma_f32_16x16x32_bf16 v[10:13], v[212:215], v[70:73], v[10:13]
	ds_read_b128 v[70:73], v119 offset:2048
	s_waitcnt lgkmcnt(7)
	v_mfma_f32_16x16x32_bf16 v[34:37], v[82:85], v[74:77], v[34:37]
	v_mfma_f32_16x16x32_bf16 v[22:25], v[86:89], v[74:77], v[22:25]
	v_mfma_f32_16x16x32_bf16 v[18:21], v[208:211], v[74:77], v[18:21]
	v_mfma_f32_16x16x32_bf16 v[62:65], v[212:215], v[74:77], v[62:65]
	ds_read_b128 v[74:77], v119 offset:4096
	s_waitcnt lgkmcnt(7)
	v_mfma_f32_16x16x32_bf16 v[58:61], v[82:85], v[78:81], v[58:61]
	v_mfma_f32_16x16x32_bf16 v[54:57], v[86:89], v[78:81], v[54:57]
	v_mfma_f32_16x16x32_bf16 v[50:53], v[208:211], v[78:81], v[50:53]
	v_mfma_f32_16x16x32_bf16 v[2:5], v[212:215], v[78:81], v[2:5]
	ds_read_b128 v[78:81], v119 offset:6144
	s_waitcnt lgkmcnt(3)
	v_mfma_f32_16x16x32_bf16 v[6:9], v[216:219], v[66:69], v[6:9]
	s_waitcnt vmcnt(18)
	v_mfma_f32_16x16x32_bf16 v[30:33], v[220:223], v[66:69], v[30:33]
	v_mfma_f32_16x16x32_bf16 v[38:41], v[224:227], v[66:69], v[38:41]
	v_mfma_f32_16x16x32_bf16 v[42:45], v[228:231], v[66:69], v[42:45]
	v_cvt_f32_ubyte0_e32 v248, v232
	v_cvt_f32_ubyte1_e32 v249, v232
	v_cvt_f32_ubyte2_e32 v250, v232
	v_cvt_f32_ubyte3_e32 v251, v232
	v_mul_f32_e32 v248, s34, v248
	v_mul_f32_e32 v249, s34, v249
	v_mul_f32_e32 v250, s34, v250
	v_mul_f32_e32 v251, s34, v251
	v_fma_f32 v184, v6, v248, v184
	v_fma_f32 v185, v7, v249, v185
	v_fma_f32 v186, v8, v250, v186
	v_fma_f32 v187, v9, v251, v187
	s_waitcnt lgkmcnt(2)
	v_mfma_f32_16x16x32_bf16 v[46:49], v[216:219], v[70:73], v[46:49]
	v_cvt_f32_ubyte0_e32 v248, v233
	v_cvt_f32_ubyte1_e32 v249, v233
	v_cvt_f32_ubyte2_e32 v250, v233
	v_cvt_f32_ubyte3_e32 v251, v233
	v_mul_f32_e32 v248, s34, v248
	v_mul_f32_e32 v249, s34, v249
	v_mul_f32_e32 v250, s34, v250
	v_mul_f32_e32 v251, s34, v251
	v_fma_f32 v180, v30, v248, v180
	v_fma_f32 v181, v31, v249, v181
	v_fma_f32 v182, v32, v250, v182
	v_fma_f32 v183, v33, v251, v183
	v_mfma_f32_16x16x32_bf16 v[26:29], v[220:223], v[70:73], v[26:29]
	v_cvt_f32_ubyte0_e32 v248, v234
	v_cvt_f32_ubyte1_e32 v249, v234
	v_cvt_f32_ubyte2_e32 v250, v234
	v_cvt_f32_ubyte3_e32 v251, v234
	v_mul_f32_e32 v248, s34, v248
	v_mul_f32_e32 v249, s34, v249
	v_mul_f32_e32 v250, s34, v250
	v_mul_f32_e32 v251, s34, v251
	v_fma_f32 v176, v38, v248, v176
	v_fma_f32 v177, v39, v249, v177
	v_fma_f32 v178, v40, v250, v178
	v_fma_f32 v179, v41, v251, v179
	v_mfma_f32_16x16x32_bf16 v[14:17], v[224:227], v[70:73], v[14:17]
	v_cvt_f32_ubyte0_e32 v248, v235
	v_cvt_f32_ubyte1_e32 v249, v235
	v_cvt_f32_ubyte2_e32 v250, v235
	v_cvt_f32_ubyte3_e32 v251, v235
	v_mul_f32_e32 v248, s34, v248
	v_mul_f32_e32 v249, s34, v249
	v_mul_f32_e32 v250, s34, v250
	v_mul_f32_e32 v251, s34, v251
	v_fma_f32 v172, v42, v248, v172
	v_fma_f32 v173, v43, v249, v173
	v_fma_f32 v174, v44, v250, v174
	v_fma_f32 v175, v45, v251, v175
	v_mfma_f32_16x16x32_bf16 v[10:13], v[228:231], v[70:73], v[10:13]
	v_cvt_f32_ubyte0_e32 v248, v236
	v_cvt_f32_ubyte1_e32 v249, v236
	v_cvt_f32_ubyte2_e32 v250, v236
	v_cvt_f32_ubyte3_e32 v251, v236
	v_mul_f32_e32 v248, s34, v248
	v_mul_f32_e32 v249, s34, v249
	v_mul_f32_e32 v250, s34, v250
	v_mul_f32_e32 v251, s34, v251
	v_fma_f32 v168, v46, v248, v168
	v_fma_f32 v169, v47, v249, v169
	v_fma_f32 v170, v48, v250, v170
	v_fma_f32 v171, v49, v251, v171
	s_waitcnt vmcnt(6)
	s_waitcnt lgkmcnt(0)
	s_barrier
	s_add_i32 m0, s67, 0x0
	s_nop 0
	global_load_lds_dwordx4 v188, s[80:81]
	s_add_i32 m0, s67, 0x2000
	s_nop 0
	global_load_lds_dwordx4 v189, s[80:81]
	s_add_i32 m0, s67, 0x4000
	s_nop 0
	global_load_lds_dwordx4 v190, s[80:81]
	s_add_i32 m0, s67, 0x6000
	s_nop 0
	global_load_lds_dwordx4 v191, s[80:81]
	s_add_i32 m0, s67, 0x18000
	s_nop 0
	global_load_lds_dwordx4 v205, s[96:97]
	s_add_i32 m0, s67, 0x1a000
	s_nop 0
	global_load_lds_dwordx4 v206, s[96:97]
	s_add_u32 s80, s80, 0x80
	s_addc_u32 s81, s81, 0
	s_add_u32 s96, s96, 0x80
	s_addc_u32 s97, s97, 0
	ds_read_b128 v[82:85], v90 offset:16384
	ds_read_b128 v[86:89], v90 offset:18432
	ds_read_b128 v[208:211], v90 offset:20480
	ds_read_b128 v[212:215], v90 offset:22528
	ds_read_b128 v[66:69], v207 offset:32768
	ds_read_b128 v[70:73], v207 offset:34816
	v_mfma_f32_16x16x32_bf16 v[34:37], v[216:219], v[74:77], v[34:37]
	v_cvt_f32_ubyte0_e32 v248, v237
	v_cvt_f32_ubyte1_e32 v249, v237
	v_cvt_f32_ubyte2_e32 v250, v237
	v_cvt_f32_ubyte3_e32 v251, v237
	v_mul_f32_e32 v248, s34, v248
	v_mul_f32_e32 v249, s34, v249
	v_mul_f32_e32 v250, s34, v250
	v_mul_f32_e32 v251, s34, v251
	v_fma_f32 v164, v26, v248, v164
	v_fma_f32 v165, v27, v249, v165
	v_fma_f32 v166, v28, v250, v166
	v_fma_f32 v167, v29, v251, v167
	v_mfma_f32_16x16x32_bf16 v[22:25], v[220:223], v[74:77], v[22:25]
	v_cvt_f32_ubyte0_e32 v248, v238
	v_cvt_f32_ubyte1_e32 v249, v238
	v_cvt_f32_ubyte2_e32 v250, v238
	v_cvt_f32_ubyte3_e32 v251, v238
	v_mul_f32_e32 v248, s34, v248
	v_mul_f32_e32 v249, s34, v249
	v_mul_f32_e32 v250, s34, v250
	v_mul_f32_e32 v251, s34, v251
	v_fma_f32 v160, v14, v248, v160
	v_fma_f32 v161, v15, v249, v161
	v_fma_f32 v162, v16, v250, v162
	v_fma_f32 v163, v17, v251, v163
	v_mfma_f32_16x16x32_bf16 v[18:21], v[224:227], v[74:77], v[18:21]
	v_cvt_f32_ubyte0_e32 v248, v239
	v_cvt_f32_ubyte1_e32 v249, v239
	v_cvt_f32_ubyte2_e32 v250, v239
	v_cvt_f32_ubyte3_e32 v251, v239
	v_mul_f32_e32 v248, s34, v248
	v_mul_f32_e32 v249, s34, v249
	v_mul_f32_e32 v250, s34, v250
	v_mul_f32_e32 v251, s34, v251
	v_fma_f32 v156, v10, v248, v156
	v_fma_f32 v157, v11, v249, v157
	v_fma_f32 v158, v12, v250, v158
	v_fma_f32 v159, v13, v251, v159
	v_mfma_f32_16x16x32_bf16 v[62:65], v[228:231], v[74:77], v[62:65]
	v_cvt_f32_ubyte0_e32 v248, v240
	v_cvt_f32_ubyte1_e32 v249, v240
	v_cvt_f32_ubyte2_e32 v250, v240
	v_cvt_f32_ubyte3_e32 v251, v240
	v_mul_f32_e32 v248, s34, v248
	v_mul_f32_e32 v249, s34, v249
	v_mul_f32_e32 v250, s34, v250
	v_mul_f32_e32 v251, s34, v251
	v_fma_f32 v136, v34, v248, v136
	v_fma_f32 v137, v35, v249, v137
	v_fma_f32 v150, v36, v250, v150
	v_fma_f32 v151, v37, v251, v151
	ds_read_b128 v[74:77], v207 offset:36864
	v_mfma_f32_16x16x32_bf16 v[58:61], v[216:219], v[78:81], v[58:61]
	v_cvt_f32_ubyte0_e32 v248, v241
	v_cvt_f32_ubyte1_e32 v249, v241
	v_cvt_f32_ubyte2_e32 v250, v241
	v_cvt_f32_ubyte3_e32 v251, v241
	v_mul_f32_e32 v248, s34, v248
	v_mul_f32_e32 v249, s34, v249
	v_mul_f32_e32 v250, s34, v250
	v_mul_f32_e32 v251, s34, v251
	v_fma_f32 v130, v22, v248, v130
	v_fma_f32 v131, v23, v249, v131
	v_fma_f32 v134, v24, v250, v134
	v_fma_f32 v135, v25, v251, v135
	v_mfma_f32_16x16x32_bf16 v[54:57], v[220:223], v[78:81], v[54:57]
	v_cvt_f32_ubyte0_e32 v248, v242
	v_cvt_f32_ubyte1_e32 v249, v242
	v_cvt_f32_ubyte2_e32 v250, v242
	v_cvt_f32_ubyte3_e32 v251, v242
	v_mul_f32_e32 v248, s34, v248
	v_mul_f32_e32 v249, s34, v249
	v_mul_f32_e32 v250, s34, v250
	v_mul_f32_e32 v251, s34, v251
	v_fma_f32 v124, v18, v248, v124
	v_fma_f32 v125, v19, v249, v125
	v_fma_f32 v126, v20, v250, v126
	v_fma_f32 v127, v21, v251, v127
	v_mfma_f32_16x16x32_bf16 v[50:53], v[224:227], v[78:81], v[50:53]
	v_cvt_f32_ubyte0_e32 v248, v243
	v_cvt_f32_ubyte1_e32 v249, v243
	v_cvt_f32_ubyte2_e32 v250, v243
	v_cvt_f32_ubyte3_e32 v251, v243
	v_mul_f32_e32 v248, s34, v248
	v_mul_f32_e32 v249, s34, v249
	v_mul_f32_e32 v250, s34, v250
	v_mul_f32_e32 v251, s34, v251
	v_fma_f32 v120, v62, v248, v120
	v_fma_f32 v121, v63, v249, v121
	v_fma_f32 v122, v64, v250, v122
	v_fma_f32 v123, v65, v251, v123
	v_mfma_f32_16x16x32_bf16 v[2:5], v[228:231], v[78:81], v[2:5]
	v_cvt_f32_ubyte0_e32 v248, v244
	v_cvt_f32_ubyte1_e32 v249, v244
	v_cvt_f32_ubyte2_e32 v250, v244
	v_cvt_f32_ubyte3_e32 v251, v244
	v_mul_f32_e32 v248, s34, v248
	v_mul_f32_e32 v249, s34, v249
	v_mul_f32_e32 v250, s34, v250
	v_mul_f32_e32 v251, s34, v251
	v_fma_f32 v114, v58, v248, v114
	v_fma_f32 v115, v59, v249, v115
	v_fma_f32 v116, v60, v250, v116
	v_fma_f32 v117, v61, v251, v117
	ds_read_b128 v[78:81], v207 offset:38912
	s_nop 7
	s_nop 3
	v_cvt_f32_ubyte0_e32 v248, v245
	v_cvt_f32_ubyte1_e32 v249, v245
	v_cvt_f32_ubyte2_e32 v250, v245
	v_cvt_f32_ubyte3_e32 v251, v245
	v_mul_f32_e32 v248, s34, v248
	v_mul_f32_e32 v249, s34, v249
	v_mul_f32_e32 v250, s34, v250
	v_mul_f32_e32 v251, s34, v251
	v_fma_f32 v106, v54, v248, v106
	v_fma_f32 v107, v55, v249, v107
	v_fma_f32 v108, v56, v250, v108
	v_fma_f32 v109, v57, v251, v109
	v_cvt_f32_ubyte0_e32 v248, v246
	v_cvt_f32_ubyte1_e32 v249, v246
	v_cvt_f32_ubyte2_e32 v250, v246
	v_cvt_f32_ubyte3_e32 v251, v246
	v_mul_f32_e32 v248, s34, v248
	v_mul_f32_e32 v249, s34, v249
	v_mul_f32_e32 v250, s34, v250
	v_mul_f32_e32 v251, s34, v251
	v_fma_f32 v100, v50, v248, v100
	v_fma_f32 v101, v51, v249, v101
	v_fma_f32 v102, v52, v250, v102
	v_fma_f32 v103, v53, v251, v103
	v_cvt_f32_ubyte0_e32 v248, v247
	v_cvt_f32_ubyte1_e32 v249, v247
	v_cvt_f32_ubyte2_e32 v250, v247
	v_cvt_f32_ubyte3_e32 v251, v247
	v_mul_f32_e32 v248, s34, v248
	v_mul_f32_e32 v249, s34, v249
	v_mul_f32_e32 v250, s34, v250
	v_mul_f32_e32 v251, s34, v251
	v_fma_f32 v96, v2, v248, v96
	v_fma_f32 v97, v3, v249, v97
	v_fma_f32 v98, v4, v250, v98
	v_fma_f32 v99, v5, v251, v99
	s_add_u32 s98, s86, 0x2200
	s_addc_u32 s99, s87, 0
	global_load_dword v92, v93, s[98:99]
	ds_read_b128 v[216:219], v91 offset:16384
	ds_read_b128 v[220:223], v91 offset:18432
	ds_read_b128 v[224:227], v91 offset:20480
	ds_read_b128 v[228:231], v91 offset:22528
	s_waitcnt lgkmcnt(7)
	v_mfma_f32_16x16x32_bf16 v[6:9], v[82:85], v[66:69], 0
	v_mfma_f32_16x16x32_bf16 v[30:33], v[86:89], v[66:69], 0
	v_mfma_f32_16x16x32_bf16 v[38:41], v[208:211], v[66:69], 0
	v_mfma_f32_16x16x32_bf16 v[42:45], v[212:215], v[66:69], 0
	ds_read_b128 v[66:69], v119 offset:32768
	s_waitcnt lgkmcnt(7)
	v_mfma_f32_16x16x32_bf16 v[46:49], v[82:85], v[70:73], 0
	v_mfma_f32_16x16x32_bf16 v[26:29], v[86:89], v[70:73], 0
	v_mfma_f32_16x16x32_bf16 v[14:17], v[208:211], v[70:73], 0
	v_mfma_f32_16x16x32_bf16 v[10:13], v[212:215], v[70:73], 0
	ds_read_b128 v[70:73], v119 offset:34816
	s_waitcnt lgkmcnt(7)
	v_mfma_f32_16x16x32_bf16 v[34:37], v[82:85], v[74:77], 0
	v_mfma_f32_16x16x32_bf16 v[22:25], v[86:89], v[74:77], 0
	v_mfma_f32_16x16x32_bf16 v[18:21], v[208:211], v[74:77], 0
	v_mfma_f32_16x16x32_bf16 v[62:65], v[212:215], v[74:77], 0
	ds_read_b128 v[74:77], v119 offset:36864
	s_waitcnt lgkmcnt(7)
	v_mfma_f32_16x16x32_bf16 v[58:61], v[82:85], v[78:81], 0
	v_mfma_f32_16x16x32_bf16 v[54:57], v[86:89], v[78:81], 0
	v_mfma_f32_16x16x32_bf16 v[50:53], v[208:211], v[78:81], 0
	v_mfma_f32_16x16x32_bf16 v[2:5], v[212:215], v[78:81], 0
	ds_read_b128 v[78:81], v119 offset:38912
	s_waitcnt lgkmcnt(3)
	v_mfma_f32_16x16x32_bf16 v[6:9], v[216:219], v[66:69], v[6:9]
	v_mfma_f32_16x16x32_bf16 v[30:33], v[220:223], v[66:69], v[30:33]
	v_mfma_f32_16x16x32_bf16 v[38:41], v[224:227], v[66:69], v[38:41]
	v_mfma_f32_16x16x32_bf16 v[42:45], v[228:231], v[66:69], v[42:45]
	s_waitcnt lgkmcnt(2)
	v_mfma_f32_16x16x32_bf16 v[46:49], v[216:219], v[70:73], v[46:49]
	v_mfma_f32_16x16x32_bf16 v[26:29], v[220:223], v[70:73], v[26:29]
	v_mfma_f32_16x16x32_bf16 v[14:17], v[224:227], v[70:73], v[14:17]
	v_mfma_f32_16x16x32_bf16 v[10:13], v[228:231], v[70:73], v[10:13]
	s_waitcnt vmcnt(7)
	s_waitcnt lgkmcnt(0)
	s_barrier
	s_add_i32 m0, s67, 0x8000
	s_nop 0
	global_load_lds_dwordx4 v188, s[80:81]
	s_add_i32 m0, s67, 0xa000
	s_nop 0
	global_load_lds_dwordx4 v189, s[80:81]
	s_add_i32 m0, s67, 0xc000
	s_nop 0
	global_load_lds_dwordx4 v190, s[80:81]
	s_add_i32 m0, s67, 0xe000
	s_nop 0
	global_load_lds_dwordx4 v191, s[80:81]
	s_add_i32 m0, s67, 0x1c000
	s_nop 0
	global_load_lds_dwordx4 v205, s[96:97]
	s_add_i32 m0, s67, 0x1e000
	s_nop 0
	global_load_lds_dwordx4 v206, s[96:97]
	s_add_u32 s80, s80, 0x80
	s_addc_u32 s81, s81, 0
	s_add_u32 s96, s96, 0x80
	s_addc_u32 s97, s97, 0
	ds_read_b128 v[82:85], v90 offset:33792
	ds_read_b128 v[86:89], v90 offset:35840
	ds_read_b128 v[208:211], v90 offset:37888
	ds_read_b128 v[212:215], v90 offset:39936
	ds_read_b128 v[66:69], v0 offset:0
	ds_read_b128 v[70:73], v0 offset:2048
	v_mfma_f32_16x16x32_bf16 v[34:37], v[216:219], v[74:77], v[34:37]
	v_mfma_f32_16x16x32_bf16 v[22:25], v[220:223], v[74:77], v[22:25]
	v_mfma_f32_16x16x32_bf16 v[18:21], v[224:227], v[74:77], v[18:21]
	v_mfma_f32_16x16x32_bf16 v[62:65], v[228:231], v[74:77], v[62:65]
	ds_read_b128 v[74:77], v0 offset:4096
	v_mfma_f32_16x16x32_bf16 v[58:61], v[216:219], v[78:81], v[58:61]
	v_mfma_f32_16x16x32_bf16 v[54:57], v[220:223], v[78:81], v[54:57]
	v_mfma_f32_16x16x32_bf16 v[50:53], v[224:227], v[78:81], v[50:53]
	v_mfma_f32_16x16x32_bf16 v[2:5], v[228:231], v[78:81], v[2:5]
	ds_read_b128 v[78:81], v0 offset:6144
	ds_read_b128 v[216:219], v91 offset:33792
	ds_read_b128 v[220:223], v91 offset:35840
	ds_read_b128 v[224:227], v91 offset:37888
	ds_read_b128 v[228:231], v91 offset:39936
	s_waitcnt lgkmcnt(7)
	v_mfma_f32_16x16x32_bf16 v[6:9], v[82:85], v[66:69], v[6:9]
	v_mfma_f32_16x16x32_bf16 v[30:33], v[86:89], v[66:69], v[30:33]
	v_mfma_f32_16x16x32_bf16 v[38:41], v[208:211], v[66:69], v[38:41]
	v_mfma_f32_16x16x32_bf16 v[42:45], v[212:215], v[66:69], v[42:45]
	ds_read_b128 v[66:69], v255 offset:0
	s_waitcnt lgkmcnt(7)
	v_mfma_f32_16x16x32_bf16 v[46:49], v[82:85], v[70:73], v[46:49]
	v_mfma_f32_16x16x32_bf16 v[26:29], v[86:89], v[70:73], v[26:29]
	v_mfma_f32_16x16x32_bf16 v[14:17], v[208:211], v[70:73], v[14:17]
	v_mfma_f32_16x16x32_bf16 v[10:13], v[212:215], v[70:73], v[10:13]
	ds_read_b128 v[70:73], v255 offset:2048
	s_waitcnt lgkmcnt(7)
	v_mfma_f32_16x16x32_bf16 v[34:37], v[82:85], v[74:77], v[34:37]
	v_mfma_f32_16x16x32_bf16 v[22:25], v[86:89], v[74:77], v[22:25]
	v_mfma_f32_16x16x32_bf16 v[18:21], v[208:211], v[74:77], v[18:21]
	v_mfma_f32_16x16x32_bf16 v[62:65], v[212:215], v[74:77], v[62:65]
	ds_read_b128 v[74:77], v255 offset:4096
	s_waitcnt lgkmcnt(7)
	v_mfma_f32_16x16x32_bf16 v[58:61], v[82:85], v[78:81], v[58:61]
	v_mfma_f32_16x16x32_bf16 v[54:57], v[86:89], v[78:81], v[54:57]
	v_mfma_f32_16x16x32_bf16 v[50:53], v[208:211], v[78:81], v[50:53]
	v_mfma_f32_16x16x32_bf16 v[2:5], v[212:215], v[78:81], v[2:5]
	ds_read_b128 v[78:81], v255 offset:6144
	s_waitcnt lgkmcnt(3)
	v_mfma_f32_16x16x32_bf16 v[6:9], v[216:219], v[66:69], v[6:9]
	v_mfma_f32_16x16x32_bf16 v[30:33], v[220:223], v[66:69], v[30:33]
	v_mfma_f32_16x16x32_bf16 v[38:41], v[224:227], v[66:69], v[38:41]
	v_mfma_f32_16x16x32_bf16 v[42:45], v[228:231], v[66:69], v[42:45]
	s_waitcnt lgkmcnt(2)
	v_mfma_f32_16x16x32_bf16 v[46:49], v[216:219], v[70:73], v[46:49]
	v_mfma_f32_16x16x32_bf16 v[26:29], v[220:223], v[70:73], v[26:29]
	v_mfma_f32_16x16x32_bf16 v[14:17], v[224:227], v[70:73], v[14:17]
	v_mfma_f32_16x16x32_bf16 v[10:13], v[228:231], v[70:73], v[10:13]
	s_waitcnt vmcnt(7)
	s_waitcnt lgkmcnt(0)
	s_barrier
	s_add_i32 m0, s67, 0x10000
	s_nop 0
	global_load_lds_dwordx4 v188, s[80:81]
	s_add_i32 m0, s67, 0x12000
	s_nop 0
	global_load_lds_dwordx4 v189, s[80:81]
	s_add_i32 m0, s67, 0x14000
	s_nop 0
	global_load_lds_dwordx4 v190, s[80:81]
	s_add_i32 m0, s67, 0x16000
	s_nop 0
	global_load_lds_dwordx4 v191, s[80:81]
	s_add_i32 m0, s67, 0x20400
	s_nop 0
	global_load_lds_dwordx4 v205, s[96:97]
	s_add_i32 m0, s67, 0x22400
	s_nop 0
	global_load_lds_dwordx4 v206, s[96:97]
	s_add_u32 s80, s80, 0x80
	s_addc_u32 s81, s81, 0
	s_add_u32 s96, s96, 0x80
	s_addc_u32 s97, s97, 0
	ds_read_b128 v[82:85], v90 offset:0
	ds_read_b128 v[86:89], v90 offset:2048
	ds_read_b128 v[208:211], v90 offset:4096
	ds_read_b128 v[212:215], v90 offset:6144
	ds_read_b128 v[66:69], v207 offset:0
	ds_read_b128 v[70:73], v207 offset:2048
	v_mfma_f32_16x16x32_bf16 v[34:37], v[216:219], v[74:77], v[34:37]
	v_mfma_f32_16x16x32_bf16 v[22:25], v[220:223], v[74:77], v[22:25]
	v_mfma_f32_16x16x32_bf16 v[18:21], v[224:227], v[74:77], v[18:21]
	v_mfma_f32_16x16x32_bf16 v[62:65], v[228:231], v[74:77], v[62:65]
	ds_read_b128 v[74:77], v207 offset:4096
	v_mfma_f32_16x16x32_bf16 v[58:61], v[216:219], v[78:81], v[58:61]
	v_mfma_f32_16x16x32_bf16 v[54:57], v[220:223], v[78:81], v[54:57]
	v_mfma_f32_16x16x32_bf16 v[50:53], v[224:227], v[78:81], v[50:53]
	v_mfma_f32_16x16x32_bf16 v[2:5], v[228:231], v[78:81], v[2:5]
	ds_read_b128 v[78:81], v207 offset:6144
	ds_read_b128 v[216:219], v91 offset:0
	ds_read_b128 v[220:223], v91 offset:2048
	ds_read_b128 v[224:227], v91 offset:4096
	ds_read_b128 v[228:231], v91 offset:6144
	s_waitcnt lgkmcnt(7)
	v_mfma_f32_16x16x32_bf16 v[6:9], v[82:85], v[66:69], v[6:9]
	v_mfma_f32_16x16x32_bf16 v[30:33], v[86:89], v[66:69], v[30:33]
	v_mfma_f32_16x16x32_bf16 v[38:41], v[208:211], v[66:69], v[38:41]
	v_mfma_f32_16x16x32_bf16 v[42:45], v[212:215], v[66:69], v[42:45]
	ds_read_b128 v[66:69], v119 offset:0
	s_waitcnt lgkmcnt(7)
	v_mfma_f32_16x16x32_bf16 v[46:49], v[82:85], v[70:73], v[46:49]
	v_mfma_f32_16x16x32_bf16 v[26:29], v[86:89], v[70:73], v[26:29]
	v_mfma_f32_16x16x32_bf16 v[14:17], v[208:211], v[70:73], v[14:17]
	v_mfma_f32_16x16x32_bf16 v[10:13], v[212:215], v[70:73], v[10:13]
	ds_read_b128 v[70:73], v119 offset:2048
	s_waitcnt lgkmcnt(7)
	v_mfma_f32_16x16x32_bf16 v[34:37], v[82:85], v[74:77], v[34:37]
	v_mfma_f32_16x16x32_bf16 v[22:25], v[86:89], v[74:77], v[22:25]
	v_mfma_f32_16x16x32_bf16 v[18:21], v[208:211], v[74:77], v[18:21]
	v_mfma_f32_16x16x32_bf16 v[62:65], v[212:215], v[74:77], v[62:65]
	ds_read_b128 v[74:77], v119 offset:4096
	s_waitcnt lgkmcnt(7)
	v_mfma_f32_16x16x32_bf16 v[58:61], v[82:85], v[78:81], v[58:61]
	v_mfma_f32_16x16x32_bf16 v[54:57], v[86:89], v[78:81], v[54:57]
	v_mfma_f32_16x16x32_bf16 v[50:53], v[208:211], v[78:81], v[50:53]
	v_mfma_f32_16x16x32_bf16 v[2:5], v[212:215], v[78:81], v[2:5]
	ds_read_b128 v[78:81], v119 offset:6144
	s_waitcnt lgkmcnt(3)
	v_mfma_f32_16x16x32_bf16 v[6:9], v[216:219], v[66:69], v[6:9]
	v_mfma_f32_16x16x32_bf16 v[30:33], v[220:223], v[66:69], v[30:33]
	v_mfma_f32_16x16x32_bf16 v[38:41], v[224:227], v[66:69], v[38:41]
	v_mfma_f32_16x16x32_bf16 v[42:45], v[228:231], v[66:69], v[42:45]
	s_waitcnt lgkmcnt(2)
	v_mfma_f32_16x16x32_bf16 v[46:49], v[216:219], v[70:73], v[46:49]
	v_mfma_f32_16x16x32_bf16 v[26:29], v[220:223], v[70:73], v[26:29]
	v_mfma_f32_16x16x32_bf16 v[14:17], v[224:227], v[70:73], v[14:17]
	v_mfma_f32_16x16x32_bf16 v[10:13], v[228:231], v[70:73], v[10:13]
	s_waitcnt vmcnt(6)
	s_waitcnt lgkmcnt(0)
	s_barrier
	s_add_i32 m0, s67, 0x0
	s_nop 0
	global_load_lds_dwordx4 v188, s[80:81]
	s_add_i32 m0, s67, 0x2000
	s_nop 0
	global_load_lds_dwordx4 v189, s[80:81]
	s_add_i32 m0, s67, 0x4000
	s_nop 0
	global_load_lds_dwordx4 v190, s[80:81]
	s_add_i32 m0, s67, 0x6000
	s_nop 0
	global_load_lds_dwordx4 v191, s[80:81]
	s_add_i32 m0, s67, 0x18000
	s_nop 0
	global_load_lds_dwordx4 v205, s[96:97]
	s_add_i32 m0, s67, 0x1a000
	s_nop 0
	global_load_lds_dwordx4 v206, s[96:97]
	s_add_u32 s80, s80, 0x80
	s_addc_u32 s81, s81, 0
	s_add_u32 s96, s96, 0x80
	s_addc_u32 s97, s97, 0
	ds_read_b128 v[82:85], v90 offset:16384
	ds_read_b128 v[86:89], v90 offset:18432
	ds_read_b128 v[208:211], v90 offset:20480
	ds_read_b128 v[212:215], v90 offset:22528
	ds_read_b128 v[66:69], v207 offset:32768
	ds_read_b128 v[70:73], v207 offset:34816
	v_mfma_f32_16x16x32_bf16 v[34:37], v[216:219], v[74:77], v[34:37]
	v_mfma_f32_16x16x32_bf16 v[22:25], v[220:223], v[74:77], v[22:25]
	v_mfma_f32_16x16x32_bf16 v[18:21], v[224:227], v[74:77], v[18:21]
	v_mfma_f32_16x16x32_bf16 v[62:65], v[228:231], v[74:77], v[62:65]
	ds_read_b128 v[74:77], v207 offset:36864
	v_mfma_f32_16x16x32_bf16 v[58:61], v[216:219], v[78:81], v[58:61]
	v_mfma_f32_16x16x32_bf16 v[54:57], v[220:223], v[78:81], v[54:57]
	v_mfma_f32_16x16x32_bf16 v[50:53], v[224:227], v[78:81], v[50:53]
	v_mfma_f32_16x16x32_bf16 v[2:5], v[228:231], v[78:81], v[2:5]
	ds_read_b128 v[78:81], v207 offset:38912
	ds_read_b128 v[216:219], v91 offset:16384
	ds_read_b128 v[220:223], v91 offset:18432
	ds_read_b128 v[224:227], v91 offset:20480
	ds_read_b128 v[228:231], v91 offset:22528
	s_waitcnt lgkmcnt(7)
	v_mfma_f32_16x16x32_bf16 v[6:9], v[82:85], v[66:69], v[6:9]
	v_mfma_f32_16x16x32_bf16 v[30:33], v[86:89], v[66:69], v[30:33]
	v_mfma_f32_16x16x32_bf16 v[38:41], v[208:211], v[66:69], v[38:41]
	v_mfma_f32_16x16x32_bf16 v[42:45], v[212:215], v[66:69], v[42:45]
	ds_read_b128 v[66:69], v119 offset:32768
	s_waitcnt lgkmcnt(7)
	v_mfma_f32_16x16x32_bf16 v[46:49], v[82:85], v[70:73], v[46:49]
	v_mfma_f32_16x16x32_bf16 v[26:29], v[86:89], v[70:73], v[26:29]
	v_mfma_f32_16x16x32_bf16 v[14:17], v[208:211], v[70:73], v[14:17]
	v_mfma_f32_16x16x32_bf16 v[10:13], v[212:215], v[70:73], v[10:13]
	ds_read_b128 v[70:73], v119 offset:34816
	s_waitcnt lgkmcnt(7)
	v_mfma_f32_16x16x32_bf16 v[34:37], v[82:85], v[74:77], v[34:37]
	v_mfma_f32_16x16x32_bf16 v[22:25], v[86:89], v[74:77], v[22:25]
	v_mfma_f32_16x16x32_bf16 v[18:21], v[208:211], v[74:77], v[18:21]
	v_mfma_f32_16x16x32_bf16 v[62:65], v[212:215], v[74:77], v[62:65]
	ds_read_b128 v[74:77], v119 offset:36864
	s_waitcnt lgkmcnt(7)
	v_mfma_f32_16x16x32_bf16 v[58:61], v[82:85], v[78:81], v[58:61]
	v_mfma_f32_16x16x32_bf16 v[54:57], v[86:89], v[78:81], v[54:57]
	v_mfma_f32_16x16x32_bf16 v[50:53], v[208:211], v[78:81], v[50:53]
	v_mfma_f32_16x16x32_bf16 v[2:5], v[212:215], v[78:81], v[2:5]
	ds_read_b128 v[78:81], v119 offset:38912
	s_waitcnt lgkmcnt(3)
	v_mfma_f32_16x16x32_bf16 v[6:9], v[216:219], v[66:69], v[6:9]
	v_mfma_f32_16x16x32_bf16 v[30:33], v[220:223], v[66:69], v[30:33]
	v_mfma_f32_16x16x32_bf16 v[38:41], v[224:227], v[66:69], v[38:41]
	v_mfma_f32_16x16x32_bf16 v[42:45], v[228:231], v[66:69], v[42:45]
	s_waitcnt lgkmcnt(2)
	v_mfma_f32_16x16x32_bf16 v[46:49], v[216:219], v[70:73], v[46:49]
	v_mfma_f32_16x16x32_bf16 v[26:29], v[220:223], v[70:73], v[26:29]
	v_mfma_f32_16x16x32_bf16 v[14:17], v[224:227], v[70:73], v[14:17]
	v_mfma_f32_16x16x32_bf16 v[10:13], v[228:231], v[70:73], v[10:13]
	s_waitcnt vmcnt(6)
	s_waitcnt lgkmcnt(0)
	s_barrier
	s_add_i32 m0, s67, 0x8000
	s_nop 0
	global_load_lds_dwordx4 v188, s[80:81]
	s_add_i32 m0, s67, 0xa000
	s_nop 0
	global_load_lds_dwordx4 v189, s[80:81]
	s_add_i32 m0, s67, 0xc000
	s_nop 0
	global_load_lds_dwordx4 v190, s[80:81]
	s_add_i32 m0, s67, 0xe000
	s_nop 0
	global_load_lds_dwordx4 v191, s[80:81]
	s_add_i32 m0, s67, 0x1c000
	s_nop 0
	global_load_lds_dwordx4 v205, s[96:97]
	s_add_i32 m0, s67, 0x1e000
	s_nop 0
	global_load_lds_dwordx4 v206, s[96:97]
	s_add_u32 s80, s80, 0x80
	s_addc_u32 s81, s81, 0
	s_add_u32 s96, s96, 0x80
	s_addc_u32 s97, s97, 0
	s_movk_i32 s10, 0x800
	s_mov_b32 s11, 0
	v_lshl_add_u64 v[248:249], v[128:129], 0, s[10:11]
	global_load_dwordx2 v[232:233], v[248:249], off
	global_load_dwordx2 v[234:235], v[248:249], off offset:32
	v_lshl_add_u64 v[248:249], v[132:133], 0, s[10:11]
	global_load_dwordx2 v[236:237], v[248:249], off
	global_load_dwordx2 v[238:239], v[248:249], off offset:32
	v_lshl_add_u64 v[248:249], v[152:153], 0, s[10:11]
	global_load_dwordx2 v[240:241], v[248:249], off
	global_load_dwordx2 v[242:243], v[248:249], off offset:32
	v_lshl_add_u64 v[248:249], v[154:155], 0, s[10:11]
	global_load_dwordx2 v[244:245], v[248:249], off
	global_load_dwordx2 v[246:247], v[248:249], off offset:32
	ds_read_b128 v[82:85], v90 offset:33792
	ds_read_b128 v[86:89], v90 offset:35840
	ds_read_b128 v[208:211], v90 offset:37888
	ds_read_b128 v[212:215], v90 offset:39936
	ds_read_b128 v[66:69], v0 offset:0
	ds_read_b128 v[70:73], v0 offset:2048
	v_mfma_f32_16x16x32_bf16 v[34:37], v[216:219], v[74:77], v[34:37]
	v_mfma_f32_16x16x32_bf16 v[22:25], v[220:223], v[74:77], v[22:25]
	v_mfma_f32_16x16x32_bf16 v[18:21], v[224:227], v[74:77], v[18:21]
	v_mfma_f32_16x16x32_bf16 v[62:65], v[228:231], v[74:77], v[62:65]
	ds_read_b128 v[74:77], v0 offset:4096
	v_mfma_f32_16x16x32_bf16 v[58:61], v[216:219], v[78:81], v[58:61]
	v_mfma_f32_16x16x32_bf16 v[54:57], v[220:223], v[78:81], v[54:57]
	v_mfma_f32_16x16x32_bf16 v[50:53], v[224:227], v[78:81], v[50:53]
	v_mfma_f32_16x16x32_bf16 v[2:5], v[228:231], v[78:81], v[2:5]
	ds_read_b128 v[78:81], v0 offset:6144
	ds_read_b128 v[216:219], v91 offset:33792
	ds_read_b128 v[220:223], v91 offset:35840
	ds_read_b128 v[224:227], v91 offset:37888
	ds_read_b128 v[228:231], v91 offset:39936
	s_waitcnt lgkmcnt(7)
	v_mfma_f32_16x16x32_bf16 v[6:9], v[82:85], v[66:69], v[6:9]
	v_mfma_f32_16x16x32_bf16 v[30:33], v[86:89], v[66:69], v[30:33]
	v_mfma_f32_16x16x32_bf16 v[38:41], v[208:211], v[66:69], v[38:41]
	v_mfma_f32_16x16x32_bf16 v[42:45], v[212:215], v[66:69], v[42:45]
	ds_read_b128 v[66:69], v255 offset:0
	s_waitcnt lgkmcnt(7)
	v_mfma_f32_16x16x32_bf16 v[46:49], v[82:85], v[70:73], v[46:49]
	v_mfma_f32_16x16x32_bf16 v[26:29], v[86:89], v[70:73], v[26:29]
	v_mfma_f32_16x16x32_bf16 v[14:17], v[208:211], v[70:73], v[14:17]
	v_mfma_f32_16x16x32_bf16 v[10:13], v[212:215], v[70:73], v[10:13]
	ds_read_b128 v[70:73], v255 offset:2048
	s_waitcnt lgkmcnt(7)
	v_mfma_f32_16x16x32_bf16 v[34:37], v[82:85], v[74:77], v[34:37]
	v_mfma_f32_16x16x32_bf16 v[22:25], v[86:89], v[74:77], v[22:25]
	v_mfma_f32_16x16x32_bf16 v[18:21], v[208:211], v[74:77], v[18:21]
	v_mfma_f32_16x16x32_bf16 v[62:65], v[212:215], v[74:77], v[62:65]
	ds_read_b128 v[74:77], v255 offset:4096
	s_waitcnt lgkmcnt(7)
	v_mfma_f32_16x16x32_bf16 v[58:61], v[82:85], v[78:81], v[58:61]
	v_mfma_f32_16x16x32_bf16 v[54:57], v[86:89], v[78:81], v[54:57]
	v_mfma_f32_16x16x32_bf16 v[50:53], v[208:211], v[78:81], v[50:53]
	v_mfma_f32_16x16x32_bf16 v[2:5], v[212:215], v[78:81], v[2:5]
	ds_read_b128 v[78:81], v255 offset:6144
	s_waitcnt lgkmcnt(3)
	v_mfma_f32_16x16x32_bf16 v[6:9], v[216:219], v[66:69], v[6:9]
	v_mfma_f32_16x16x32_bf16 v[30:33], v[220:223], v[66:69], v[30:33]
	v_mfma_f32_16x16x32_bf16 v[38:41], v[224:227], v[66:69], v[38:41]
	v_mfma_f32_16x16x32_bf16 v[42:45], v[228:231], v[66:69], v[42:45]
	s_waitcnt lgkmcnt(2)
	v_mfma_f32_16x16x32_bf16 v[46:49], v[216:219], v[70:73], v[46:49]
	v_mfma_f32_16x16x32_bf16 v[26:29], v[220:223], v[70:73], v[26:29]
	v_mfma_f32_16x16x32_bf16 v[14:17], v[224:227], v[70:73], v[14:17]
	v_mfma_f32_16x16x32_bf16 v[10:13], v[228:231], v[70:73], v[10:13]
	s_waitcnt vmcnt(14)
	s_waitcnt lgkmcnt(0)
	s_barrier
	s_add_i32 m0, s67, 0x10000
	s_nop 0
	global_load_lds_dwordx4 v188, s[80:81]
	s_add_i32 m0, s67, 0x12000
	s_nop 0
	global_load_lds_dwordx4 v189, s[80:81]
	s_add_i32 m0, s67, 0x14000
	s_nop 0
	global_load_lds_dwordx4 v190, s[80:81]
	s_add_i32 m0, s67, 0x16000
	s_nop 0
	global_load_lds_dwordx4 v191, s[80:81]
	s_add_i32 m0, s67, 0x20400
	s_nop 0
	global_load_lds_dwordx4 v205, s[96:97]
	s_add_i32 m0, s67, 0x22400
	s_nop 0
	global_load_lds_dwordx4 v206, s[96:97]
	s_add_u32 s80, s80, 0x880
	s_addc_u32 s81, s81, 0
	s_add_u32 s96, s96, 0xffc80
	s_addc_u32 s97, s97, 0
	ds_read_b128 v[82:85], v90 offset:0
	ds_read_b128 v[86:89], v90 offset:2048
	ds_read_b128 v[208:211], v90 offset:4096
	ds_read_b128 v[212:215], v90 offset:6144
	ds_read_b128 v[66:69], v207 offset:0
	ds_read_b128 v[70:73], v207 offset:2048
	v_mfma_f32_16x16x32_bf16 v[34:37], v[216:219], v[74:77], v[34:37]
	v_mfma_f32_16x16x32_bf16 v[22:25], v[220:223], v[74:77], v[22:25]
	v_mfma_f32_16x16x32_bf16 v[18:21], v[224:227], v[74:77], v[18:21]
	v_mfma_f32_16x16x32_bf16 v[62:65], v[228:231], v[74:77], v[62:65]
	ds_read_b128 v[74:77], v207 offset:4096
	v_mfma_f32_16x16x32_bf16 v[58:61], v[216:219], v[78:81], v[58:61]
	v_mfma_f32_16x16x32_bf16 v[54:57], v[220:223], v[78:81], v[54:57]
	v_mfma_f32_16x16x32_bf16 v[50:53], v[224:227], v[78:81], v[50:53]
	v_mfma_f32_16x16x32_bf16 v[2:5], v[228:231], v[78:81], v[2:5]
	ds_read_b128 v[78:81], v207 offset:6144
	ds_read_b128 v[216:219], v91 offset:0
	ds_read_b128 v[220:223], v91 offset:2048
	ds_read_b128 v[224:227], v91 offset:4096
	ds_read_b128 v[228:231], v91 offset:6144
	s_waitcnt lgkmcnt(7)
	v_mfma_f32_16x16x32_bf16 v[6:9], v[82:85], v[66:69], v[6:9]
	v_mfma_f32_16x16x32_bf16 v[30:33], v[86:89], v[66:69], v[30:33]
	v_mfma_f32_16x16x32_bf16 v[38:41], v[208:211], v[66:69], v[38:41]
	v_mfma_f32_16x16x32_bf16 v[42:45], v[212:215], v[66:69], v[42:45]
	ds_read_b128 v[66:69], v119 offset:0
	s_waitcnt lgkmcnt(7)
	v_mfma_f32_16x16x32_bf16 v[46:49], v[82:85], v[70:73], v[46:49]
	v_mfma_f32_16x16x32_bf16 v[26:29], v[86:89], v[70:73], v[26:29]
	v_mfma_f32_16x16x32_bf16 v[14:17], v[208:211], v[70:73], v[14:17]
	v_mfma_f32_16x16x32_bf16 v[10:13], v[212:215], v[70:73], v[10:13]
	ds_read_b128 v[70:73], v119 offset:2048
	s_waitcnt lgkmcnt(7)
	v_mfma_f32_16x16x32_bf16 v[34:37], v[82:85], v[74:77], v[34:37]
	v_mfma_f32_16x16x32_bf16 v[22:25], v[86:89], v[74:77], v[22:25]
	v_mfma_f32_16x16x32_bf16 v[18:21], v[208:211], v[74:77], v[18:21]
	v_mfma_f32_16x16x32_bf16 v[62:65], v[212:215], v[74:77], v[62:65]
	ds_read_b128 v[74:77], v119 offset:4096
	s_waitcnt lgkmcnt(7)
	v_mfma_f32_16x16x32_bf16 v[58:61], v[82:85], v[78:81], v[58:61]
	v_mfma_f32_16x16x32_bf16 v[54:57], v[86:89], v[78:81], v[54:57]
	v_mfma_f32_16x16x32_bf16 v[50:53], v[208:211], v[78:81], v[50:53]
	v_mfma_f32_16x16x32_bf16 v[2:5], v[212:215], v[78:81], v[2:5]
	ds_read_b128 v[78:81], v119 offset:6144
	s_waitcnt lgkmcnt(3)
	v_mfma_f32_16x16x32_bf16 v[6:9], v[216:219], v[66:69], v[6:9]
	v_mfma_f32_16x16x32_bf16 v[30:33], v[220:223], v[66:69], v[30:33]
	v_mfma_f32_16x16x32_bf16 v[38:41], v[224:227], v[66:69], v[38:41]
	v_mfma_f32_16x16x32_bf16 v[42:45], v[228:231], v[66:69], v[42:45]
	s_waitcnt lgkmcnt(2)
	v_mfma_f32_16x16x32_bf16 v[46:49], v[216:219], v[70:73], v[46:49]
	v_mfma_f32_16x16x32_bf16 v[26:29], v[220:223], v[70:73], v[26:29]
	v_mfma_f32_16x16x32_bf16 v[14:17], v[224:227], v[70:73], v[14:17]
	v_mfma_f32_16x16x32_bf16 v[10:13], v[228:231], v[70:73], v[10:13]
	s_waitcnt vmcnt(14)
	s_waitcnt lgkmcnt(0)
	s_barrier
	s_add_i32 m0, s67, 0x0
	s_nop 0
	global_load_lds_dwordx4 v188, s[80:81]
	s_add_i32 m0, s67, 0x2000
	s_nop 0
	global_load_lds_dwordx4 v189, s[80:81]
	s_add_i32 m0, s67, 0x4000
	s_nop 0
	global_load_lds_dwordx4 v190, s[80:81]
	s_add_i32 m0, s67, 0x6000
	s_nop 0
	global_load_lds_dwordx4 v191, s[80:81]
	s_add_i32 m0, s67, 0x18000
	s_nop 0
	global_load_lds_dwordx4 v205, s[96:97]
	s_add_i32 m0, s67, 0x1a000
	s_nop 0
	global_load_lds_dwordx4 v206, s[96:97]
	s_add_u32 s80, s80, 0x80
	s_addc_u32 s81, s81, 0
	s_add_u32 s96, s96, 0x80
	s_addc_u32 s97, s97, 0
	ds_read_b128 v[82:85], v90 offset:16384
	ds_read_b128 v[86:89], v90 offset:18432
	ds_read_b128 v[208:211], v90 offset:20480
	ds_read_b128 v[212:215], v90 offset:22528
	ds_read_b128 v[66:69], v207 offset:32768
	ds_read_b128 v[70:73], v207 offset:34816
	v_mfma_f32_16x16x32_bf16 v[34:37], v[216:219], v[74:77], v[34:37]
	v_mfma_f32_16x16x32_bf16 v[22:25], v[220:223], v[74:77], v[22:25]
	v_mfma_f32_16x16x32_bf16 v[18:21], v[224:227], v[74:77], v[18:21]
	v_mfma_f32_16x16x32_bf16 v[62:65], v[228:231], v[74:77], v[62:65]
	ds_read_b128 v[74:77], v207 offset:36864
	v_mfma_f32_16x16x32_bf16 v[58:61], v[216:219], v[78:81], v[58:61]
	v_mfma_f32_16x16x32_bf16 v[54:57], v[220:223], v[78:81], v[54:57]
	v_mfma_f32_16x16x32_bf16 v[50:53], v[224:227], v[78:81], v[50:53]
	v_mfma_f32_16x16x32_bf16 v[2:5], v[228:231], v[78:81], v[2:5]
	ds_read_b128 v[78:81], v207 offset:38912
	ds_read_b128 v[216:219], v91 offset:16384
	ds_read_b128 v[220:223], v91 offset:18432
	ds_read_b128 v[224:227], v91 offset:20480
	ds_read_b128 v[228:231], v91 offset:22528
	s_waitcnt lgkmcnt(7)
	v_mfma_f32_16x16x32_bf16 v[6:9], v[82:85], v[66:69], v[6:9]
	v_mfma_f32_16x16x32_bf16 v[30:33], v[86:89], v[66:69], v[30:33]
	v_mfma_f32_16x16x32_bf16 v[38:41], v[208:211], v[66:69], v[38:41]
	v_mfma_f32_16x16x32_bf16 v[42:45], v[212:215], v[66:69], v[42:45]
	ds_read_b128 v[66:69], v119 offset:32768
	s_waitcnt lgkmcnt(7)
	v_mfma_f32_16x16x32_bf16 v[46:49], v[82:85], v[70:73], v[46:49]
	v_mfma_f32_16x16x32_bf16 v[26:29], v[86:89], v[70:73], v[26:29]
	v_mfma_f32_16x16x32_bf16 v[14:17], v[208:211], v[70:73], v[14:17]
	v_mfma_f32_16x16x32_bf16 v[10:13], v[212:215], v[70:73], v[10:13]
	ds_read_b128 v[70:73], v119 offset:34816
	s_waitcnt lgkmcnt(7)
	v_mfma_f32_16x16x32_bf16 v[34:37], v[82:85], v[74:77], v[34:37]
	v_mfma_f32_16x16x32_bf16 v[22:25], v[86:89], v[74:77], v[22:25]
	v_mfma_f32_16x16x32_bf16 v[18:21], v[208:211], v[74:77], v[18:21]
	v_mfma_f32_16x16x32_bf16 v[62:65], v[212:215], v[74:77], v[62:65]
	ds_read_b128 v[74:77], v119 offset:36864
	s_waitcnt lgkmcnt(7)
	v_mfma_f32_16x16x32_bf16 v[58:61], v[82:85], v[78:81], v[58:61]
	v_mfma_f32_16x16x32_bf16 v[54:57], v[86:89], v[78:81], v[54:57]
	v_mfma_f32_16x16x32_bf16 v[50:53], v[208:211], v[78:81], v[50:53]
	v_mfma_f32_16x16x32_bf16 v[2:5], v[212:215], v[78:81], v[2:5]
	ds_read_b128 v[78:81], v119 offset:38912
	s_waitcnt lgkmcnt(3)
	v_mfma_f32_16x16x32_bf16 v[6:9], v[216:219], v[66:69], v[6:9]
	v_mfma_f32_16x16x32_bf16 v[30:33], v[220:223], v[66:69], v[30:33]
	v_mfma_f32_16x16x32_bf16 v[38:41], v[224:227], v[66:69], v[38:41]
	v_mfma_f32_16x16x32_bf16 v[42:45], v[228:231], v[66:69], v[42:45]
	s_waitcnt lgkmcnt(2)
	v_mfma_f32_16x16x32_bf16 v[46:49], v[216:219], v[70:73], v[46:49]
	v_mfma_f32_16x16x32_bf16 v[26:29], v[220:223], v[70:73], v[26:29]
	v_mfma_f32_16x16x32_bf16 v[14:17], v[224:227], v[70:73], v[14:17]
	v_mfma_f32_16x16x32_bf16 v[10:13], v[228:231], v[70:73], v[10:13]
	s_waitcnt vmcnt(6)
	s_waitcnt lgkmcnt(0)
	s_barrier
	s_add_i32 m0, s67, 0x8000
	s_nop 0
	global_load_lds_dwordx4 v188, s[80:81]
	s_add_i32 m0, s67, 0xa000
	s_nop 0
	global_load_lds_dwordx4 v189, s[80:81]
	s_add_i32 m0, s67, 0xc000
	s_nop 0
	global_load_lds_dwordx4 v190, s[80:81]
	s_add_i32 m0, s67, 0xe000
	s_nop 0
	global_load_lds_dwordx4 v191, s[80:81]
	s_add_i32 m0, s67, 0x1c000
	s_nop 0
	global_load_lds_dwordx4 v205, s[96:97]
	s_add_i32 m0, s67, 0x1e000
	s_nop 0
	global_load_lds_dwordx4 v206, s[96:97]
	s_add_u32 s80, s80, 0x80
	s_addc_u32 s81, s81, 0
	s_add_u32 s96, s96, 0x80
	s_addc_u32 s97, s97, 0
	ds_read_b128 v[82:85], v90 offset:33792
	ds_read_b128 v[86:89], v90 offset:35840
	ds_read_b128 v[208:211], v90 offset:37888
	ds_read_b128 v[212:215], v90 offset:39936
	ds_read_b128 v[66:69], v0 offset:0
	ds_read_b128 v[70:73], v0 offset:2048
	v_mfma_f32_16x16x32_bf16 v[34:37], v[216:219], v[74:77], v[34:37]
	v_mfma_f32_16x16x32_bf16 v[22:25], v[220:223], v[74:77], v[22:25]
	v_mfma_f32_16x16x32_bf16 v[18:21], v[224:227], v[74:77], v[18:21]
	v_mfma_f32_16x16x32_bf16 v[62:65], v[228:231], v[74:77], v[62:65]
	ds_read_b128 v[74:77], v0 offset:4096
	v_mfma_f32_16x16x32_bf16 v[58:61], v[216:219], v[78:81], v[58:61]
	v_mfma_f32_16x16x32_bf16 v[54:57], v[220:223], v[78:81], v[54:57]
	v_mfma_f32_16x16x32_bf16 v[50:53], v[224:227], v[78:81], v[50:53]
	v_mfma_f32_16x16x32_bf16 v[2:5], v[228:231], v[78:81], v[2:5]
	ds_read_b128 v[78:81], v0 offset:6144
	ds_read_b128 v[216:219], v91 offset:33792
	ds_read_b128 v[220:223], v91 offset:35840
	ds_read_b128 v[224:227], v91 offset:37888
	ds_read_b128 v[228:231], v91 offset:39936
	s_waitcnt lgkmcnt(7)
	v_mfma_f32_16x16x32_bf16 v[6:9], v[82:85], v[66:69], v[6:9]
	v_mfma_f32_16x16x32_bf16 v[30:33], v[86:89], v[66:69], v[30:33]
	v_mfma_f32_16x16x32_bf16 v[38:41], v[208:211], v[66:69], v[38:41]
	v_mfma_f32_16x16x32_bf16 v[42:45], v[212:215], v[66:69], v[42:45]
	ds_read_b128 v[66:69], v255 offset:0
	s_waitcnt lgkmcnt(7)
	v_mfma_f32_16x16x32_bf16 v[46:49], v[82:85], v[70:73], v[46:49]
	v_mfma_f32_16x16x32_bf16 v[26:29], v[86:89], v[70:73], v[26:29]
	v_mfma_f32_16x16x32_bf16 v[14:17], v[208:211], v[70:73], v[14:17]
	v_mfma_f32_16x16x32_bf16 v[10:13], v[212:215], v[70:73], v[10:13]
	ds_read_b128 v[70:73], v255 offset:2048
	s_waitcnt lgkmcnt(7)
	v_mfma_f32_16x16x32_bf16 v[34:37], v[82:85], v[74:77], v[34:37]
	v_mfma_f32_16x16x32_bf16 v[22:25], v[86:89], v[74:77], v[22:25]
	v_mfma_f32_16x16x32_bf16 v[18:21], v[208:211], v[74:77], v[18:21]
	v_mfma_f32_16x16x32_bf16 v[62:65], v[212:215], v[74:77], v[62:65]
	ds_read_b128 v[74:77], v255 offset:4096
	s_waitcnt lgkmcnt(7)
	v_mfma_f32_16x16x32_bf16 v[58:61], v[82:85], v[78:81], v[58:61]
	v_mfma_f32_16x16x32_bf16 v[54:57], v[86:89], v[78:81], v[54:57]
	v_mfma_f32_16x16x32_bf16 v[50:53], v[208:211], v[78:81], v[50:53]
	v_mfma_f32_16x16x32_bf16 v[2:5], v[212:215], v[78:81], v[2:5]
	ds_read_b128 v[78:81], v255 offset:6144
	s_waitcnt lgkmcnt(3)
	v_mfma_f32_16x16x32_bf16 v[6:9], v[216:219], v[66:69], v[6:9]
	s_waitcnt vmcnt(18)
	v_mfma_f32_16x16x32_bf16 v[30:33], v[220:223], v[66:69], v[30:33]
	v_mfma_f32_16x16x32_bf16 v[38:41], v[224:227], v[66:69], v[38:41]
	v_mfma_f32_16x16x32_bf16 v[42:45], v[228:231], v[66:69], v[42:45]
	v_cvt_f32_ubyte0_e32 v248, v232
	v_cvt_f32_ubyte1_e32 v249, v232
	v_cvt_f32_ubyte2_e32 v250, v232
	v_cvt_f32_ubyte3_e32 v251, v232
	v_mul_f32_e32 v248, s34, v248
	v_mul_f32_e32 v249, s34, v249
	v_mul_f32_e32 v250, s34, v250
	v_mul_f32_e32 v251, s34, v251
	v_fma_f32 v184, v6, v248, v184
	v_fma_f32 v185, v7, v249, v185
	v_fma_f32 v186, v8, v250, v186
	v_fma_f32 v187, v9, v251, v187
	s_waitcnt lgkmcnt(2)
	v_mfma_f32_16x16x32_bf16 v[46:49], v[216:219], v[70:73], v[46:49]
	v_cvt_f32_ubyte0_e32 v248, v233
	v_cvt_f32_ubyte1_e32 v249, v233
	v_cvt_f32_ubyte2_e32 v250, v233
	v_cvt_f32_ubyte3_e32 v251, v233
	v_mul_f32_e32 v248, s34, v248
	v_mul_f32_e32 v249, s34, v249
	v_mul_f32_e32 v250, s34, v250
	v_mul_f32_e32 v251, s34, v251
	v_fma_f32 v180, v30, v248, v180
	v_fma_f32 v181, v31, v249, v181
	v_fma_f32 v182, v32, v250, v182
	v_fma_f32 v183, v33, v251, v183
	v_mfma_f32_16x16x32_bf16 v[26:29], v[220:223], v[70:73], v[26:29]
	v_cvt_f32_ubyte0_e32 v248, v234
	v_cvt_f32_ubyte1_e32 v249, v234
	v_cvt_f32_ubyte2_e32 v250, v234
	v_cvt_f32_ubyte3_e32 v251, v234
	v_mul_f32_e32 v248, s34, v248
	v_mul_f32_e32 v249, s34, v249
	v_mul_f32_e32 v250, s34, v250
	v_mul_f32_e32 v251, s34, v251
	v_fma_f32 v176, v38, v248, v176
	v_fma_f32 v177, v39, v249, v177
	v_fma_f32 v178, v40, v250, v178
	v_fma_f32 v179, v41, v251, v179
	v_mfma_f32_16x16x32_bf16 v[14:17], v[224:227], v[70:73], v[14:17]
	v_cvt_f32_ubyte0_e32 v248, v235
	v_cvt_f32_ubyte1_e32 v249, v235
	v_cvt_f32_ubyte2_e32 v250, v235
	v_cvt_f32_ubyte3_e32 v251, v235
	v_mul_f32_e32 v248, s34, v248
	v_mul_f32_e32 v249, s34, v249
	v_mul_f32_e32 v250, s34, v250
	v_mul_f32_e32 v251, s34, v251
	v_fma_f32 v172, v42, v248, v172
	v_fma_f32 v173, v43, v249, v173
	v_fma_f32 v174, v44, v250, v174
	v_fma_f32 v175, v45, v251, v175
	v_mfma_f32_16x16x32_bf16 v[10:13], v[228:231], v[70:73], v[10:13]
	v_cvt_f32_ubyte0_e32 v248, v236
	v_cvt_f32_ubyte1_e32 v249, v236
	v_cvt_f32_ubyte2_e32 v250, v236
	v_cvt_f32_ubyte3_e32 v251, v236
	v_mul_f32_e32 v248, s34, v248
	v_mul_f32_e32 v249, s34, v249
	v_mul_f32_e32 v250, s34, v250
	v_mul_f32_e32 v251, s34, v251
	v_fma_f32 v168, v46, v248, v168
	v_fma_f32 v169, v47, v249, v169
	v_fma_f32 v170, v48, v250, v170
	v_fma_f32 v171, v49, v251, v171
	s_waitcnt vmcnt(6)
	s_waitcnt lgkmcnt(0)
	s_barrier
	s_add_i32 m0, s67, 0x10000
	s_nop 0
	global_load_lds_dwordx4 v188, s[80:81]
	s_add_i32 m0, s67, 0x12000
	s_nop 0
	global_load_lds_dwordx4 v189, s[80:81]
	s_add_i32 m0, s67, 0x14000
	s_nop 0
	global_load_lds_dwordx4 v190, s[80:81]
	s_add_i32 m0, s67, 0x16000
	s_nop 0
	global_load_lds_dwordx4 v191, s[80:81]
	s_add_i32 m0, s67, 0x20400
	s_nop 0
	global_load_lds_dwordx4 v205, s[96:97]
	s_add_i32 m0, s67, 0x22400
	s_nop 0
	global_load_lds_dwordx4 v206, s[96:97]
	s_add_u32 s80, s80, 0x80
	s_addc_u32 s81, s81, 0
	s_add_u32 s96, s96, 0x80
	s_addc_u32 s97, s97, 0
	ds_read_b128 v[82:85], v90 offset:0
	ds_read_b128 v[86:89], v90 offset:2048
	ds_read_b128 v[208:211], v90 offset:4096
	ds_read_b128 v[212:215], v90 offset:6144
	ds_read_b128 v[66:69], v207 offset:0
	ds_read_b128 v[70:73], v207 offset:2048
	v_mfma_f32_16x16x32_bf16 v[34:37], v[216:219], v[74:77], v[34:37]
	v_cvt_f32_ubyte0_e32 v248, v237
	v_cvt_f32_ubyte1_e32 v249, v237
	v_cvt_f32_ubyte2_e32 v250, v237
	v_cvt_f32_ubyte3_e32 v251, v237
	v_mul_f32_e32 v248, s34, v248
	v_mul_f32_e32 v249, s34, v249
	v_mul_f32_e32 v250, s34, v250
	v_mul_f32_e32 v251, s34, v251
	v_fma_f32 v164, v26, v248, v164
	v_fma_f32 v165, v27, v249, v165
	v_fma_f32 v166, v28, v250, v166
	v_fma_f32 v167, v29, v251, v167
	v_mfma_f32_16x16x32_bf16 v[22:25], v[220:223], v[74:77], v[22:25]
	v_cvt_f32_ubyte0_e32 v248, v238
	v_cvt_f32_ubyte1_e32 v249, v238
	v_cvt_f32_ubyte2_e32 v250, v238
	v_cvt_f32_ubyte3_e32 v251, v238
	v_mul_f32_e32 v248, s34, v248
	v_mul_f32_e32 v249, s34, v249
	v_mul_f32_e32 v250, s34, v250
	v_mul_f32_e32 v251, s34, v251
	v_fma_f32 v160, v14, v248, v160
	v_fma_f32 v161, v15, v249, v161
	v_fma_f32 v162, v16, v250, v162
	v_fma_f32 v163, v17, v251, v163
	v_mfma_f32_16x16x32_bf16 v[18:21], v[224:227], v[74:77], v[18:21]
	v_cvt_f32_ubyte0_e32 v248, v239
	v_cvt_f32_ubyte1_e32 v249, v239
	v_cvt_f32_ubyte2_e32 v250, v239
	v_cvt_f32_ubyte3_e32 v251, v239
	v_mul_f32_e32 v248, s34, v248
	v_mul_f32_e32 v249, s34, v249
	v_mul_f32_e32 v250, s34, v250
	v_mul_f32_e32 v251, s34, v251
	v_fma_f32 v156, v10, v248, v156
	v_fma_f32 v157, v11, v249, v157
	v_fma_f32 v158, v12, v250, v158
	v_fma_f32 v159, v13, v251, v159
	v_mfma_f32_16x16x32_bf16 v[62:65], v[228:231], v[74:77], v[62:65]
	v_cvt_f32_ubyte0_e32 v248, v240
	v_cvt_f32_ubyte1_e32 v249, v240
	v_cvt_f32_ubyte2_e32 v250, v240
	v_cvt_f32_ubyte3_e32 v251, v240
	v_mul_f32_e32 v248, s34, v248
	v_mul_f32_e32 v249, s34, v249
	v_mul_f32_e32 v250, s34, v250
	v_mul_f32_e32 v251, s34, v251
	v_fma_f32 v136, v34, v248, v136
	v_fma_f32 v137, v35, v249, v137
	v_fma_f32 v150, v36, v250, v150
	v_fma_f32 v151, v37, v251, v151
	ds_read_b128 v[74:77], v207 offset:4096
	v_mfma_f32_16x16x32_bf16 v[58:61], v[216:219], v[78:81], v[58:61]
	v_cvt_f32_ubyte0_e32 v248, v241
	v_cvt_f32_ubyte1_e32 v249, v241
	v_cvt_f32_ubyte2_e32 v250, v241
	v_cvt_f32_ubyte3_e32 v251, v241
	v_mul_f32_e32 v248, s34, v248
	v_mul_f32_e32 v249, s34, v249
	v_mul_f32_e32 v250, s34, v250
	v_mul_f32_e32 v251, s34, v251
	v_fma_f32 v130, v22, v248, v130
	v_fma_f32 v131, v23, v249, v131
	v_fma_f32 v134, v24, v250, v134
	v_fma_f32 v135, v25, v251, v135
	v_mfma_f32_16x16x32_bf16 v[54:57], v[220:223], v[78:81], v[54:57]
	v_cvt_f32_ubyte0_e32 v248, v242
	v_cvt_f32_ubyte1_e32 v249, v242
	v_cvt_f32_ubyte2_e32 v250, v242
	v_cvt_f32_ubyte3_e32 v251, v242
	v_mul_f32_e32 v248, s34, v248
	v_mul_f32_e32 v249, s34, v249
	v_mul_f32_e32 v250, s34, v250
	v_mul_f32_e32 v251, s34, v251
	v_fma_f32 v124, v18, v248, v124
	v_fma_f32 v125, v19, v249, v125
	v_fma_f32 v126, v20, v250, v126
	v_fma_f32 v127, v21, v251, v127
	v_mfma_f32_16x16x32_bf16 v[50:53], v[224:227], v[78:81], v[50:53]
	v_cvt_f32_ubyte0_e32 v248, v243
	v_cvt_f32_ubyte1_e32 v249, v243
	v_cvt_f32_ubyte2_e32 v250, v243
	v_cvt_f32_ubyte3_e32 v251, v243
	v_mul_f32_e32 v248, s34, v248
	v_mul_f32_e32 v249, s34, v249
	v_mul_f32_e32 v250, s34, v250
	v_mul_f32_e32 v251, s34, v251
	v_fma_f32 v120, v62, v248, v120
	v_fma_f32 v121, v63, v249, v121
	v_fma_f32 v122, v64, v250, v122
	v_fma_f32 v123, v65, v251, v123
	v_mfma_f32_16x16x32_bf16 v[2:5], v[228:231], v[78:81], v[2:5]
	v_cvt_f32_ubyte0_e32 v248, v244
	v_cvt_f32_ubyte1_e32 v249, v244
	v_cvt_f32_ubyte2_e32 v250, v244
	v_cvt_f32_ubyte3_e32 v251, v244
	v_mul_f32_e32 v248, s34, v248
	v_mul_f32_e32 v249, s34, v249
	v_mul_f32_e32 v250, s34, v250
	v_mul_f32_e32 v251, s34, v251
	v_fma_f32 v114, v58, v248, v114
	v_fma_f32 v115, v59, v249, v115
	v_fma_f32 v116, v60, v250, v116
	v_fma_f32 v117, v61, v251, v117
	ds_read_b128 v[78:81], v207 offset:6144
	s_nop 7
	s_nop 3
	v_cvt_f32_ubyte0_e32 v248, v245
	v_cvt_f32_ubyte1_e32 v249, v245
	v_cvt_f32_ubyte2_e32 v250, v245
	v_cvt_f32_ubyte3_e32 v251, v245
	v_mul_f32_e32 v248, s34, v248
	v_mul_f32_e32 v249, s34, v249
	v_mul_f32_e32 v250, s34, v250
	v_mul_f32_e32 v251, s34, v251
	v_fma_f32 v106, v54, v248, v106
	v_fma_f32 v107, v55, v249, v107
	v_fma_f32 v108, v56, v250, v108
	v_fma_f32 v109, v57, v251, v109
	v_cvt_f32_ubyte0_e32 v248, v246
	v_cvt_f32_ubyte1_e32 v249, v246
	v_cvt_f32_ubyte2_e32 v250, v246
	v_cvt_f32_ubyte3_e32 v251, v246
	v_mul_f32_e32 v248, s34, v248
	v_mul_f32_e32 v249, s34, v249
	v_mul_f32_e32 v250, s34, v250
	v_mul_f32_e32 v251, s34, v251
	v_fma_f32 v100, v50, v248, v100
	v_fma_f32 v101, v51, v249, v101
	v_fma_f32 v102, v52, v250, v102
	v_fma_f32 v103, v53, v251, v103
	v_cvt_f32_ubyte0_e32 v248, v247
	v_cvt_f32_ubyte1_e32 v249, v247
	v_cvt_f32_ubyte2_e32 v250, v247
	v_cvt_f32_ubyte3_e32 v251, v247
	v_mul_f32_e32 v248, s34, v248
	v_mul_f32_e32 v249, s34, v249
	v_mul_f32_e32 v250, s34, v250
	v_mul_f32_e32 v251, s34, v251
	v_fma_f32 v96, v2, v248, v96
	v_fma_f32 v97, v3, v249, v97
	v_fma_f32 v98, v4, v250, v98
	v_fma_f32 v99, v5, v251, v99
	s_cmp_eq_u32 s43, 0
	s_cselect_b32 s32, 0x7c00000, 0
	s_add_u32 s98, s86, s32
	s_addc_u32 s99, s87, 0
	s_add_u32 s98, s98, 0xc00
	s_addc_u32 s99, s99, 0
	global_load_dword v92, v93, s[98:99]
	ds_read_b128 v[216:219], v91 offset:0
	ds_read_b128 v[220:223], v91 offset:2048
	ds_read_b128 v[224:227], v91 offset:4096
	ds_read_b128 v[228:231], v91 offset:6144
	s_waitcnt lgkmcnt(7)
	v_mfma_f32_16x16x32_bf16 v[6:9], v[82:85], v[66:69], 0
	v_mfma_f32_16x16x32_bf16 v[30:33], v[86:89], v[66:69], 0
	v_mfma_f32_16x16x32_bf16 v[38:41], v[208:211], v[66:69], 0
	v_mfma_f32_16x16x32_bf16 v[42:45], v[212:215], v[66:69], 0
	ds_read_b128 v[66:69], v119 offset:0
	s_waitcnt lgkmcnt(7)
	v_mfma_f32_16x16x32_bf16 v[46:49], v[82:85], v[70:73], 0
	v_mfma_f32_16x16x32_bf16 v[26:29], v[86:89], v[70:73], 0
	v_mfma_f32_16x16x32_bf16 v[14:17], v[208:211], v[70:73], 0
	v_mfma_f32_16x16x32_bf16 v[10:13], v[212:215], v[70:73], 0
	ds_read_b128 v[70:73], v119 offset:2048
	s_waitcnt lgkmcnt(7)
	v_mfma_f32_16x16x32_bf16 v[34:37], v[82:85], v[74:77], 0
	v_mfma_f32_16x16x32_bf16 v[22:25], v[86:89], v[74:77], 0
	v_mfma_f32_16x16x32_bf16 v[18:21], v[208:211], v[74:77], 0
	v_mfma_f32_16x16x32_bf16 v[62:65], v[212:215], v[74:77], 0
	ds_read_b128 v[74:77], v119 offset:4096
	s_waitcnt lgkmcnt(7)
	v_mfma_f32_16x16x32_bf16 v[58:61], v[82:85], v[78:81], 0
	v_mfma_f32_16x16x32_bf16 v[54:57], v[86:89], v[78:81], 0
	v_mfma_f32_16x16x32_bf16 v[50:53], v[208:211], v[78:81], 0
	v_mfma_f32_16x16x32_bf16 v[2:5], v[212:215], v[78:81], 0
	ds_read_b128 v[78:81], v119 offset:6144
	s_waitcnt lgkmcnt(3)
	v_mfma_f32_16x16x32_bf16 v[6:9], v[216:219], v[66:69], v[6:9]
	v_mfma_f32_16x16x32_bf16 v[30:33], v[220:223], v[66:69], v[30:33]
	v_mfma_f32_16x16x32_bf16 v[38:41], v[224:227], v[66:69], v[38:41]
	v_mfma_f32_16x16x32_bf16 v[42:45], v[228:231], v[66:69], v[42:45]
	s_waitcnt lgkmcnt(2)
	v_mfma_f32_16x16x32_bf16 v[46:49], v[216:219], v[70:73], v[46:49]
	v_mfma_f32_16x16x32_bf16 v[26:29], v[220:223], v[70:73], v[26:29]
	v_mfma_f32_16x16x32_bf16 v[14:17], v[224:227], v[70:73], v[14:17]
	v_mfma_f32_16x16x32_bf16 v[10:13], v[228:231], v[70:73], v[10:13]
	s_waitcnt vmcnt(7)
	s_waitcnt lgkmcnt(0)
	s_barrier
	s_add_i32 m0, s67, 0x0
	s_nop 0
	global_load_lds_dwordx4 v188, s[80:81]
	s_add_i32 m0, s67, 0x2000
	s_nop 0
	global_load_lds_dwordx4 v189, s[80:81]
	s_add_i32 m0, s67, 0x4000
	s_nop 0
	global_load_lds_dwordx4 v190, s[80:81]
	s_add_i32 m0, s67, 0x6000
	s_nop 0
	global_load_lds_dwordx4 v191, s[80:81]
	s_add_i32 m0, s67, 0x18000
	s_nop 0
	global_load_lds_dwordx4 v205, s[96:97]
	s_add_i32 m0, s67, 0x1a000
	s_nop 0
	global_load_lds_dwordx4 v206, s[96:97]
	s_add_u32 s80, s80, 0x80
	s_addc_u32 s81, s81, 0
	s_add_u32 s96, s96, 0x80
	s_addc_u32 s97, s97, 0
	ds_read_b128 v[82:85], v90 offset:16384
	ds_read_b128 v[86:89], v90 offset:18432
	ds_read_b128 v[208:211], v90 offset:20480
	ds_read_b128 v[212:215], v90 offset:22528
	ds_read_b128 v[66:69], v207 offset:32768
	ds_read_b128 v[70:73], v207 offset:34816
	v_mfma_f32_16x16x32_bf16 v[34:37], v[216:219], v[74:77], v[34:37]
	v_mfma_f32_16x16x32_bf16 v[22:25], v[220:223], v[74:77], v[22:25]
	v_mfma_f32_16x16x32_bf16 v[18:21], v[224:227], v[74:77], v[18:21]
	v_mfma_f32_16x16x32_bf16 v[62:65], v[228:231], v[74:77], v[62:65]
	ds_read_b128 v[74:77], v207 offset:36864
	v_mfma_f32_16x16x32_bf16 v[58:61], v[216:219], v[78:81], v[58:61]
	v_mfma_f32_16x16x32_bf16 v[54:57], v[220:223], v[78:81], v[54:57]
	v_mfma_f32_16x16x32_bf16 v[50:53], v[224:227], v[78:81], v[50:53]
	v_mfma_f32_16x16x32_bf16 v[2:5], v[228:231], v[78:81], v[2:5]
	ds_read_b128 v[78:81], v207 offset:38912
	ds_read_b128 v[216:219], v91 offset:16384
	ds_read_b128 v[220:223], v91 offset:18432
	ds_read_b128 v[224:227], v91 offset:20480
	ds_read_b128 v[228:231], v91 offset:22528
	s_waitcnt lgkmcnt(7)
	v_mfma_f32_16x16x32_bf16 v[6:9], v[82:85], v[66:69], v[6:9]
	v_mfma_f32_16x16x32_bf16 v[30:33], v[86:89], v[66:69], v[30:33]
	v_mfma_f32_16x16x32_bf16 v[38:41], v[208:211], v[66:69], v[38:41]
	v_mfma_f32_16x16x32_bf16 v[42:45], v[212:215], v[66:69], v[42:45]
	ds_read_b128 v[66:69], v119 offset:32768
	s_waitcnt lgkmcnt(7)
	v_mfma_f32_16x16x32_bf16 v[46:49], v[82:85], v[70:73], v[46:49]
	v_mfma_f32_16x16x32_bf16 v[26:29], v[86:89], v[70:73], v[26:29]
	v_mfma_f32_16x16x32_bf16 v[14:17], v[208:211], v[70:73], v[14:17]
	v_mfma_f32_16x16x32_bf16 v[10:13], v[212:215], v[70:73], v[10:13]
	ds_read_b128 v[70:73], v119 offset:34816
	s_waitcnt lgkmcnt(7)
	v_mfma_f32_16x16x32_bf16 v[34:37], v[82:85], v[74:77], v[34:37]
	v_mfma_f32_16x16x32_bf16 v[22:25], v[86:89], v[74:77], v[22:25]
	v_mfma_f32_16x16x32_bf16 v[18:21], v[208:211], v[74:77], v[18:21]
	v_mfma_f32_16x16x32_bf16 v[62:65], v[212:215], v[74:77], v[62:65]
	ds_read_b128 v[74:77], v119 offset:36864
	s_waitcnt lgkmcnt(7)
	v_mfma_f32_16x16x32_bf16 v[58:61], v[82:85], v[78:81], v[58:61]
	v_mfma_f32_16x16x32_bf16 v[54:57], v[86:89], v[78:81], v[54:57]
	v_mfma_f32_16x16x32_bf16 v[50:53], v[208:211], v[78:81], v[50:53]
	v_mfma_f32_16x16x32_bf16 v[2:5], v[212:215], v[78:81], v[2:5]
	ds_read_b128 v[78:81], v119 offset:38912
	s_waitcnt lgkmcnt(3)
	v_mfma_f32_16x16x32_bf16 v[6:9], v[216:219], v[66:69], v[6:9]
	v_mfma_f32_16x16x32_bf16 v[30:33], v[220:223], v[66:69], v[30:33]
	v_mfma_f32_16x16x32_bf16 v[38:41], v[224:227], v[66:69], v[38:41]
	v_mfma_f32_16x16x32_bf16 v[42:45], v[228:231], v[66:69], v[42:45]
	s_waitcnt lgkmcnt(2)
	v_mfma_f32_16x16x32_bf16 v[46:49], v[216:219], v[70:73], v[46:49]
	v_mfma_f32_16x16x32_bf16 v[26:29], v[220:223], v[70:73], v[26:29]
	v_mfma_f32_16x16x32_bf16 v[14:17], v[224:227], v[70:73], v[14:17]
	v_mfma_f32_16x16x32_bf16 v[10:13], v[228:231], v[70:73], v[10:13]
	s_waitcnt vmcnt(7)
	s_waitcnt lgkmcnt(0)
	s_barrier
	s_add_i32 m0, s67, 0x8000
	s_nop 0
	global_load_lds_dwordx4 v188, s[80:81]
	s_add_i32 m0, s67, 0xa000
	s_nop 0
	global_load_lds_dwordx4 v189, s[80:81]
	s_add_i32 m0, s67, 0xc000
	s_nop 0
	global_load_lds_dwordx4 v190, s[80:81]
	s_add_i32 m0, s67, 0xe000
	s_nop 0
	global_load_lds_dwordx4 v191, s[80:81]
	s_add_i32 m0, s67, 0x1c000
	s_nop 0
	global_load_lds_dwordx4 v205, s[96:97]
	s_add_i32 m0, s67, 0x1e000
	s_nop 0
	global_load_lds_dwordx4 v206, s[96:97]
	s_add_u32 s80, s80, 0x80
	s_addc_u32 s81, s81, 0
	s_add_u32 s96, s96, 0x80
	s_addc_u32 s97, s97, 0
	ds_read_b128 v[82:85], v90 offset:33792
	ds_read_b128 v[86:89], v90 offset:35840
	ds_read_b128 v[208:211], v90 offset:37888
	ds_read_b128 v[212:215], v90 offset:39936
	ds_read_b128 v[66:69], v0 offset:0
	ds_read_b128 v[70:73], v0 offset:2048
	v_mfma_f32_16x16x32_bf16 v[34:37], v[216:219], v[74:77], v[34:37]
	v_mfma_f32_16x16x32_bf16 v[22:25], v[220:223], v[74:77], v[22:25]
	v_mfma_f32_16x16x32_bf16 v[18:21], v[224:227], v[74:77], v[18:21]
	v_mfma_f32_16x16x32_bf16 v[62:65], v[228:231], v[74:77], v[62:65]
	ds_read_b128 v[74:77], v0 offset:4096
	v_mfma_f32_16x16x32_bf16 v[58:61], v[216:219], v[78:81], v[58:61]
	v_mfma_f32_16x16x32_bf16 v[54:57], v[220:223], v[78:81], v[54:57]
	v_mfma_f32_16x16x32_bf16 v[50:53], v[224:227], v[78:81], v[50:53]
	v_mfma_f32_16x16x32_bf16 v[2:5], v[228:231], v[78:81], v[2:5]
	ds_read_b128 v[78:81], v0 offset:6144
	ds_read_b128 v[216:219], v91 offset:33792
	ds_read_b128 v[220:223], v91 offset:35840
	ds_read_b128 v[224:227], v91 offset:37888
	ds_read_b128 v[228:231], v91 offset:39936
	s_waitcnt lgkmcnt(7)
	v_mfma_f32_16x16x32_bf16 v[6:9], v[82:85], v[66:69], v[6:9]
	v_mfma_f32_16x16x32_bf16 v[30:33], v[86:89], v[66:69], v[30:33]
	v_mfma_f32_16x16x32_bf16 v[38:41], v[208:211], v[66:69], v[38:41]
	v_mfma_f32_16x16x32_bf16 v[42:45], v[212:215], v[66:69], v[42:45]
	ds_read_b128 v[66:69], v255 offset:0
	s_waitcnt lgkmcnt(7)
	v_mfma_f32_16x16x32_bf16 v[46:49], v[82:85], v[70:73], v[46:49]
	v_mfma_f32_16x16x32_bf16 v[26:29], v[86:89], v[70:73], v[26:29]
	v_mfma_f32_16x16x32_bf16 v[14:17], v[208:211], v[70:73], v[14:17]
	v_mfma_f32_16x16x32_bf16 v[10:13], v[212:215], v[70:73], v[10:13]
	ds_read_b128 v[70:73], v255 offset:2048
	s_waitcnt lgkmcnt(7)
	v_mfma_f32_16x16x32_bf16 v[34:37], v[82:85], v[74:77], v[34:37]
	v_mfma_f32_16x16x32_bf16 v[22:25], v[86:89], v[74:77], v[22:25]
	v_mfma_f32_16x16x32_bf16 v[18:21], v[208:211], v[74:77], v[18:21]
	v_mfma_f32_16x16x32_bf16 v[62:65], v[212:215], v[74:77], v[62:65]
	ds_read_b128 v[74:77], v255 offset:4096
	s_waitcnt lgkmcnt(7)
	v_mfma_f32_16x16x32_bf16 v[58:61], v[82:85], v[78:81], v[58:61]
	v_mfma_f32_16x16x32_bf16 v[54:57], v[86:89], v[78:81], v[54:57]
	v_mfma_f32_16x16x32_bf16 v[50:53], v[208:211], v[78:81], v[50:53]
	v_mfma_f32_16x16x32_bf16 v[2:5], v[212:215], v[78:81], v[2:5]
	ds_read_b128 v[78:81], v255 offset:6144
	s_waitcnt lgkmcnt(3)
	v_mfma_f32_16x16x32_bf16 v[6:9], v[216:219], v[66:69], v[6:9]
	v_mfma_f32_16x16x32_bf16 v[30:33], v[220:223], v[66:69], v[30:33]
	v_mfma_f32_16x16x32_bf16 v[38:41], v[224:227], v[66:69], v[38:41]
	v_mfma_f32_16x16x32_bf16 v[42:45], v[228:231], v[66:69], v[42:45]
	s_waitcnt lgkmcnt(2)
	v_mfma_f32_16x16x32_bf16 v[46:49], v[216:219], v[70:73], v[46:49]
	v_mfma_f32_16x16x32_bf16 v[26:29], v[220:223], v[70:73], v[26:29]
	v_mfma_f32_16x16x32_bf16 v[14:17], v[224:227], v[70:73], v[14:17]
	v_mfma_f32_16x16x32_bf16 v[10:13], v[228:231], v[70:73], v[10:13]
	s_waitcnt vmcnt(6)
	s_waitcnt lgkmcnt(0)
	s_barrier
	s_add_i32 m0, s67, 0x10000
	s_nop 0
	global_load_lds_dwordx4 v188, s[80:81]
	s_add_i32 m0, s67, 0x12000
	s_nop 0
	global_load_lds_dwordx4 v189, s[80:81]
	s_add_i32 m0, s67, 0x14000
	s_nop 0
	global_load_lds_dwordx4 v190, s[80:81]
	s_add_i32 m0, s67, 0x16000
	s_nop 0
	global_load_lds_dwordx4 v191, s[80:81]
	s_add_i32 m0, s67, 0x20400
	s_nop 0
	global_load_lds_dwordx4 v205, s[96:97]
	s_add_i32 m0, s67, 0x22400
	s_nop 0
	global_load_lds_dwordx4 v206, s[96:97]
	s_add_u32 s80, s80, 0x80
	s_addc_u32 s81, s81, 0
	s_add_u32 s96, s96, 0x80
	s_addc_u32 s97, s97, 0
	ds_read_b128 v[82:85], v90 offset:0
	ds_read_b128 v[86:89], v90 offset:2048
	ds_read_b128 v[208:211], v90 offset:4096
	ds_read_b128 v[212:215], v90 offset:6144
	ds_read_b128 v[66:69], v207 offset:0
	ds_read_b128 v[70:73], v207 offset:2048
	v_mfma_f32_16x16x32_bf16 v[34:37], v[216:219], v[74:77], v[34:37]
	v_mfma_f32_16x16x32_bf16 v[22:25], v[220:223], v[74:77], v[22:25]
	v_mfma_f32_16x16x32_bf16 v[18:21], v[224:227], v[74:77], v[18:21]
	v_mfma_f32_16x16x32_bf16 v[62:65], v[228:231], v[74:77], v[62:65]
	ds_read_b128 v[74:77], v207 offset:4096
	v_mfma_f32_16x16x32_bf16 v[58:61], v[216:219], v[78:81], v[58:61]
	v_mfma_f32_16x16x32_bf16 v[54:57], v[220:223], v[78:81], v[54:57]
	v_mfma_f32_16x16x32_bf16 v[50:53], v[224:227], v[78:81], v[50:53]
	v_mfma_f32_16x16x32_bf16 v[2:5], v[228:231], v[78:81], v[2:5]
	ds_read_b128 v[78:81], v207 offset:6144
	ds_read_b128 v[216:219], v91 offset:0
	ds_read_b128 v[220:223], v91 offset:2048
	ds_read_b128 v[224:227], v91 offset:4096
	ds_read_b128 v[228:231], v91 offset:6144
	s_waitcnt lgkmcnt(7)
	v_mfma_f32_16x16x32_bf16 v[6:9], v[82:85], v[66:69], v[6:9]
	v_mfma_f32_16x16x32_bf16 v[30:33], v[86:89], v[66:69], v[30:33]
	v_mfma_f32_16x16x32_bf16 v[38:41], v[208:211], v[66:69], v[38:41]
	v_mfma_f32_16x16x32_bf16 v[42:45], v[212:215], v[66:69], v[42:45]
	ds_read_b128 v[66:69], v119 offset:0
	s_waitcnt lgkmcnt(7)
	v_mfma_f32_16x16x32_bf16 v[46:49], v[82:85], v[70:73], v[46:49]
	v_mfma_f32_16x16x32_bf16 v[26:29], v[86:89], v[70:73], v[26:29]
	v_mfma_f32_16x16x32_bf16 v[14:17], v[208:211], v[70:73], v[14:17]
	v_mfma_f32_16x16x32_bf16 v[10:13], v[212:215], v[70:73], v[10:13]
	ds_read_b128 v[70:73], v119 offset:2048
	s_waitcnt lgkmcnt(7)
	v_mfma_f32_16x16x32_bf16 v[34:37], v[82:85], v[74:77], v[34:37]
	v_mfma_f32_16x16x32_bf16 v[22:25], v[86:89], v[74:77], v[22:25]
	v_mfma_f32_16x16x32_bf16 v[18:21], v[208:211], v[74:77], v[18:21]
	v_mfma_f32_16x16x32_bf16 v[62:65], v[212:215], v[74:77], v[62:65]
	ds_read_b128 v[74:77], v119 offset:4096
	s_waitcnt lgkmcnt(7)
	v_mfma_f32_16x16x32_bf16 v[58:61], v[82:85], v[78:81], v[58:61]
	v_mfma_f32_16x16x32_bf16 v[54:57], v[86:89], v[78:81], v[54:57]
	v_mfma_f32_16x16x32_bf16 v[50:53], v[208:211], v[78:81], v[50:53]
	v_mfma_f32_16x16x32_bf16 v[2:5], v[212:215], v[78:81], v[2:5]
	ds_read_b128 v[78:81], v119 offset:6144
	s_waitcnt lgkmcnt(3)
	v_mfma_f32_16x16x32_bf16 v[6:9], v[216:219], v[66:69], v[6:9]
	v_mfma_f32_16x16x32_bf16 v[30:33], v[220:223], v[66:69], v[30:33]
	v_mfma_f32_16x16x32_bf16 v[38:41], v[224:227], v[66:69], v[38:41]
	v_mfma_f32_16x16x32_bf16 v[42:45], v[228:231], v[66:69], v[42:45]
	s_waitcnt lgkmcnt(2)
	v_mfma_f32_16x16x32_bf16 v[46:49], v[216:219], v[70:73], v[46:49]
	v_mfma_f32_16x16x32_bf16 v[26:29], v[220:223], v[70:73], v[26:29]
	v_mfma_f32_16x16x32_bf16 v[14:17], v[224:227], v[70:73], v[14:17]
	v_mfma_f32_16x16x32_bf16 v[10:13], v[228:231], v[70:73], v[10:13]
	s_waitcnt vmcnt(6)
	s_waitcnt lgkmcnt(0)
	s_barrier
	s_add_i32 m0, s67, 0x0
	s_nop 0
	global_load_lds_dwordx4 v188, s[80:81]
	s_add_i32 m0, s67, 0x2000
	s_nop 0
	global_load_lds_dwordx4 v189, s[80:81]
	s_add_i32 m0, s67, 0x4000
	s_nop 0
	global_load_lds_dwordx4 v190, s[80:81]
	s_add_i32 m0, s67, 0x6000
	s_nop 0
	global_load_lds_dwordx4 v191, s[80:81]
	s_add_i32 m0, s67, 0x18000
	s_nop 0
	global_load_lds_dwordx4 v205, s[96:97]
	s_add_i32 m0, s67, 0x1a000
	s_nop 0
	global_load_lds_dwordx4 v206, s[96:97]
	s_add_u32 s80, s80, 0x80
	s_addc_u32 s81, s81, 0
	s_add_u32 s96, s96, 0x80
	s_addc_u32 s97, s97, 0
	s_movk_i32 s10, 0xc00
	s_mov_b32 s11, 0
	v_lshl_add_u64 v[248:249], v[128:129], 0, s[10:11]
	global_load_dwordx2 v[232:233], v[248:249], off
	global_load_dwordx2 v[234:235], v[248:249], off offset:32
	v_lshl_add_u64 v[248:249], v[132:133], 0, s[10:11]
	global_load_dwordx2 v[236:237], v[248:249], off
	global_load_dwordx2 v[238:239], v[248:249], off offset:32
	v_lshl_add_u64 v[248:249], v[152:153], 0, s[10:11]
	global_load_dwordx2 v[240:241], v[248:249], off
	global_load_dwordx2 v[242:243], v[248:249], off offset:32
	v_lshl_add_u64 v[248:249], v[154:155], 0, s[10:11]
	global_load_dwordx2 v[244:245], v[248:249], off
	global_load_dwordx2 v[246:247], v[248:249], off offset:32
	ds_read_b128 v[82:85], v90 offset:16384
	ds_read_b128 v[86:89], v90 offset:18432
	ds_read_b128 v[208:211], v90 offset:20480
	ds_read_b128 v[212:215], v90 offset:22528
	ds_read_b128 v[66:69], v207 offset:32768
	ds_read_b128 v[70:73], v207 offset:34816
	v_mfma_f32_16x16x32_bf16 v[34:37], v[216:219], v[74:77], v[34:37]
	v_mfma_f32_16x16x32_bf16 v[22:25], v[220:223], v[74:77], v[22:25]
	v_mfma_f32_16x16x32_bf16 v[18:21], v[224:227], v[74:77], v[18:21]
	v_mfma_f32_16x16x32_bf16 v[62:65], v[228:231], v[74:77], v[62:65]
	ds_read_b128 v[74:77], v207 offset:36864
	v_mfma_f32_16x16x32_bf16 v[58:61], v[216:219], v[78:81], v[58:61]
	v_mfma_f32_16x16x32_bf16 v[54:57], v[220:223], v[78:81], v[54:57]
	v_mfma_f32_16x16x32_bf16 v[50:53], v[224:227], v[78:81], v[50:53]
	v_mfma_f32_16x16x32_bf16 v[2:5], v[228:231], v[78:81], v[2:5]
	ds_read_b128 v[78:81], v207 offset:38912
	ds_read_b128 v[216:219], v91 offset:16384
	ds_read_b128 v[220:223], v91 offset:18432
	ds_read_b128 v[224:227], v91 offset:20480
	ds_read_b128 v[228:231], v91 offset:22528
	s_waitcnt lgkmcnt(7)
	v_mfma_f32_16x16x32_bf16 v[6:9], v[82:85], v[66:69], v[6:9]
	v_mfma_f32_16x16x32_bf16 v[30:33], v[86:89], v[66:69], v[30:33]
	v_mfma_f32_16x16x32_bf16 v[38:41], v[208:211], v[66:69], v[38:41]
	v_mfma_f32_16x16x32_bf16 v[42:45], v[212:215], v[66:69], v[42:45]
	ds_read_b128 v[66:69], v119 offset:32768
	s_waitcnt lgkmcnt(7)
	v_mfma_f32_16x16x32_bf16 v[46:49], v[82:85], v[70:73], v[46:49]
	v_mfma_f32_16x16x32_bf16 v[26:29], v[86:89], v[70:73], v[26:29]
	v_mfma_f32_16x16x32_bf16 v[14:17], v[208:211], v[70:73], v[14:17]
	v_mfma_f32_16x16x32_bf16 v[10:13], v[212:215], v[70:73], v[10:13]
	ds_read_b128 v[70:73], v119 offset:34816
	s_waitcnt lgkmcnt(7)
	v_mfma_f32_16x16x32_bf16 v[34:37], v[82:85], v[74:77], v[34:37]
	v_mfma_f32_16x16x32_bf16 v[22:25], v[86:89], v[74:77], v[22:25]
	v_mfma_f32_16x16x32_bf16 v[18:21], v[208:211], v[74:77], v[18:21]
	v_mfma_f32_16x16x32_bf16 v[62:65], v[212:215], v[74:77], v[62:65]
	ds_read_b128 v[74:77], v119 offset:36864
	s_waitcnt lgkmcnt(7)
	v_mfma_f32_16x16x32_bf16 v[58:61], v[82:85], v[78:81], v[58:61]
	v_mfma_f32_16x16x32_bf16 v[54:57], v[86:89], v[78:81], v[54:57]
	v_mfma_f32_16x16x32_bf16 v[50:53], v[208:211], v[78:81], v[50:53]
	v_mfma_f32_16x16x32_bf16 v[2:5], v[212:215], v[78:81], v[2:5]
	ds_read_b128 v[78:81], v119 offset:38912
	s_waitcnt lgkmcnt(3)
	v_mfma_f32_16x16x32_bf16 v[6:9], v[216:219], v[66:69], v[6:9]
	v_mfma_f32_16x16x32_bf16 v[30:33], v[220:223], v[66:69], v[30:33]
	v_mfma_f32_16x16x32_bf16 v[38:41], v[224:227], v[66:69], v[38:41]
	v_mfma_f32_16x16x32_bf16 v[42:45], v[228:231], v[66:69], v[42:45]
	s_waitcnt lgkmcnt(2)
	v_mfma_f32_16x16x32_bf16 v[46:49], v[216:219], v[70:73], v[46:49]
	v_mfma_f32_16x16x32_bf16 v[26:29], v[220:223], v[70:73], v[26:29]
	v_mfma_f32_16x16x32_bf16 v[14:17], v[224:227], v[70:73], v[14:17]
	v_mfma_f32_16x16x32_bf16 v[10:13], v[228:231], v[70:73], v[10:13]
	s_waitcnt vmcnt(14)
	s_waitcnt lgkmcnt(0)
	s_barrier
	s_add_i32 m0, s67, 0x8000
	s_nop 0
	global_load_lds_dwordx4 v188, s[80:81]
	s_add_i32 m0, s67, 0xa000
	s_nop 0
	global_load_lds_dwordx4 v189, s[80:81]
	s_add_i32 m0, s67, 0xc000
	s_nop 0
	global_load_lds_dwordx4 v190, s[80:81]
	s_add_i32 m0, s67, 0xe000
	s_nop 0
	global_load_lds_dwordx4 v191, s[80:81]
	s_add_i32 m0, s67, 0x1c000
	s_nop 0
	global_load_lds_dwordx4 v205, s[96:97]
	s_add_i32 m0, s67, 0x1e000
	s_nop 0
	global_load_lds_dwordx4 v206, s[96:97]
	ds_read_b128 v[82:85], v90 offset:33792
	ds_read_b128 v[86:89], v90 offset:35840
	ds_read_b128 v[208:211], v90 offset:37888
	ds_read_b128 v[212:215], v90 offset:39936
	ds_read_b128 v[66:69], v0 offset:0
	ds_read_b128 v[70:73], v0 offset:2048
	v_mfma_f32_16x16x32_bf16 v[34:37], v[216:219], v[74:77], v[34:37]
	v_mfma_f32_16x16x32_bf16 v[22:25], v[220:223], v[74:77], v[22:25]
	v_mfma_f32_16x16x32_bf16 v[18:21], v[224:227], v[74:77], v[18:21]
	v_mfma_f32_16x16x32_bf16 v[62:65], v[228:231], v[74:77], v[62:65]
	ds_read_b128 v[74:77], v0 offset:4096
	v_mfma_f32_16x16x32_bf16 v[58:61], v[216:219], v[78:81], v[58:61]
	v_mfma_f32_16x16x32_bf16 v[54:57], v[220:223], v[78:81], v[54:57]
	v_mfma_f32_16x16x32_bf16 v[50:53], v[224:227], v[78:81], v[50:53]
	v_mfma_f32_16x16x32_bf16 v[2:5], v[228:231], v[78:81], v[2:5]
	ds_read_b128 v[78:81], v0 offset:6144
	ds_read_b128 v[216:219], v91 offset:33792
	ds_read_b128 v[220:223], v91 offset:35840
	ds_read_b128 v[224:227], v91 offset:37888
	ds_read_b128 v[228:231], v91 offset:39936
	s_waitcnt lgkmcnt(7)
	v_mfma_f32_16x16x32_bf16 v[6:9], v[82:85], v[66:69], v[6:9]
	v_mfma_f32_16x16x32_bf16 v[30:33], v[86:89], v[66:69], v[30:33]
	v_mfma_f32_16x16x32_bf16 v[38:41], v[208:211], v[66:69], v[38:41]
	v_mfma_f32_16x16x32_bf16 v[42:45], v[212:215], v[66:69], v[42:45]
	ds_read_b128 v[66:69], v255 offset:0
	s_waitcnt lgkmcnt(7)
	v_mfma_f32_16x16x32_bf16 v[46:49], v[82:85], v[70:73], v[46:49]
	v_mfma_f32_16x16x32_bf16 v[26:29], v[86:89], v[70:73], v[26:29]
	v_mfma_f32_16x16x32_bf16 v[14:17], v[208:211], v[70:73], v[14:17]
	v_mfma_f32_16x16x32_bf16 v[10:13], v[212:215], v[70:73], v[10:13]
	ds_read_b128 v[70:73], v255 offset:2048
	s_waitcnt lgkmcnt(7)
	v_mfma_f32_16x16x32_bf16 v[34:37], v[82:85], v[74:77], v[34:37]
	v_mfma_f32_16x16x32_bf16 v[22:25], v[86:89], v[74:77], v[22:25]
	v_mfma_f32_16x16x32_bf16 v[18:21], v[208:211], v[74:77], v[18:21]
	v_mfma_f32_16x16x32_bf16 v[62:65], v[212:215], v[74:77], v[62:65]
	ds_read_b128 v[74:77], v255 offset:4096
	s_waitcnt lgkmcnt(7)
	v_mfma_f32_16x16x32_bf16 v[58:61], v[82:85], v[78:81], v[58:61]
	v_mfma_f32_16x16x32_bf16 v[54:57], v[86:89], v[78:81], v[54:57]
	v_mfma_f32_16x16x32_bf16 v[50:53], v[208:211], v[78:81], v[50:53]
	v_mfma_f32_16x16x32_bf16 v[2:5], v[212:215], v[78:81], v[2:5]
	ds_read_b128 v[78:81], v255 offset:6144
	s_waitcnt lgkmcnt(3)
	v_mfma_f32_16x16x32_bf16 v[6:9], v[216:219], v[66:69], v[6:9]
	v_mfma_f32_16x16x32_bf16 v[30:33], v[220:223], v[66:69], v[30:33]
	v_mfma_f32_16x16x32_bf16 v[38:41], v[224:227], v[66:69], v[38:41]
	v_mfma_f32_16x16x32_bf16 v[42:45], v[228:231], v[66:69], v[42:45]
	s_waitcnt lgkmcnt(2)
	v_mfma_f32_16x16x32_bf16 v[46:49], v[216:219], v[70:73], v[46:49]
	v_mfma_f32_16x16x32_bf16 v[26:29], v[220:223], v[70:73], v[26:29]
	v_mfma_f32_16x16x32_bf16 v[14:17], v[224:227], v[70:73], v[14:17]
	v_mfma_f32_16x16x32_bf16 v[10:13], v[228:231], v[70:73], v[10:13]
	s_waitcnt vmcnt(14)
	s_waitcnt lgkmcnt(0)
	s_barrier
	ds_read_b128 v[82:85], v90 offset:0
	ds_read_b128 v[86:89], v90 offset:2048
	ds_read_b128 v[208:211], v90 offset:4096
	ds_read_b128 v[212:215], v90 offset:6144
	ds_read_b128 v[66:69], v207 offset:0
	ds_read_b128 v[70:73], v207 offset:2048
	v_mfma_f32_16x16x32_bf16 v[34:37], v[216:219], v[74:77], v[34:37]
	v_mfma_f32_16x16x32_bf16 v[22:25], v[220:223], v[74:77], v[22:25]
	v_mfma_f32_16x16x32_bf16 v[18:21], v[224:227], v[74:77], v[18:21]
	v_mfma_f32_16x16x32_bf16 v[62:65], v[228:231], v[74:77], v[62:65]
	ds_read_b128 v[74:77], v207 offset:4096
	v_mfma_f32_16x16x32_bf16 v[58:61], v[216:219], v[78:81], v[58:61]
	v_mfma_f32_16x16x32_bf16 v[54:57], v[220:223], v[78:81], v[54:57]
	v_mfma_f32_16x16x32_bf16 v[50:53], v[224:227], v[78:81], v[50:53]
	v_mfma_f32_16x16x32_bf16 v[2:5], v[228:231], v[78:81], v[2:5]
	ds_read_b128 v[78:81], v207 offset:6144
	ds_read_b128 v[216:219], v91 offset:0
	ds_read_b128 v[220:223], v91 offset:2048
	ds_read_b128 v[224:227], v91 offset:4096
	ds_read_b128 v[228:231], v91 offset:6144
	s_waitcnt lgkmcnt(7)
	v_mfma_f32_16x16x32_bf16 v[6:9], v[82:85], v[66:69], v[6:9]
	v_mfma_f32_16x16x32_bf16 v[30:33], v[86:89], v[66:69], v[30:33]
	v_mfma_f32_16x16x32_bf16 v[38:41], v[208:211], v[66:69], v[38:41]
	v_mfma_f32_16x16x32_bf16 v[42:45], v[212:215], v[66:69], v[42:45]
	ds_read_b128 v[66:69], v119 offset:0
	s_waitcnt lgkmcnt(7)
	v_mfma_f32_16x16x32_bf16 v[46:49], v[82:85], v[70:73], v[46:49]
	v_mfma_f32_16x16x32_bf16 v[26:29], v[86:89], v[70:73], v[26:29]
	v_mfma_f32_16x16x32_bf16 v[14:17], v[208:211], v[70:73], v[14:17]
	v_mfma_f32_16x16x32_bf16 v[10:13], v[212:215], v[70:73], v[10:13]
	ds_read_b128 v[70:73], v119 offset:2048
	s_waitcnt lgkmcnt(7)
	v_mfma_f32_16x16x32_bf16 v[34:37], v[82:85], v[74:77], v[34:37]
	v_mfma_f32_16x16x32_bf16 v[22:25], v[86:89], v[74:77], v[22:25]
	v_mfma_f32_16x16x32_bf16 v[18:21], v[208:211], v[74:77], v[18:21]
	v_mfma_f32_16x16x32_bf16 v[62:65], v[212:215], v[74:77], v[62:65]
	ds_read_b128 v[74:77], v119 offset:4096
	s_waitcnt lgkmcnt(7)
	v_mfma_f32_16x16x32_bf16 v[58:61], v[82:85], v[78:81], v[58:61]
	v_mfma_f32_16x16x32_bf16 v[54:57], v[86:89], v[78:81], v[54:57]
	v_mfma_f32_16x16x32_bf16 v[50:53], v[208:211], v[78:81], v[50:53]
	v_mfma_f32_16x16x32_bf16 v[2:5], v[212:215], v[78:81], v[2:5]
	ds_read_b128 v[78:81], v119 offset:6144
	s_waitcnt lgkmcnt(3)
	v_mfma_f32_16x16x32_bf16 v[6:9], v[216:219], v[66:69], v[6:9]
	v_mfma_f32_16x16x32_bf16 v[30:33], v[220:223], v[66:69], v[30:33]
	v_mfma_f32_16x16x32_bf16 v[38:41], v[224:227], v[66:69], v[38:41]
	v_mfma_f32_16x16x32_bf16 v[42:45], v[228:231], v[66:69], v[42:45]
	s_waitcnt lgkmcnt(2)
	v_mfma_f32_16x16x32_bf16 v[46:49], v[216:219], v[70:73], v[46:49]
	v_mfma_f32_16x16x32_bf16 v[26:29], v[220:223], v[70:73], v[26:29]
	v_mfma_f32_16x16x32_bf16 v[14:17], v[224:227], v[70:73], v[14:17]
	v_mfma_f32_16x16x32_bf16 v[10:13], v[228:231], v[70:73], v[10:13]
	s_waitcnt vmcnt(0)
	s_waitcnt lgkmcnt(0)
	s_barrier
	ds_read_b128 v[82:85], v90 offset:16384
	ds_read_b128 v[86:89], v90 offset:18432
	ds_read_b128 v[208:211], v90 offset:20480
	ds_read_b128 v[212:215], v90 offset:22528
	ds_read_b128 v[66:69], v207 offset:32768
	ds_read_b128 v[70:73], v207 offset:34816
	v_mfma_f32_16x16x32_bf16 v[34:37], v[216:219], v[74:77], v[34:37]
	v_mfma_f32_16x16x32_bf16 v[22:25], v[220:223], v[74:77], v[22:25]
	v_mfma_f32_16x16x32_bf16 v[18:21], v[224:227], v[74:77], v[18:21]
	v_mfma_f32_16x16x32_bf16 v[62:65], v[228:231], v[74:77], v[62:65]
	ds_read_b128 v[74:77], v207 offset:36864
	v_mfma_f32_16x16x32_bf16 v[58:61], v[216:219], v[78:81], v[58:61]
	v_mfma_f32_16x16x32_bf16 v[54:57], v[220:223], v[78:81], v[54:57]
	v_mfma_f32_16x16x32_bf16 v[50:53], v[224:227], v[78:81], v[50:53]
	v_mfma_f32_16x16x32_bf16 v[2:5], v[228:231], v[78:81], v[2:5]
	ds_read_b128 v[78:81], v207 offset:38912
	ds_read_b128 v[216:219], v91 offset:16384
	ds_read_b128 v[220:223], v91 offset:18432
	ds_read_b128 v[224:227], v91 offset:20480
	ds_read_b128 v[228:231], v91 offset:22528
	s_waitcnt lgkmcnt(7)
	v_mfma_f32_16x16x32_bf16 v[6:9], v[82:85], v[66:69], v[6:9]
	v_mfma_f32_16x16x32_bf16 v[30:33], v[86:89], v[66:69], v[30:33]
	v_mfma_f32_16x16x32_bf16 v[38:41], v[208:211], v[66:69], v[38:41]
	v_mfma_f32_16x16x32_bf16 v[42:45], v[212:215], v[66:69], v[42:45]
	ds_read_b128 v[66:69], v119 offset:32768
	s_waitcnt lgkmcnt(7)
	v_mfma_f32_16x16x32_bf16 v[46:49], v[82:85], v[70:73], v[46:49]
	v_mfma_f32_16x16x32_bf16 v[26:29], v[86:89], v[70:73], v[26:29]
	v_mfma_f32_16x16x32_bf16 v[14:17], v[208:211], v[70:73], v[14:17]
	v_mfma_f32_16x16x32_bf16 v[10:13], v[212:215], v[70:73], v[10:13]
	ds_read_b128 v[70:73], v119 offset:34816
	s_waitcnt lgkmcnt(7)
	v_mfma_f32_16x16x32_bf16 v[34:37], v[82:85], v[74:77], v[34:37]
	v_mfma_f32_16x16x32_bf16 v[22:25], v[86:89], v[74:77], v[22:25]
	v_mfma_f32_16x16x32_bf16 v[18:21], v[208:211], v[74:77], v[18:21]
	v_mfma_f32_16x16x32_bf16 v[62:65], v[212:215], v[74:77], v[62:65]
	ds_read_b128 v[74:77], v119 offset:36864
	s_waitcnt lgkmcnt(7)
	v_mfma_f32_16x16x32_bf16 v[58:61], v[82:85], v[78:81], v[58:61]
	v_mfma_f32_16x16x32_bf16 v[54:57], v[86:89], v[78:81], v[54:57]
	v_mfma_f32_16x16x32_bf16 v[50:53], v[208:211], v[78:81], v[50:53]
	v_mfma_f32_16x16x32_bf16 v[2:5], v[212:215], v[78:81], v[2:5]
	ds_read_b128 v[78:81], v119 offset:38912
	s_waitcnt lgkmcnt(3)
	v_mfma_f32_16x16x32_bf16 v[6:9], v[216:219], v[66:69], v[6:9]
	s_waitcnt vmcnt(6)
	v_mfma_f32_16x16x32_bf16 v[30:33], v[220:223], v[66:69], v[30:33]
	v_mfma_f32_16x16x32_bf16 v[38:41], v[224:227], v[66:69], v[38:41]
	v_mfma_f32_16x16x32_bf16 v[42:45], v[228:231], v[66:69], v[42:45]
	v_cvt_f32_ubyte0_e32 v248, v232
	v_cvt_f32_ubyte1_e32 v249, v232
	v_cvt_f32_ubyte2_e32 v250, v232
	v_cvt_f32_ubyte3_e32 v251, v232
	v_mul_f32_e32 v248, s34, v248
	v_mul_f32_e32 v249, s34, v249
	v_mul_f32_e32 v250, s34, v250
	v_mul_f32_e32 v251, s34, v251
	v_fma_f32 v184, v6, v248, v184
	v_fma_f32 v185, v7, v249, v185
	v_fma_f32 v186, v8, v250, v186
	v_fma_f32 v187, v9, v251, v187
	s_waitcnt lgkmcnt(2)
	v_mfma_f32_16x16x32_bf16 v[46:49], v[216:219], v[70:73], v[46:49]
	v_cvt_f32_ubyte0_e32 v248, v233
	v_cvt_f32_ubyte1_e32 v249, v233
	v_cvt_f32_ubyte2_e32 v250, v233
	v_cvt_f32_ubyte3_e32 v251, v233
	v_mul_f32_e32 v248, s34, v248
	v_mul_f32_e32 v249, s34, v249
	v_mul_f32_e32 v250, s34, v250
	v_mul_f32_e32 v251, s34, v251
	v_fma_f32 v180, v30, v248, v180
	v_fma_f32 v181, v31, v249, v181
	v_fma_f32 v182, v32, v250, v182
	v_fma_f32 v183, v33, v251, v183
	v_mfma_f32_16x16x32_bf16 v[26:29], v[220:223], v[70:73], v[26:29]
	v_cvt_f32_ubyte0_e32 v248, v234
	v_cvt_f32_ubyte1_e32 v249, v234
	v_cvt_f32_ubyte2_e32 v250, v234
	v_cvt_f32_ubyte3_e32 v251, v234
	v_mul_f32_e32 v248, s34, v248
	v_mul_f32_e32 v249, s34, v249
	v_mul_f32_e32 v250, s34, v250
	v_mul_f32_e32 v251, s34, v251
	v_fma_f32 v176, v38, v248, v176
	v_fma_f32 v177, v39, v249, v177
	v_fma_f32 v178, v40, v250, v178
	v_fma_f32 v179, v41, v251, v179
	v_mfma_f32_16x16x32_bf16 v[14:17], v[224:227], v[70:73], v[14:17]
	v_cvt_f32_ubyte0_e32 v248, v235
	v_cvt_f32_ubyte1_e32 v249, v235
	v_cvt_f32_ubyte2_e32 v250, v235
	v_cvt_f32_ubyte3_e32 v251, v235
	v_mul_f32_e32 v248, s34, v248
	v_mul_f32_e32 v249, s34, v249
	v_mul_f32_e32 v250, s34, v250
	v_mul_f32_e32 v251, s34, v251
	v_fma_f32 v172, v42, v248, v172
	v_fma_f32 v173, v43, v249, v173
	v_fma_f32 v174, v44, v250, v174
	v_fma_f32 v175, v45, v251, v175
	v_mfma_f32_16x16x32_bf16 v[10:13], v[228:231], v[70:73], v[10:13]
	v_cvt_f32_ubyte0_e32 v248, v236
	v_cvt_f32_ubyte1_e32 v249, v236
	v_cvt_f32_ubyte2_e32 v250, v236
	v_cvt_f32_ubyte3_e32 v251, v236
	v_mul_f32_e32 v248, s34, v248
	v_mul_f32_e32 v249, s34, v249
	v_mul_f32_e32 v250, s34, v250
	v_mul_f32_e32 v251, s34, v251
	v_fma_f32 v168, v46, v248, v168
	v_fma_f32 v169, v47, v249, v169
	v_fma_f32 v170, v48, v250, v170
	v_fma_f32 v171, v49, v251, v171
	s_waitcnt lgkmcnt(0)
	s_barrier
	v_mfma_f32_16x16x32_bf16 v[34:37], v[216:219], v[74:77], v[34:37]
	v_cvt_f32_ubyte0_e32 v248, v237
	v_cvt_f32_ubyte1_e32 v249, v237
	v_cvt_f32_ubyte2_e32 v250, v237
	v_cvt_f32_ubyte3_e32 v251, v237
	v_mul_f32_e32 v248, s34, v248
	v_mul_f32_e32 v249, s34, v249
	v_mul_f32_e32 v250, s34, v250
	v_mul_f32_e32 v251, s34, v251
	v_fma_f32 v164, v26, v248, v164
	v_fma_f32 v165, v27, v249, v165
	v_fma_f32 v166, v28, v250, v166
	v_fma_f32 v167, v29, v251, v167
	v_mfma_f32_16x16x32_bf16 v[22:25], v[220:223], v[74:77], v[22:25]
	v_cvt_f32_ubyte0_e32 v248, v238
	v_cvt_f32_ubyte1_e32 v249, v238
	v_cvt_f32_ubyte2_e32 v250, v238
	v_cvt_f32_ubyte3_e32 v251, v238
	v_mul_f32_e32 v248, s34, v248
	v_mul_f32_e32 v249, s34, v249
	v_mul_f32_e32 v250, s34, v250
	v_mul_f32_e32 v251, s34, v251
	v_fma_f32 v160, v14, v248, v160
	v_fma_f32 v161, v15, v249, v161
	v_fma_f32 v162, v16, v250, v162
	v_fma_f32 v163, v17, v251, v163
	v_mfma_f32_16x16x32_bf16 v[18:21], v[224:227], v[74:77], v[18:21]
	v_cvt_f32_ubyte0_e32 v248, v239
	v_cvt_f32_ubyte1_e32 v249, v239
	v_cvt_f32_ubyte2_e32 v250, v239
	v_cvt_f32_ubyte3_e32 v251, v239
	v_mul_f32_e32 v248, s34, v248
	v_mul_f32_e32 v249, s34, v249
	v_mul_f32_e32 v250, s34, v250
	v_mul_f32_e32 v251, s34, v251
	v_fma_f32 v156, v10, v248, v156
	v_fma_f32 v157, v11, v249, v157
	v_fma_f32 v158, v12, v250, v158
	v_fma_f32 v159, v13, v251, v159
	v_mfma_f32_16x16x32_bf16 v[62:65], v[228:231], v[74:77], v[62:65]
	v_cvt_f32_ubyte0_e32 v248, v240
	v_cvt_f32_ubyte1_e32 v249, v240
	v_cvt_f32_ubyte2_e32 v250, v240
	v_cvt_f32_ubyte3_e32 v251, v240
	v_mul_f32_e32 v248, s34, v248
	v_mul_f32_e32 v249, s34, v249
	v_mul_f32_e32 v250, s34, v250
	v_mul_f32_e32 v251, s34, v251
	v_fma_f32 v136, v34, v248, v136
	v_fma_f32 v137, v35, v249, v137
	v_fma_f32 v150, v36, v250, v150
	v_fma_f32 v151, v37, v251, v151
	v_mfma_f32_16x16x32_bf16 v[58:61], v[216:219], v[78:81], v[58:61]
	v_cvt_f32_ubyte0_e32 v248, v241
	v_cvt_f32_ubyte1_e32 v249, v241
	v_cvt_f32_ubyte2_e32 v250, v241
	v_cvt_f32_ubyte3_e32 v251, v241
	v_mul_f32_e32 v248, s34, v248
	v_mul_f32_e32 v249, s34, v249
	v_mul_f32_e32 v250, s34, v250
	v_mul_f32_e32 v251, s34, v251
	v_fma_f32 v130, v22, v248, v130
	v_fma_f32 v131, v23, v249, v131
	v_fma_f32 v134, v24, v250, v134
	v_fma_f32 v135, v25, v251, v135
	v_mfma_f32_16x16x32_bf16 v[54:57], v[220:223], v[78:81], v[54:57]
	v_cvt_f32_ubyte0_e32 v248, v242
	v_cvt_f32_ubyte1_e32 v249, v242
	v_cvt_f32_ubyte2_e32 v250, v242
	v_cvt_f32_ubyte3_e32 v251, v242
	v_mul_f32_e32 v248, s34, v248
	v_mul_f32_e32 v249, s34, v249
	v_mul_f32_e32 v250, s34, v250
	v_mul_f32_e32 v251, s34, v251
	v_fma_f32 v124, v18, v248, v124
	v_fma_f32 v125, v19, v249, v125
	v_fma_f32 v126, v20, v250, v126
	v_fma_f32 v127, v21, v251, v127
	v_mfma_f32_16x16x32_bf16 v[50:53], v[224:227], v[78:81], v[50:53]
	v_cvt_f32_ubyte0_e32 v248, v243
	v_cvt_f32_ubyte1_e32 v249, v243
	v_cvt_f32_ubyte2_e32 v250, v243
	v_cvt_f32_ubyte3_e32 v251, v243
	v_mul_f32_e32 v248, s34, v248
	v_mul_f32_e32 v249, s34, v249
	v_mul_f32_e32 v250, s34, v250
	v_mul_f32_e32 v251, s34, v251
	v_fma_f32 v120, v62, v248, v120
	v_fma_f32 v121, v63, v249, v121
	v_fma_f32 v122, v64, v250, v122
	v_fma_f32 v123, v65, v251, v123
	v_mfma_f32_16x16x32_bf16 v[2:5], v[228:231], v[78:81], v[2:5]
	v_cvt_f32_ubyte0_e32 v248, v244
	v_cvt_f32_ubyte1_e32 v249, v244
	v_cvt_f32_ubyte2_e32 v250, v244
	v_cvt_f32_ubyte3_e32 v251, v244
	v_mul_f32_e32 v248, s34, v248
	v_mul_f32_e32 v249, s34, v249
	v_mul_f32_e32 v250, s34, v250
	v_mul_f32_e32 v251, s34, v251
	v_fma_f32 v114, v58, v248, v114
	v_fma_f32 v115, v59, v249, v115
	v_fma_f32 v116, v60, v250, v116
	v_fma_f32 v117, v61, v251, v117
	s_nop 7
	s_nop 3
	v_cvt_f32_ubyte0_e32 v248, v245
	v_cvt_f32_ubyte1_e32 v249, v245
	v_cvt_f32_ubyte2_e32 v250, v245
	v_cvt_f32_ubyte3_e32 v251, v245
	v_mul_f32_e32 v248, s34, v248
	v_mul_f32_e32 v249, s34, v249
	v_mul_f32_e32 v250, s34, v250
	v_mul_f32_e32 v251, s34, v251
	v_fma_f32 v106, v54, v248, v106
	v_fma_f32 v107, v55, v249, v107
	v_fma_f32 v108, v56, v250, v108
	v_fma_f32 v109, v57, v251, v109
	v_cvt_f32_ubyte0_e32 v248, v246
	v_cvt_f32_ubyte1_e32 v249, v246
	v_cvt_f32_ubyte2_e32 v250, v246
	v_cvt_f32_ubyte3_e32 v251, v246
	v_mul_f32_e32 v248, s34, v248
	v_mul_f32_e32 v249, s34, v249
	v_mul_f32_e32 v250, s34, v250
	v_mul_f32_e32 v251, s34, v251
	v_fma_f32 v100, v50, v248, v100
	v_fma_f32 v101, v51, v249, v101
	v_fma_f32 v102, v52, v250, v102
	v_fma_f32 v103, v53, v251, v103
	v_cvt_f32_ubyte0_e32 v248, v247
	v_cvt_f32_ubyte1_e32 v249, v247
	v_cvt_f32_ubyte2_e32 v250, v247
	v_cvt_f32_ubyte3_e32 v251, v247
	v_mul_f32_e32 v248, s34, v248
	v_mul_f32_e32 v249, s34, v249
	v_mul_f32_e32 v250, s34, v250
	v_mul_f32_e32 v251, s34, v251
	v_fma_f32 v96, v2, v248, v96
	v_fma_f32 v97, v3, v249, v97
	v_fma_f32 v98, v4, v250, v98
	v_fma_f32 v99, v5, v251, v99
	s_cmp_eq_u32 0, 0
	s_cbranch_scc0 .LBB0_1004
	v_lshlrev_b32_e32 v0, 1, v118
	v_lshl_add_u64 v[6:7], s[4:5], 0, v[0:1]
	v_lshlrev_b64 v[2:3], 11, v[112:113]
	v_lshl_add_u64 v[8:9], v[6:7], 0, v[2:3]
	v_cvt_pk_bf16_f32 v2, v184, v185
	v_cvt_pk_bf16_f32 v3, v186, v187
	v_cvt_pk_bf16_f32 v4, v180, v181
	v_cvt_pk_bf16_f32 v5, v182, v183
	global_store_dwordx4 v[8:9], v[2:5], off
	v_readlane_b32 s46, v254, 29
	s_mov_b32 s38, 0
	v_cvt_pk_bf16_f32 v2, v176, v177
	v_cvt_pk_bf16_f32 v3, v178, v179
	v_cvt_pk_bf16_f32 v4, v172, v173
	v_cvt_pk_bf16_f32 v5, v174, v175
	global_store_dwordx4 v[8:9], v[2:5], off offset:64
	v_readlane_b32 s47, v254, 30
	s_nop 0
	v_lshlrev_b64 v[2:3], 11, v[110:111]
	v_lshl_add_u64 v[8:9], v[6:7], 0, v[2:3]
	v_cvt_pk_bf16_f32 v2, v168, v169
	v_cvt_pk_bf16_f32 v3, v170, v171
	v_cvt_pk_bf16_f32 v4, v164, v165
	v_cvt_pk_bf16_f32 v5, v166, v167
	global_store_dwordx4 v[8:9], v[2:5], off
	s_nop 1
	v_cvt_pk_bf16_f32 v2, v160, v161
	v_cvt_pk_bf16_f32 v3, v162, v163
	v_cvt_pk_bf16_f32 v4, v156, v157
	v_cvt_pk_bf16_f32 v5, v158, v159
	global_store_dwordx4 v[8:9], v[2:5], off offset:64
	s_nop 1
	v_lshlrev_b64 v[2:3], 11, v[104:105]
	v_lshl_add_u64 v[8:9], v[6:7], 0, v[2:3]
	v_cvt_pk_bf16_f32 v2, v136, v137
	v_cvt_pk_bf16_f32 v3, v150, v151
	v_cvt_pk_bf16_f32 v4, v130, v131
	v_cvt_pk_bf16_f32 v5, v134, v135
	global_store_dwordx4 v[8:9], v[2:5], off
	s_nop 1
	v_cvt_pk_bf16_f32 v2, v124, v125
	v_cvt_pk_bf16_f32 v3, v126, v127
	v_cvt_pk_bf16_f32 v4, v120, v121
	v_cvt_pk_bf16_f32 v5, v122, v123
	global_store_dwordx4 v[8:9], v[2:5], off offset:64
	s_nop 1
	v_lshlrev_b64 v[2:3], 11, v[94:95]
	v_lshl_add_u64 v[6:7], v[6:7], 0, v[2:3]
	v_cvt_pk_bf16_f32 v2, v114, v115
	v_cvt_pk_bf16_f32 v3, v116, v117
	v_cvt_pk_bf16_f32 v4, v106, v107
	v_cvt_pk_bf16_f32 v5, v108, v109
	global_store_dwordx4 v[6:7], v[2:5], off
	s_nop 1
	v_cvt_pk_bf16_f32 v2, v100, v101
	v_cvt_pk_bf16_f32 v3, v102, v103
	v_cvt_pk_bf16_f32 v4, v96, v97
	v_cvt_pk_bf16_f32 v5, v98, v99
	global_store_dwordx4 v[6:7], v[2:5], off offset:64
